# FFN1 epilogue pipeline refined: a barrier every half quarter (8 stages) between the two wave rows
# speedup vs baseline: 1.0022x; 1.0022x over previous
; #define LAS __attribute__((address_space(3)))
; __device__ __forceinline__ float sigmoidf_(float x) { return __builtin_amdgcn_rcpf(1.0f + __expf(-x)); }
;     __device__ __forceinline__ void operator()(AccRef acc, const Unit& u, int wr, int wc, int fr, int fq) const {
;     ...
;                 f32x4 h2v = (f32x4){0.f, 0.f, 0.f, 0.f}, h3v = h2v, h2g = h2v, h3g = h2v;
;                 const int pb = ai * 2 + wr - 1;
;                 if (pb >= 0 && fr == 0) { const LAS float* xp = xch + (pb * 2) * 256 + clb + 4 * n;
;                     h2v = *(const LAS f32x4*)(xp); h3v = *(const LAS f32x4*)(xp + 256); h2g = *(const LAS f32x4*)(xp + 128); h3g = *(const LAS f32x4*)(xp + 256 + 128); }
;                 float o[4][4];
; #pragma unroll
;                 for (int j = 0; j < 4; ++j) {
;                     const float v0 = acc[ai][0][0][n][j], v1 = acc[ai][0][1][n][j], v2 = acc[ai][0][2][n][j], v3 = acc[ai][0][3][n][j];
;                     const float g0 = acc[ai][1][0][n][j], g1 = acc[ai][1][1][n][j], g2 = acc[ai][1][2][n][j], g3 = acc[ai][1][3][n][j];
;                     const float pv3 = dpp_upd<0x111>(h3v[j], v3), pv2 = dpp_upd<0x111>(h2v[j], v2), pg3 = dpp_upd<0x111>(h3g[j], g3), pg2 = dpp_upd<0x111>(h2g[j], g2);
;                     const float hv0 = bvv[j] + w2v[j] * v0 + w1v[j] * pv3 + w0v[j] * pv2, hv1 = bvv[j] + w2v[j] * v1 + w1v[j] * v0 + w0v[j] * pv3;
;                     const float hv2 = bvv[j] + w2v[j] * v2 + w1v[j] * v1 + w0v[j] * v0, hv3 = bvv[j] + w2v[j] * v3 + w1v[j] * v2 + w0v[j] * v1;
;                     const float hg0 = bvg[j] + w2g[j] * g0 + w1g[j] * pg3 + w0g[j] * pg2, hg1 = bvg[j] + w2g[j] * g1 + w1g[j] * g0 + w0g[j] * pg3;
;                     const float hg2 = bvg[j] + w2g[j] * g2 + w1g[j] * g1 + w0g[j] * g0, hg3 = bvg[j] + w2g[j] * g3 + w1g[j] * g2 + w0g[j] * g1;
;                     o[0][j] = hg0 * sigmoidf_(hg0) * hv0; o[1][j] = hg1 * sigmoidf_(hg1) * hv1; o[2][j] = hg2 * sigmoidf_(hg2) * hv2; o[3][j] = hg3 * sigmoidf_(hg3) * hv3; }
; #pragma unroll
;                 for (int m = 0; m < 4; ++m) { u32x2 w; w.x = cvt_pk_bf16(o[m][0], o[m][1]); w.y = cvt_pk_bf16(o[m][2], o[m][3]);
;                     *(u32x2*)(Aout + (size_t)(row0 + ai * 128 + m) * FH + hc0 + 4 * n) = w; } } }
.LBB0_305:
	s_or_b64 exec, exec, s[34:35]
	s_waitcnt lgkmcnt(0)
	v_mov_b32_dpp v64, v8 row_shr:1 row_mask:0xf bank_mask:0xf
	v_mov_b32_dpp v65, v9 row_shr:1 row_mask:0xf bank_mask:0xf
	v_pk_fma_f32 v[44:45], v[24:25], v[120:121], v[124:125]
	v_mov_b32_dpp v40, v0 row_shr:1 row_mask:0xf bank_mask:0xf
	v_mov_b32_dpp v41, v1 row_shr:1 row_mask:0xf bank_mask:0xf
	v_pk_fma_f32 v[44:45], v[116:117], v[64:65], v[44:45]
	v_mov_b32_dpp v32, v20 row_shr:1 row_mask:0xf bank_mask:0xf
	v_pk_fma_f32 v[40:41], v[112:113], v[40:41], v[44:45]
	v_mov_b32_dpp v33, v21 row_shr:1 row_mask:0xf bank_mask:0xf
	v_exp_f32_e32 v44, v40
	v_exp_f32_e32 v45, v41
	v_pk_fma_f32 v[46:47], v[28:29], v[104:105], v[108:109]
	v_mov_b32_dpp v36, v12 row_shr:1 row_mask:0xf bank_mask:0xf
	v_pk_add_f32 v[44:45], v[44:45], 1.0 op_sel_hi:[1,0]
	v_rcp_f32_e32 v44, v44
	v_rcp_f32_e32 v45, v45
	v_mov_b32_dpp v37, v13 row_shr:1 row_mask:0xf bank_mask:0xf
	v_pk_fma_f32 v[46:47], v[100:101], v[32:33], v[46:47]
	v_mov_b32_dpp v66, v10 row_shr:1 row_mask:0xf bank_mask:0xf
	v_pk_fma_f32 v[36:37], v[96:97], v[36:37], v[46:47]
	v_pk_mul_f32 v[40:41], v[40:41], v[44:45]
	v_mov_b32_dpp v67, v11 row_shr:1 row_mask:0xf bank_mask:0xf
	v_pk_mul_f32 v[36:37], v[36:37], v[40:41]
	v_pk_fma_f32 v[40:41], v[26:27], v[122:123], v[126:127]
	v_mov_b32_dpp v42, v2 row_shr:1 row_mask:0xf bank_mask:0xf
	v_mov_b32_dpp v43, v3 row_shr:1 row_mask:0xf bank_mask:0xf
	v_pk_fma_f32 v[40:41], v[118:119], v[66:67], v[40:41]
	v_cvt_pk_bf16_f32 v146, v36, v37
	v_pk_fma_f32 v[40:41], v[114:115], v[42:43], v[40:41]
	v_mov_b32_dpp v34, v22 row_shr:1 row_mask:0xf bank_mask:0xf
	v_exp_f32_e32 v42, v40
	v_exp_f32_e32 v43, v41
	v_mov_b32_dpp v35, v23 row_shr:1 row_mask:0xf bank_mask:0xf
	v_pk_add_f32 v[42:43], v[42:43], 1.0 op_sel_hi:[1,0]
	v_rcp_f32_e32 v42, v42
	v_rcp_f32_e32 v43, v43
	v_pk_fma_f32 v[44:45], v[30:31], v[106:107], v[110:111]
	v_mov_b32_dpp v38, v14 row_shr:1 row_mask:0xf bank_mask:0xf
	v_mov_b32_dpp v39, v15 row_shr:1 row_mask:0xf bank_mask:0xf
	v_pk_fma_f32 v[44:45], v[102:103], v[34:35], v[44:45]
	v_pk_mul_f32 v[40:41], v[40:41], v[42:43]
	v_pk_fma_f32 v[38:39], v[98:99], v[38:39], v[44:45]
	v_pk_fma_f32 v[8:9], v[8:9], v[120:121], v[124:125]
	v_pk_mul_f32 v[38:39], v[38:39], v[40:41]
	v_pk_fma_f32 v[20:21], v[20:21], v[104:105], v[108:109]
	v_cvt_pk_bf16_f32 v147, v38, v39
	v_pk_fma_f32 v[38:39], v[4:5], v[120:121], v[124:125]
	global_store_dwordx4 v[132:133], v[144:147], off
	v_pk_fma_f32 v[38:39], v[24:25], v[116:117], v[38:39]
	s_and_b64 vcc, exec, s[12:13]
	v_pk_fma_f32 v[38:39], v[112:113], v[64:65], v[38:39]
	s_mov_b32 s35, s24
	v_exp_f32_e32 v36, v38
	v_exp_f32_e32 v37, v39
	s_mov_b32 s34, s26
	s_mov_b64 s[38:39], s[30:31]
	v_pk_add_f32 v[36:37], v[36:37], 1.0 op_sel_hi:[1,0]
	v_rcp_f32_e32 v36, v36
	v_rcp_f32_e32 v37, v37
	v_pk_fma_f32 v[40:41], v[16:17], v[104:105], v[108:109]
	s_mov_b64 s[36:37], s[28:29]
	v_pk_fma_f32 v[40:41], v[28:29], v[100:101], v[40:41]
	v_pk_mul_f32 v[36:37], v[38:39], v[36:37]
	v_pk_fma_f32 v[32:33], v[96:97], v[32:33], v[40:41]
	v_pk_fma_f32 v[40:41], v[18:19], v[106:107], v[110:111]
	v_pk_mul_f32 v[32:33], v[32:33], v[36:37]
	v_pk_fma_f32 v[36:37], v[6:7], v[122:123], v[126:127]
	v_cvt_pk_bf16_f32 v156, v32, v33
	v_pk_fma_f32 v[36:37], v[26:27], v[118:119], v[36:37]
	v_pk_fma_f32 v[40:41], v[30:31], v[102:103], v[40:41]
	s_barrier
	v_pk_fma_f32 v[36:37], v[114:115], v[66:67], v[36:37]
	v_pk_fma_f32 v[34:35], v[98:99], v[34:35], v[40:41]
	v_exp_f32_e32 v38, v36
	v_exp_f32_e32 v39, v37
	s_nop 0
	v_pk_add_f32 v[38:39], v[38:39], 1.0 op_sel_hi:[1,0]
	v_rcp_f32_e32 v38, v38
	v_rcp_f32_e32 v39, v39
	s_nop 0
	v_pk_mul_f32 v[36:37], v[36:37], v[38:39]
	s_nop 0
	v_pk_mul_f32 v[34:35], v[34:35], v[36:37]
	s_nop 0
	v_cvt_pk_bf16_f32 v157, v34, v35
	v_pk_fma_f32 v[34:35], v[0:1], v[120:121], v[124:125]
	global_store_dwordx4 v[128:129], v[154:157], off
	v_pk_fma_f32 v[34:35], v[4:5], v[116:117], v[34:35]
	v_pk_fma_f32 v[0:1], v[0:1], v[116:117], v[8:9]
	v_pk_fma_f32 v[24:25], v[24:25], v[112:113], v[34:35]
	v_pk_fma_f32 v[0:1], v[4:5], v[112:113], v[0:1]
	v_exp_f32_e32 v32, v24
	v_exp_f32_e32 v33, v25
	v_exp_f32_e32 v8, v0
	v_pk_add_f32 v[32:33], v[32:33], 1.0 op_sel_hi:[1,0]
	v_rcp_f32_e32 v32, v32
	v_rcp_f32_e32 v33, v33
	v_pk_fma_f32 v[34:35], v[12:13], v[104:105], v[108:109]
	v_pk_fma_f32 v[4:5], v[10:11], v[122:123], v[126:127]
	v_pk_fma_f32 v[34:35], v[16:17], v[100:101], v[34:35]
	v_pk_mul_f32 v[24:25], v[24:25], v[32:33]
	v_pk_fma_f32 v[28:29], v[28:29], v[96:97], v[34:35]
	v_pk_mul_f32 v[24:25], v[28:29], v[24:25]
	v_pk_fma_f32 v[28:29], v[2:3], v[122:123], v[126:127]
	v_pk_fma_f32 v[2:3], v[2:3], v[118:119], v[4:5]
	v_pk_fma_f32 v[28:29], v[6:7], v[118:119], v[28:29]
	v_pk_fma_f32 v[2:3], v[6:7], v[114:115], v[2:3]
	v_pk_fma_f32 v[26:27], v[26:27], v[114:115], v[28:29]
	v_exp_f32_e32 v28, v26
	v_exp_f32_e32 v29, v27
	v_exp_f32_e32 v9, v1
	v_exp_f32_e32 v4, v2
	v_exp_f32_e32 v5, v3
	v_cvt_pk_bf16_f32 v200, v24, v25
	v_pk_add_f32 v[28:29], v[28:29], 1.0 op_sel_hi:[1,0]
	v_pk_add_f32 v[8:9], v[8:9], 1.0 op_sel_hi:[1,0]
	v_pk_add_f32 v[4:5], v[4:5], 1.0 op_sel_hi:[1,0]
	v_rcp_f32_e32 v28, v28
	v_rcp_f32_e32 v29, v29
	v_rcp_f32_e32 v8, v8
	v_rcp_f32_e32 v9, v9
	v_rcp_f32_e32 v4, v4
	v_rcp_f32_e32 v5, v5
	v_pk_fma_f32 v[32:33], v[14:15], v[106:107], v[110:111]
	v_pk_fma_f32 v[10:11], v[22:23], v[106:107], v[110:111]
	v_pk_fma_f32 v[32:33], v[18:19], v[102:103], v[32:33]
	v_pk_fma_f32 v[12:13], v[12:13], v[100:101], v[20:21]
	v_pk_fma_f32 v[6:7], v[14:15], v[102:103], v[10:11]
	v_pk_fma_f32 v[30:31], v[30:31], v[98:99], v[32:33]
	v_pk_mul_f32 v[26:27], v[26:27], v[28:29]
	v_pk_fma_f32 v[12:13], v[16:17], v[96:97], v[12:13]
	v_pk_mul_f32 v[0:1], v[0:1], v[8:9]
	v_pk_fma_f32 v[6:7], v[18:19], v[98:99], v[6:7]
	v_pk_mul_f32 v[2:3], v[2:3], v[4:5]
	v_pk_mul_f32 v[26:27], v[30:31], v[26:27]
	v_pk_mul_f32 v[0:1], v[12:13], v[0:1]
	v_pk_mul_f32 v[2:3], v[6:7], v[2:3]
	v_cvt_pk_bf16_f32 v201, v26, v27
	v_cvt_pk_bf16_f32 v150, v0, v1
	v_cvt_pk_bf16_f32 v151, v2, v3
	global_store_dwordx4 v[88:89], v[198:201], off
	global_store_dwordx4 v[82:83], v[148:151], off
	s_cbranch_vccnz .LBB0_324

; #define LAS __attribute__((address_space(3)))
;     __device__ __forceinline__ void operator()(AccRef acc, const Unit& u, int wr, int wc, int fr, int fq) const {
;     ...
;         const int hc0 = 128 * u.pn + clb, row0 = u.pm * 256 + wr * 64 + 4 * fr;
; #pragma unroll
;         for (int n = 0; n < 2; ++n) {
;             const f32x4 w0v = cwv[n][0], w1v = cwv[n][1], w2v = cwv[n][2], bvv = cwv[n][3], w0g = cwv[n][4], w1g = cwv[n][5], w2g = cwv[n][6], bvg = cwv[n][7];
; #pragma unroll
;             for (int ai = 0; ai < 2; ++ai) {
;                 if (n == 0 && ai == 0) {
;                     asm volatile("" ::: "memory");
;                     const float* cv = cw + hc0 + 4; const float* cg = cv + FH; const float* bp = cb + hc0 + 4;
;                     cwv[1][0] = *(const f32x4*)(cv); cwv[1][1] = *(const f32x4*)(cv + F2); cwv[1][2] = *(const f32x4*)(cv + 2 * F2); cwv[1][3] = *(const f32x4*)(bp);
;                     cwv[1][4] = *(const f32x4*)(cg); cwv[1][5] = *(const f32x4*)(cg + F2); cwv[1][6] = *(const f32x4*)(cg + 2 * F2); cwv[1][7] = *(const f32x4*)(bp + FH);
;                     asm volatile("" ::: "memory"); }
;                 f32x4 h2v = (f32x4){0.f, 0.f, 0.f, 0.f}, h3v = h2v, h2g = h2v, h3g = h2v;
;                 const int pb = ai * 2 + wr - 1;
;                 if (pb >= 0 && fr == 0) { const LAS float* xp = xch + (pb * 2) * 256 + clb + 4 * n;
;                     h2v = *(const LAS f32x4*)(xp); h3v = *(const LAS f32x4*)(xp + 256); h2g = *(const LAS f32x4*)(xp + 128); h3g = *(const LAS f32x4*)(xp + 256 + 128); }
;                 float o[4][4];
; #pragma unroll
;                 for (int j = 0; j < 4; ++j) {
;                     const float v0 = acc[ai][0][0][n][j], v1 = acc[ai][0][1][n][j], v2 = acc[ai][0][2][n][j], v3 = acc[ai][0][3][n][j];
;                     const float g0 = acc[ai][1][0][n][j], g1 = acc[ai][1][1][n][j], g2 = acc[ai][1][2][n][j], g3 = acc[ai][1][3][n][j];
;                     const float pv3 = dpp_upd<0x111>(h3v[j], v3), pv2 = dpp_upd<0x111>(h2v[j], v2), pg3 = dpp_upd<0x111>(h3g[j], g3), pg2 = dpp_upd<0x111>(h2g[j], g2);
;                     const float hv0 = bvv[j] + w2v[j] * v0 + w1v[j] * pv3 + w0v[j] * pv2, hv1 = bvv[j] + w2v[j] * v1 + w1v[j] * v0 + w0v[j] * pv3;
;                     const float hv2 = bvv[j] + w2v[j] * v2 + w1v[j] * v1 + w0v[j] * v0, hv3 = bvv[j] + w2v[j] * v3 + w1v[j] * v2 + w0v[j] * v1;
.LBB0_316:
	s_or_b64 exec, exec, s[40:41]
	v_pk_fma_f32 v[248:249], v[152:153], v[184:185], v[188:189]
	v_mov_b32_dpp v206, v128 row_shr:1 row_mask:0xf bank_mask:0xf
	v_mov_b32_dpp v207, v129 row_shr:1 row_mask:0xf bank_mask:0xf
	v_pk_fma_f32 v[248:249], v[180:181], v[198:199], v[248:249]
	v_mov_b32_dpp v194, v148 row_shr:1 row_mask:0xf bank_mask:0xf
	v_pk_fma_f32 v[206:207], v[176:177], v[206:207], v[248:249]
	v_mov_b32_dpp v195, v149 row_shr:1 row_mask:0xf bank_mask:0xf
	v_exp_f32_e32 v248, v206
	v_exp_f32_e32 v249, v207
	v_pk_fma_f32 v[250:251], v[156:157], v[168:169], v[172:173]
	v_pk_add_f32 v[248:249], v[248:249], 1.0 op_sel_hi:[1,0]
	v_rcp_f32_e32 v248, v248
	v_rcp_f32_e32 v249, v249
	v_mov_b32_dpp v202, v136 row_shr:1 row_mask:0xf bank_mask:0xf
	v_mov_b32_dpp v203, v137 row_shr:1 row_mask:0xf bank_mask:0xf
	v_pk_fma_f32 v[250:251], v[164:165], v[194:195], v[250:251]
	v_pk_mul_f32 v[206:207], v[206:207], v[248:249]
	v_pk_fma_f32 v[202:203], v[160:161], v[202:203], v[250:251]
	v_mov_b32_dpp v200, v142 row_shr:1 row_mask:0xf bank_mask:0xf
	v_mov_b32_dpp v201, v143 row_shr:1 row_mask:0xf bank_mask:0xf
	v_pk_mul_f32 v[202:203], v[202:203], v[206:207]
	v_pk_fma_f32 v[206:207], v[154:155], v[186:187], v[190:191]
	v_mov_b32_dpp v208, v130 row_shr:1 row_mask:0xf bank_mask:0xf
	v_mov_b32_dpp v209, v131 row_shr:1 row_mask:0xf bank_mask:0xf
	v_pk_fma_f32 v[206:207], v[182:183], v[200:201], v[206:207]
	v_mov_b32_dpp v196, v150 row_shr:1 row_mask:0xf bank_mask:0xf
	v_pk_fma_f32 v[206:207], v[178:179], v[208:209], v[206:207]
	v_mov_b32_dpp v197, v151 row_shr:1 row_mask:0xf bank_mask:0xf
	v_exp_f32_e32 v193, v206
	v_exp_f32_e32 v209, v207
	v_cvt_pk_bf16_f32 v247, v202, v203
	v_add_f32_e32 v193, 1.0, v193
	v_rcp_f32_e32 v202, v193
	v_add_f32_e32 v193, 1.0, v209
	v_rcp_f32_e32 v203, v193
	v_pk_fma_f32 v[248:249], v[158:159], v[170:171], v[174:175]
	v_mov_b32_dpp v204, v138 row_shr:1 row_mask:0xf bank_mask:0xf
	v_mov_b32_dpp v205, v139 row_shr:1 row_mask:0xf bank_mask:0xf
	v_pk_fma_f32 v[248:249], v[166:167], v[196:197], v[248:249]
	v_pk_mul_f32 v[202:203], v[206:207], v[202:203]
	v_pk_fma_f32 v[204:205], v[162:163], v[204:205], v[248:249]
	v_lshl_add_u32 v246, s34, 8, v236
	v_pk_mul_f32 v[202:203], v[204:205], v[202:203]
	v_lshlrev_b64 v[204:205], 1, v[232:233]
	v_pk_fma_f32 v[232:233], v[132:133], v[184:185], v[188:189]
	v_mov_b64_e32 v[206:207], s[60:61]
	v_pk_fma_f32 v[232:233], v[152:153], v[180:181], v[232:233]
	v_cvt_pk_bf16_f32 v248, v202, v203
	v_pk_fma_f32 v[198:199], v[176:177], v[198:199], v[232:233]
	v_mad_i64_i32 v[202:203], s[34:35], v246, s74, v[206:207]
	v_exp_f32_e32 v193, v198
	v_exp_f32_e32 v232, v199
	v_lshl_add_u64 v[202:203], v[202:203], 0, v[204:205]
	v_add_f32_e32 v193, 1.0, v193
	v_rcp_f32_e32 v208, v193
	v_add_f32_e32 v193, 1.0, v232
	v_rcp_f32_e32 v209, v193
	v_pk_fma_f32 v[232:233], v[144:145], v[168:169], v[172:173]
	v_pk_fma_f32 v[140:141], v[140:141], v[184:185], v[188:189]
	v_pk_fma_f32 v[232:233], v[156:157], v[164:165], v[232:233]
	v_pk_mul_f32 v[198:199], v[198:199], v[208:209]
	v_pk_fma_f32 v[194:195], v[160:161], v[194:195], v[232:233]
	v_pk_fma_f32 v[208:209], v[146:147], v[170:171], v[174:175]
	v_pk_mul_f32 v[194:195], v[194:195], v[198:199]
	v_pk_fma_f32 v[198:199], v[134:135], v[186:187], v[190:191]
	v_pk_fma_f32 v[208:209], v[158:159], v[166:167], v[208:209]
	v_pk_fma_f32 v[198:199], v[154:155], v[182:183], v[198:199]
	v_pk_fma_f32 v[196:197], v[162:163], v[196:197], v[208:209]
	v_pk_fma_f32 v[198:199], v[178:179], v[200:201], v[198:199]
	v_cvt_pk_bf16_f32 v249, v194, v195
	v_exp_f32_e32 v200, v198
	v_exp_f32_e32 v201, v199
	v_pk_fma_f32 v[148:149], v[148:149], v[168:169], v[172:173]
	v_pk_add_f32 v[200:201], v[200:201], 1.0 op_sel_hi:[1,0]
	s_barrier
	v_rcp_f32_e32 v200, v200
	v_rcp_f32_e32 v201, v201
	v_or_b32_e32 v193, 1, v246
	v_pk_mul_f32 v[198:199], v[198:199], v[200:201]
	s_nop 0
	v_pk_mul_f32 v[196:197], v[196:197], v[198:199]
	v_pk_fma_f32 v[198:199], v[128:129], v[184:185], v[188:189]
	v_cvt_pk_bf16_f32 v250, v196, v197
	v_pk_fma_f32 v[198:199], v[132:133], v[180:181], v[198:199]
	v_mad_i64_i32 v[196:197], s[34:35], v193, s74, v[206:207]
	v_pk_fma_f32 v[152:153], v[152:153], v[176:177], v[198:199]
	v_lshl_add_u64 v[196:197], v[196:197], 0, v[204:205]
	v_exp_f32_e32 v193, v152
	v_exp_f32_e32 v198, v153
	v_add_f32_e32 v193, 1.0, v193
	v_rcp_f32_e32 v194, v193
	v_add_f32_e32 v193, 1.0, v198
	v_rcp_f32_e32 v195, v193
	v_pk_fma_f32 v[198:199], v[136:137], v[168:169], v[172:173]
	v_pk_fma_f32 v[128:129], v[128:129], v[180:181], v[140:141]
	v_pk_fma_f32 v[198:199], v[144:145], v[164:165], v[198:199]
	v_pk_fma_f32 v[128:129], v[132:133], v[176:177], v[128:129]
	v_pk_fma_f32 v[156:157], v[156:157], v[160:161], v[198:199]
	v_pk_mul_f32 v[152:153], v[152:153], v[194:195]
	v_pk_mul_f32 v[152:153], v[156:157], v[152:153]
	v_pk_fma_f32 v[156:157], v[130:131], v[186:187], v[190:191]
	v_exp_f32_e32 v140, v128
	v_pk_fma_f32 v[132:133], v[142:143], v[186:187], v[190:191]
	v_pk_fma_f32 v[156:157], v[134:135], v[182:183], v[156:157]
	v_pk_fma_f32 v[130:131], v[130:131], v[182:183], v[132:133]
	v_pk_fma_f32 v[154:155], v[154:155], v[178:179], v[156:157]
	v_pk_fma_f32 v[130:131], v[134:135], v[178:179], v[130:131]
	v_exp_f32_e32 v157, v154
	v_exp_f32_e32 v141, v129
	v_exp_f32_e32 v132, v130
	v_exp_f32_e32 v133, v131
	v_exp_f32_e32 v193, v155
	v_pk_add_f32 v[140:141], v[140:141], 1.0 op_sel_hi:[1,0]
	v_pk_add_f32 v[132:133], v[132:133], 1.0 op_sel_hi:[1,0]
	v_cvt_pk_bf16_f32 v254, v152, v153
	v_add_f32_e32 v152, 1.0, v157
	v_add_f32_e32 v153, 1.0, v193
	v_rcp_f32_e32 v140, v140
	v_rcp_f32_e32 v141, v141
; #define LAS __attribute__((address_space(3)))
; __device__ __forceinline__ float sigmoidf_(float x) { return __builtin_amdgcn_rcpf(1.0f + __expf(-x)); }
;     __device__ __forceinline__ void operator()(AccRef acc, const Unit& u, int wr, int wc, int fr, int fq) const {
;     ...
;                 f32x4 h2v = (f32x4){0.f, 0.f, 0.f, 0.f}, h3v = h2v, h2g = h2v, h3g = h2v;
;                 const int pb = ai * 2 + wr - 1;
;                 if (pb >= 0 && fr == 0) { const LAS float* xp = xch + (pb * 2) * 256 + clb + 4 * n;
;                     h2v = *(const LAS f32x4*)(xp); h3v = *(const LAS f32x4*)(xp + 256); h2g = *(const LAS f32x4*)(xp + 128); h3g = *(const LAS f32x4*)(xp + 256 + 128); }
;                 float o[4][4];
; #pragma unroll
;                 for (int j = 0; j < 4; ++j) {
;                     const float v0 = acc[ai][0][0][n][j], v1 = acc[ai][0][1][n][j], v2 = acc[ai][0][2][n][j], v3 = acc[ai][0][3][n][j];
;                     const float g0 = acc[ai][1][0][n][j], g1 = acc[ai][1][1][n][j], g2 = acc[ai][1][2][n][j], g3 = acc[ai][1][3][n][j];
;                     const float pv3 = dpp_upd<0x111>(h3v[j], v3), pv2 = dpp_upd<0x111>(h2v[j], v2), pg3 = dpp_upd<0x111>(h3g[j], g3), pg2 = dpp_upd<0x111>(h2g[j], g2);
;                     const float hv0 = bvv[j] + w2v[j] * v0 + w1v[j] * pv3 + w0v[j] * pv2, hv1 = bvv[j] + w2v[j] * v1 + w1v[j] * v0 + w0v[j] * pv3;
;                     const float hv2 = bvv[j] + w2v[j] * v2 + w1v[j] * v1 + w0v[j] * v0, hv3 = bvv[j] + w2v[j] * v3 + w1v[j] * v2 + w0v[j] * v1;
;                     const float hg0 = bvg[j] + w2g[j] * g0 + w1g[j] * pg3 + w0g[j] * pg2, hg1 = bvg[j] + w2g[j] * g1 + w1g[j] * g0 + w0g[j] * pg3;
;                     const float hg2 = bvg[j] + w2g[j] * g2 + w1g[j] * g1 + w0g[j] * g0, hg3 = bvg[j] + w2g[j] * g3 + w1g[j] * g2 + w0g[j] * g1;
;                     o[0][j] = hg0 * sigmoidf_(hg0) * hv0; o[1][j] = hg1 * sigmoidf_(hg1) * hv1; o[2][j] = hg2 * sigmoidf_(hg2) * hv2; o[3][j] = hg3 * sigmoidf_(hg3) * hv3; }
; #pragma unroll
;                 for (int m = 0; m < 4; ++m) { u32x2 w; w.x = cvt_pk_bf16(o[m][0], o[m][1]); w.y = cvt_pk_bf16(o[m][2], o[m][3]);
;                     *(u32x2*)(Aout + (size_t)(row0 + ai * 128 + m) * FH + hc0 + 4 * n) = w; } } }
	v_rcp_f32_e32 v132, v132
	v_rcp_f32_e32 v133, v133
	v_rcp_f32_e32 v152, v152
	v_rcp_f32_e32 v153, v153
	v_pk_fma_f32 v[142:143], v[150:151], v[170:171], v[174:175]
	v_pk_fma_f32 v[194:195], v[138:139], v[170:171], v[174:175]
	v_pk_fma_f32 v[136:137], v[136:137], v[164:165], v[148:149]
	v_pk_fma_f32 v[134:135], v[138:139], v[166:167], v[142:143]
	v_pk_fma_f32 v[194:195], v[146:147], v[166:167], v[194:195]
	v_pk_fma_f32 v[136:137], v[144:145], v[160:161], v[136:137]
	v_pk_mul_f32 v[128:129], v[128:129], v[140:141]
	v_pk_fma_f32 v[134:135], v[146:147], v[162:163], v[134:135]
	v_pk_mul_f32 v[130:131], v[130:131], v[132:133]
	v_pk_fma_f32 v[158:159], v[158:159], v[162:163], v[194:195]
	v_pk_mul_f32 v[152:153], v[154:155], v[152:153]
	v_pk_mul_f32 v[128:129], v[136:137], v[128:129]
	v_pk_mul_f32 v[130:131], v[134:135], v[130:131]
	v_pk_mul_f32 v[152:153], v[158:159], v[152:153]
	v_cvt_pk_bf16_f32 v251, v128, v129
	v_cvt_pk_bf16_f32 v253, v130, v131
	v_or_b32_e32 v130, 3, v246
	v_cvt_pk_bf16_f32 v255, v152, v153
	v_or_b32_e32 v152, 2, v246
	v_mad_i64_i32 v[130:131], s[34:35], v130, s74, v[206:207]
	v_mad_i64_i32 v[152:153], s[34:35], v152, s74, v[206:207]
	v_lshl_add_u64 v[140:141], v[130:131], 0, v[204:205]
	v_lshl_add_u64 v[152:153], v[152:153], 0, v[204:205]
	v_mov_b32_e32 v193, 0
	v_mov_b64_e32 v[194:195], 0
	v_mov_b64_e32 v[136:137], 0
	v_mov_b64_e32 v[138:139], 0
	v_mov_b64_e32 v[128:129], 0
	v_mov_b64_e32 v[130:131], 0
	v_mov_b64_e32 v[132:133], 0
	v_mov_b64_e32 v[134:135], 0
	s_barrier
	s_and_saveexec_b64 s[34:35], s[22:23]
	s_cbranch_execz .LBB0_320
	ds_read_b128 v[132:135], v237 offset:2048
	ds_read_b128 v[136:139], v237 offset:2560
	ds_read_b128 v[128:131], v237 offset:3072
	ds_read_b128 v[192:195], v237 offset:3584
.LBB0_320:
	s_or_b64 exec, exec, s[34:35]
	s_waitcnt lgkmcnt(0)
	v_mov_b32_dpp v192, v72 row_shr:1 row_mask:0xf bank_mask:0xf
	v_mov_b32_dpp v193, v73 row_shr:1 row_mask:0xf bank_mask:0xf
	v_pk_fma_f32 v[142:143], v[88:89], v[184:185], v[188:189]
	v_mov_b32_dpp v136, v64 row_shr:1 row_mask:0xf bank_mask:0xf
	v_mov_b32_dpp v137, v65 row_shr:1 row_mask:0xf bank_mask:0xf
	v_pk_fma_f32 v[142:143], v[180:181], v[192:193], v[142:143]
	v_mov_b32_dpp v128, v84 row_shr:1 row_mask:0xf bank_mask:0xf
	v_pk_fma_f32 v[136:137], v[176:177], v[136:137], v[142:143]
	v_mov_b32_dpp v129, v85 row_shr:1 row_mask:0xf bank_mask:0xf
	v_exp_f32_e32 v142, v136
	v_exp_f32_e32 v143, v137
	v_pk_fma_f32 v[144:145], v[92:93], v[168:169], v[172:173]
	v_mov_b32_dpp v132, v76 row_shr:1 row_mask:0xf bank_mask:0xf
	v_pk_add_f32 v[142:143], v[142:143], 1.0 op_sel_hi:[1,0]
	v_rcp_f32_e32 v142, v142
	v_rcp_f32_e32 v143, v143
	v_mov_b32_dpp v133, v77 row_shr:1 row_mask:0xf bank_mask:0xf
	v_pk_fma_f32 v[144:145], v[164:165], v[128:129], v[144:145]
	v_mov_b32_dpp v194, v74 row_shr:1 row_mask:0xf bank_mask:0xf
	v_pk_fma_f32 v[132:133], v[160:161], v[132:133], v[144:145]
	v_pk_mul_f32 v[136:137], v[136:137], v[142:143]
	v_mov_b32_dpp v195, v75 row_shr:1 row_mask:0xf bank_mask:0xf
	v_pk_mul_f32 v[132:133], v[132:133], v[136:137]
	v_pk_fma_f32 v[136:137], v[90:91], v[186:187], v[190:191]
	v_mov_b32_dpp v138, v66 row_shr:1 row_mask:0xf bank_mask:0xf
	v_mov_b32_dpp v139, v67 row_shr:1 row_mask:0xf bank_mask:0xf
	v_pk_fma_f32 v[136:137], v[182:183], v[194:195], v[136:137]
	v_mov_b32_dpp v130, v86 row_shr:1 row_mask:0xf bank_mask:0xf
	v_pk_fma_f32 v[136:137], v[178:179], v[138:139], v[136:137]
	v_mov_b32_dpp v131, v87 row_shr:1 row_mask:0xf bank_mask:0xf
	v_exp_f32_e32 v139, v136
	v_exp_f32_e32 v142, v137
	v_cvt_pk_bf16_f32 v144, v132, v133
	v_add_f32_e32 v132, 1.0, v139
	v_rcp_f32_e32 v132, v132
	v_add_f32_e32 v133, 1.0, v142
	v_rcp_f32_e32 v133, v133
	v_pk_fma_f32 v[142:143], v[94:95], v[170:171], v[174:175]
	v_mov_b32_dpp v134, v78 row_shr:1 row_mask:0xf bank_mask:0xf
	v_mov_b32_dpp v135, v79 row_shr:1 row_mask:0xf bank_mask:0xf
	v_pk_mul_f32 v[132:133], v[136:137], v[132:133]
	v_pk_fma_f32 v[136:137], v[68:69], v[184:185], v[188:189]
	v_pk_fma_f32 v[142:143], v[166:167], v[130:131], v[142:143]
	v_pk_fma_f32 v[136:137], v[88:89], v[180:181], v[136:137]
	v_pk_fma_f32 v[134:135], v[162:163], v[134:135], v[142:143]
	v_pk_fma_f32 v[136:137], v[176:177], v[192:193], v[136:137]
	v_add_u32_e32 v146, 0x80, v246
	v_exp_f32_e32 v142, v136
	v_exp_f32_e32 v143, v137
	v_pk_mul_f32 v[132:133], v[134:135], v[132:133]
	v_mov_b64_e32 v[134:135], s[60:61]
	v_cvt_pk_bf16_f32 v145, v132, v133
	v_mad_i64_i32 v[132:133], s[34:35], v146, s74, v[134:135]
	v_lshl_add_u64 v[132:133], v[132:133], 0, v[204:205]
	v_add_f32_e32 v138, 1.0, v142
	v_add_f32_e32 v139, 1.0, v143
	v_rcp_f32_e32 v138, v138
	v_rcp_f32_e32 v139, v139
	v_pk_fma_f32 v[142:143], v[80:81], v[168:169], v[172:173]
	v_pk_fma_f32 v[72:73], v[72:73], v[184:185], v[188:189]
	v_pk_fma_f32 v[142:143], v[92:93], v[164:165], v[142:143]
	v_pk_mul_f32 v[136:137], v[136:137], v[138:139]
	v_pk_fma_f32 v[128:129], v[160:161], v[128:129], v[142:143]
	v_pk_fma_f32 v[84:85], v[84:85], v[168:169], v[172:173]
	v_pk_mul_f32 v[128:129], v[128:129], v[136:137]
	v_pk_fma_f32 v[136:137], v[70:71], v[186:187], v[190:191]
	s_nop 0
	v_pk_fma_f32 v[136:137], v[90:91], v[182:183], v[136:137]
	s_nop 0
	v_pk_fma_f32 v[136:137], v[178:179], v[194:195], v[136:137]
	s_nop 0
	v_exp_f32_e32 v139, v136
	v_exp_f32_e32 v142, v137
	v_cvt_pk_bf16_f32 v138, v128, v129
	v_add_f32_e32 v128, 1.0, v139
	v_rcp_f32_e32 v128, v128
	v_add_f32_e32 v129, 1.0, v142
	v_rcp_f32_e32 v129, v129
	v_pk_fma_f32 v[142:143], v[82:83], v[170:171], v[174:175]
	v_pk_mul_f32 v[128:129], v[136:137], v[128:129]
	s_barrier
; #define LAS __attribute__((address_space(3)))
; __device__ __forceinline__ float sigmoidf_(float x) { return __builtin_amdgcn_rcpf(1.0f + __expf(-x)); }
;     __device__ __forceinline__ void operator()(AccRef acc, const Unit& u, int wr, int wc, int fr, int fq) const {
;     ...
;                 f32x4 h2v = (f32x4){0.f, 0.f, 0.f, 0.f}, h3v = h2v, h2g = h2v, h3g = h2v;
;                 const int pb = ai * 2 + wr - 1;
;                 if (pb >= 0 && fr == 0) { const LAS float* xp = xch + (pb * 2) * 256 + clb + 4 * n;
;                     h2v = *(const LAS f32x4*)(xp); h3v = *(const LAS f32x4*)(xp + 256); h2g = *(const LAS f32x4*)(xp + 128); h3g = *(const LAS f32x4*)(xp + 256 + 128); }
;                 float o[4][4];
; #pragma unroll
;                 for (int j = 0; j < 4; ++j) {
;                     const float v0 = acc[ai][0][0][n][j], v1 = acc[ai][0][1][n][j], v2 = acc[ai][0][2][n][j], v3 = acc[ai][0][3][n][j];
;                     const float g0 = acc[ai][1][0][n][j], g1 = acc[ai][1][1][n][j], g2 = acc[ai][1][2][n][j], g3 = acc[ai][1][3][n][j];
;                     const float pv3 = dpp_upd<0x111>(h3v[j], v3), pv2 = dpp_upd<0x111>(h2v[j], v2), pg3 = dpp_upd<0x111>(h3g[j], g3), pg2 = dpp_upd<0x111>(h2g[j], g2);
;                     const float hv0 = bvv[j] + w2v[j] * v0 + w1v[j] * pv3 + w0v[j] * pv2, hv1 = bvv[j] + w2v[j] * v1 + w1v[j] * v0 + w0v[j] * pv3;
;                     const float hv2 = bvv[j] + w2v[j] * v2 + w1v[j] * v1 + w0v[j] * v0, hv3 = bvv[j] + w2v[j] * v3 + w1v[j] * v2 + w0v[j] * v1;
;                     const float hg0 = bvg[j] + w2g[j] * g0 + w1g[j] * pg3 + w0g[j] * pg2, hg1 = bvg[j] + w2g[j] * g1 + w1g[j] * g0 + w0g[j] * pg3;
;                     const float hg2 = bvg[j] + w2g[j] * g2 + w1g[j] * g1 + w0g[j] * g0, hg3 = bvg[j] + w2g[j] * g3 + w1g[j] * g2 + w0g[j] * g1;
;                     o[0][j] = hg0 * sigmoidf_(hg0) * hv0; o[1][j] = hg1 * sigmoidf_(hg1) * hv1; o[2][j] = hg2 * sigmoidf_(hg2) * hv2; o[3][j] = hg3 * sigmoidf_(hg3) * hv3; }
; #pragma unroll
;                 for (int m = 0; m < 4; ++m) { u32x2 w; w.x = cvt_pk_bf16(o[m][0], o[m][1]); w.y = cvt_pk_bf16(o[m][2], o[m][3]);
;                     *(u32x2*)(Aout + (size_t)(row0 + ai * 128 + m) * FH + hc0 + 4 * n) = w; } } }
	v_pk_fma_f32 v[142:143], v[94:95], v[166:167], v[142:143]
	v_pk_fma_f32 v[136:137], v[76:77], v[168:169], v[172:173]
	v_pk_fma_f32 v[130:131], v[162:163], v[130:131], v[142:143]
	v_pk_fma_f32 v[136:137], v[80:81], v[164:165], v[136:137]
	v_pk_mul_f32 v[128:129], v[130:131], v[128:129]
	v_pk_fma_f32 v[130:131], v[64:65], v[184:185], v[188:189]
	v_pk_fma_f32 v[64:65], v[64:65], v[180:181], v[72:73]
	v_pk_fma_f32 v[130:131], v[68:69], v[180:181], v[130:131]
	v_pk_fma_f32 v[64:65], v[68:69], v[176:177], v[64:65]
	v_pk_fma_f32 v[88:89], v[88:89], v[176:177], v[130:131]
	v_pk_fma_f32 v[92:93], v[92:93], v[160:161], v[136:137]
	v_exp_f32_e32 v130, v88
	v_exp_f32_e32 v131, v89
	v_exp_f32_e32 v72, v64
	v_pk_add_f32 v[130:131], v[130:131], 1.0 op_sel_hi:[1,0]
	v_rcp_f32_e32 v130, v130
	v_rcp_f32_e32 v131, v131
	v_pk_fma_f32 v[68:69], v[74:75], v[186:187], v[190:191]
	v_exp_f32_e32 v73, v65
	v_pk_mul_f32 v[88:89], v[88:89], v[130:131]
	v_pk_mul_f32 v[88:89], v[92:93], v[88:89]
	v_pk_fma_f32 v[92:93], v[66:67], v[186:187], v[190:191]
	v_pk_fma_f32 v[66:67], v[66:67], v[182:183], v[68:69]
	v_pk_fma_f32 v[92:93], v[70:71], v[182:183], v[92:93]
	v_pk_fma_f32 v[66:67], v[70:71], v[178:179], v[66:67]
	v_pk_fma_f32 v[90:91], v[90:91], v[178:179], v[92:93]
	v_exp_f32_e32 v93, v90
	v_exp_f32_e32 v68, v66
	v_exp_f32_e32 v69, v67
	v_exp_f32_e32 v130, v91
	v_pk_add_f32 v[72:73], v[72:73], 1.0 op_sel_hi:[1,0]
	v_pk_add_f32 v[68:69], v[68:69], 1.0 op_sel_hi:[1,0]
	v_cvt_pk_bf16_f32 v198, v88, v89
	v_add_f32_e32 v88, 1.0, v93
	v_add_f32_e32 v89, 1.0, v130
	v_rcp_f32_e32 v72, v72
	v_rcp_f32_e32 v73, v73
	v_rcp_f32_e32 v68, v68
	v_rcp_f32_e32 v69, v69
	v_rcp_f32_e32 v88, v88
	v_rcp_f32_e32 v89, v89
	v_pk_fma_f32 v[74:75], v[86:87], v[170:171], v[174:175]
	v_pk_fma_f32 v[130:131], v[78:79], v[170:171], v[174:175]
	v_pk_fma_f32 v[76:77], v[76:77], v[164:165], v[84:85]
	v_pk_fma_f32 v[70:71], v[78:79], v[166:167], v[74:75]
	v_pk_fma_f32 v[130:131], v[82:83], v[166:167], v[130:131]
	v_pk_fma_f32 v[76:77], v[80:81], v[160:161], v[76:77]
	v_pk_mul_f32 v[64:65], v[64:65], v[72:73]
	v_pk_fma_f32 v[70:71], v[82:83], v[162:163], v[70:71]
	v_pk_mul_f32 v[66:67], v[66:67], v[68:69]
	v_pk_fma_f32 v[94:95], v[94:95], v[162:163], v[130:131]
	v_pk_mul_f32 v[88:89], v[90:91], v[88:89]
	v_pk_mul_f32 v[64:65], v[76:77], v[64:65]
	v_pk_mul_f32 v[66:67], v[70:71], v[66:67]
	v_pk_mul_f32 v[88:89], v[94:95], v[88:89]
	v_cvt_pk_bf16_f32 v148, v64, v65
	v_cvt_pk_bf16_f32 v149, v66, v67
	v_add_u32_e32 v66, 0x83, v246
	v_cvt_pk_bf16_f32 v155, v128, v129
	v_add_u32_e32 v128, 0x81, v246
	v_cvt_pk_bf16_f32 v199, v88, v89
	v_add_u32_e32 v88, 0x82, v246
	v_mad_i64_i32 v[66:67], s[34:35], v66, s74, v[134:135]
	v_mad_i64_i32 v[128:129], s[34:35], v128, s74, v[134:135]
	v_mad_i64_i32 v[88:89], s[34:35], v88, s74, v[134:135]
	v_lshl_add_u64 v[82:83], v[66:67], 0, v[204:205]
	v_lshl_add_u64 v[128:129], v[128:129], 0, v[204:205]
	v_lshl_add_u64 v[88:89], v[88:89], 0, v[204:205]
	v_mov_b32_e32 v64, 0
	v_mov_b64_e32 v[70:71], 0
	v_mov_b64_e32 v[72:73], 0
	v_mov_b64_e32 v[78:79], 0
	v_mov_b64_e32 v[80:81], 0
	v_mov_b64_e32 v[66:67], 0
	v_mov_b64_e32 v[68:69], 0
	v_mov_b64_e32 v[74:75], 0
	v_mov_b64_e32 v[76:77], 0
	v_mov_b32_e32 v154, v138
	s_barrier
	s_and_saveexec_b64 s[34:35], s[18:19]
	s_cbranch_execz .LBB0_322
	ds_read_b128 v[74:77], v242
	ds_read_b128 v[66:69], v241
	ds_read_b128 v[78:81], v240
	ds_read_b128 v[70:73], v239
;     __device__ __forceinline__ void operator()(AccRef acc, const Unit& u, int wr, int wc, int fr, int fq) const {
;     ...
;         for (int n = 0; n < 2; ++n) {
;             const f32x4 w0v = cwv[n][0], w1v = cwv[n][1], w2v = cwv[n][2], bvv = cwv[n][3], w0g = cwv[n][4], w1g = cwv[n][5], w2g = cwv[n][6], bvg = cwv[n][7];
; #pragma unroll
;             for (int ai = 0; ai < 2; ++ai) {
;                 if (n == 0 && ai == 0) {
;                     asm volatile("" ::: "memory");
;                     const float* cv = cw + hc0 + 4; const float* cg = cv + FH; const float* bp = cb + hc0 + 4;
;                     cwv[1][0] = *(const f32x4*)(cv); cwv[1][1] = *(const f32x4*)(cv + F2); cwv[1][2] = *(const f32x4*)(cv + 2 * F2); cwv[1][3] = *(const f32x4*)(bp);
;                     cwv[1][4] = *(const f32x4*)(cg); cwv[1][5] = *(const f32x4*)(cg + F2); cwv[1][6] = *(const f32x4*)(cg + 2 * F2); cwv[1][7] = *(const f32x4*)(bp + FH);
;                     asm volatile("" ::: "memory"); }
;                 f32x4 h2v = (f32x4){0.f, 0.f, 0.f, 0.f}, h3v = h2v, h2g = h2v, h3g = h2v;
;                 const int pb = ai * 2 + wr - 1;
;                 if (pb >= 0 && fr == 0) { const LAS float* xp = xch + (pb * 2) * 256 + clb + 4 * n;
;                     h2v = *(const LAS f32x4*)(xp); h3v = *(const LAS f32x4*)(xp + 256); h2g = *(const LAS f32x4*)(xp + 128); h3g = *(const LAS f32x4*)(xp + 256 + 128); }
;                 float o[4][4];
; #pragma unroll
;                 for (int j = 0; j < 4; ++j) {
;                     const float v0 = acc[ai][0][0][n][j], v1 = acc[ai][0][1][n][j], v2 = acc[ai][0][2][n][j], v3 = acc[ai][0][3][n][j];
;                     const float g0 = acc[ai][1][0][n][j], g1 = acc[ai][1][1][n][j], g2 = acc[ai][1][2][n][j], g3 = acc[ai][1][3][n][j];
;                     const float pv3 = dpp_upd<0x111>(h3v[j], v3), pv2 = dpp_upd<0x111>(h2v[j], v2), pg3 = dpp_upd<0x111>(h3g[j], g3), pg2 = dpp_upd<0x111>(h2g[j], g2);
;                     const float hv0 = bvv[j] + w2v[j] * v0 + w1v[j] * pv3 + w0v[j] * pv2, hv1 = bvv[j] + w2v[j] * v1 + w1v[j] * v0 + w0v[j] * pv3;
;                     const float hv2 = bvv[j] + w2v[j] * v2 + w1v[j] * v1 + w0v[j] * v0, hv3 = bvv[j] + w2v[j] * v3 + w1v[j] * v2 + w0v[j] * v1;
;                     const float hg0 = bvg[j] + w2g[j] * g0 + w1g[j] * pg3 + w0g[j] * pg2, hg1 = bvg[j] + w2g[j] * g1 + w1g[j] * g0 + w0g[j] * pg3;
.LBB0_322:
	s_or_b64 exec, exec, s[34:35]
	s_waitcnt lgkmcnt(0)
	v_mov_b32_dpp v70, v44 row_shr:1 row_mask:0xf bank_mask:0xf
	v_mov_b32_dpp v71, v45 row_shr:1 row_mask:0xf bank_mask:0xf
	s_waitcnt vmcnt(0)
	v_pk_fma_f32 v[84:85], v[56:57], v[120:121], v[124:125]
	v_mov_b32_dpp v78, v32 row_shr:1 row_mask:0xf bank_mask:0xf
	v_mov_b32_dpp v79, v33 row_shr:1 row_mask:0xf bank_mask:0xf
	v_pk_fma_f32 v[84:85], v[116:117], v[70:71], v[84:85]
	v_mov_b32_dpp v66, v52 row_shr:1 row_mask:0xf bank_mask:0xf
	v_pk_fma_f32 v[78:79], v[112:113], v[78:79], v[84:85]
	v_mov_b32_dpp v67, v53 row_shr:1 row_mask:0xf bank_mask:0xf
	v_exp_f32_e32 v84, v78
	v_exp_f32_e32 v85, v79
	v_pk_fma_f32 v[86:87], v[60:61], v[104:105], v[108:109]
	v_pk_add_f32 v[84:85], v[84:85], 1.0 op_sel_hi:[1,0]
	v_rcp_f32_e32 v84, v84
	v_rcp_f32_e32 v85, v85
	v_mov_b32_dpp v74, v40 row_shr:1 row_mask:0xf bank_mask:0xf
	v_mov_b32_dpp v75, v41 row_shr:1 row_mask:0xf bank_mask:0xf
	v_pk_fma_f32 v[86:87], v[100:101], v[66:67], v[86:87]
	v_pk_mul_f32 v[78:79], v[78:79], v[84:85]
	v_pk_fma_f32 v[74:75], v[96:97], v[74:75], v[86:87]
	v_mov_b32_dpp v72, v46 row_shr:1 row_mask:0xf bank_mask:0xf
	v_mov_b32_dpp v73, v47 row_shr:1 row_mask:0xf bank_mask:0xf
	v_pk_mul_f32 v[74:75], v[74:75], v[78:79]
	v_pk_fma_f32 v[78:79], v[58:59], v[122:123], v[126:127]
	v_mov_b32_dpp v80, v34 row_shr:1 row_mask:0xf bank_mask:0xf
	v_mov_b32_dpp v81, v35 row_shr:1 row_mask:0xf bank_mask:0xf
	v_pk_fma_f32 v[78:79], v[118:119], v[72:73], v[78:79]
	v_mov_b32_dpp v68, v54 row_shr:1 row_mask:0xf bank_mask:0xf
	v_pk_fma_f32 v[78:79], v[114:115], v[80:81], v[78:79]
	v_mov_b32_dpp v69, v55 row_shr:1 row_mask:0xf bank_mask:0xf
	v_exp_f32_e32 v80, v78
	v_exp_f32_e32 v81, v79
	v_pk_fma_f32 v[84:85], v[62:63], v[106:107], v[110:111]
	v_pk_add_f32 v[80:81], v[80:81], 1.0 op_sel_hi:[1,0]
	v_rcp_f32_e32 v80, v80
	v_rcp_f32_e32 v81, v81
	v_mov_b32_dpp v76, v42 row_shr:1 row_mask:0xf bank_mask:0xf
	v_mov_b32_dpp v77, v43 row_shr:1 row_mask:0xf bank_mask:0xf
	v_pk_fma_f32 v[84:85], v[102:103], v[68:69], v[84:85]
	v_pk_mul_f32 v[78:79], v[78:79], v[80:81]
	v_pk_fma_f32 v[76:77], v[98:99], v[76:77], v[84:85]
	v_cvt_pk_bf16_f32 v92, v74, v75
	v_pk_mul_f32 v[76:77], v[76:77], v[78:79]
	v_pk_fma_f32 v[44:45], v[44:45], v[120:121], v[124:125]
	v_cvt_pk_bf16_f32 v93, v76, v77
	v_pk_fma_f32 v[76:77], v[36:37], v[120:121], v[124:125]
	v_mov_b32_e32 v90, v247
	v_mov_b32_e32 v91, v248
	global_store_dwordx4 v[202:203], v[90:93], off
	v_pk_fma_f32 v[76:77], v[56:57], v[116:117], v[76:77]
	v_pk_fma_f32 v[52:53], v[52:53], v[104:105], v[108:109]
	v_pk_fma_f32 v[70:71], v[112:113], v[70:71], v[76:77]
	s_nop 0
	v_exp_f32_e32 v74, v70
	v_exp_f32_e32 v75, v71
	s_nop 0
	v_pk_add_f32 v[74:75], v[74:75], 1.0 op_sel_hi:[1,0]
	v_rcp_f32_e32 v74, v74
	v_rcp_f32_e32 v75, v75
	v_pk_fma_f32 v[76:77], v[48:49], v[104:105], v[108:109]
	v_pk_mul_f32 v[70:71], v[70:71], v[74:75]
	v_pk_fma_f32 v[76:77], v[60:61], v[100:101], v[76:77]
	v_pk_fma_f32 v[74:75], v[50:51], v[106:107], v[110:111]
	v_pk_fma_f32 v[66:67], v[96:97], v[66:67], v[76:77]
	v_pk_fma_f32 v[74:75], v[62:63], v[102:103], v[74:75]
	v_pk_mul_f32 v[66:67], v[66:67], v[70:71]
	v_pk_fma_f32 v[70:71], v[38:39], v[122:123], v[126:127]
	v_pk_fma_f32 v[68:69], v[98:99], v[68:69], v[74:75]
	v_pk_fma_f32 v[70:71], v[58:59], v[118:119], v[70:71]
	v_cvt_pk_bf16_f32 v136, v66, v67
	v_pk_fma_f32 v[70:71], v[114:115], v[72:73], v[70:71]
	s_nop 0
	v_exp_f32_e32 v72, v70
	v_exp_f32_e32 v73, v71
	s_nop 0
	v_pk_add_f32 v[72:73], v[72:73], 1.0 op_sel_hi:[1,0]
	v_rcp_f32_e32 v72, v72
	s_barrier
	v_rcp_f32_e32 v73, v73
	s_nop 0
	v_pk_mul_f32 v[70:71], v[70:71], v[72:73]
	s_nop 0
	v_pk_mul_f32 v[68:69], v[68:69], v[70:71]
	s_nop 0
	v_cvt_pk_bf16_f32 v137, v68, v69
	v_pk_fma_f32 v[68:69], v[32:33], v[120:121], v[124:125]
	v_mov_b32_e32 v134, v249
	v_mov_b32_e32 v135, v250
	global_store_dwordx4 v[196:197], v[134:137], off
	v_pk_fma_f32 v[68:69], v[36:37], v[116:117], v[68:69]
	v_pk_fma_f32 v[32:33], v[32:33], v[116:117], v[44:45]
	v_pk_fma_f32 v[56:57], v[56:57], v[112:113], v[68:69]
	v_pk_fma_f32 v[32:33], v[36:37], v[112:113], v[32:33]
	v_exp_f32_e32 v66, v56
	v_exp_f32_e32 v67, v57
	s_nop 0
	v_pk_add_f32 v[66:67], v[66:67], 1.0 op_sel_hi:[1,0]
	v_rcp_f32_e32 v66, v66
	v_rcp_f32_e32 v67, v67
	v_pk_fma_f32 v[68:69], v[40:41], v[104:105], v[108:109]
	v_exp_f32_e32 v44, v32
	v_pk_fma_f32 v[68:69], v[48:49], v[100:101], v[68:69]
	v_pk_mul_f32 v[56:57], v[56:57], v[66:67]
	v_pk_fma_f32 v[60:61], v[60:61], v[96:97], v[68:69]
	v_pk_fma_f32 v[36:37], v[46:47], v[122:123], v[126:127]
	v_pk_mul_f32 v[56:57], v[60:61], v[56:57]
	v_pk_fma_f32 v[60:61], v[34:35], v[122:123], v[126:127]
	v_pk_fma_f32 v[34:35], v[34:35], v[118:119], v[36:37]
	v_pk_fma_f32 v[60:61], v[38:39], v[118:119], v[60:61]
	v_pk_fma_f32 v[34:35], v[38:39], v[114:115], v[34:35]
	v_pk_fma_f32 v[58:59], v[58:59], v[114:115], v[60:61]
	v_exp_f32_e32 v60, v58
	v_exp_f32_e32 v45, v33
	v_exp_f32_e32 v36, v34
	v_exp_f32_e32 v37, v35
	v_exp_f32_e32 v61, v59
	v_cvt_pk_bf16_f32 v164, v56, v57
	v_pk_add_f32 v[44:45], v[44:45], 1.0 op_sel_hi:[1,0]
	v_pk_add_f32 v[36:37], v[36:37], 1.0 op_sel_hi:[1,0]
	v_pk_add_f32 v[60:61], v[60:61], 1.0 op_sel_hi:[1,0]
	v_rcp_f32_e32 v44, v44
	v_rcp_f32_e32 v45, v45
	v_rcp_f32_e32 v36, v36
	v_rcp_f32_e32 v37, v37
	v_rcp_f32_e32 v60, v60
	v_rcp_f32_e32 v61, v61
	v_pk_fma_f32 v[46:47], v[54:55], v[106:107], v[110:111]
	v_pk_fma_f32 v[66:67], v[42:43], v[106:107], v[110:111]
	v_pk_fma_f32 v[40:41], v[40:41], v[100:101], v[52:53]
	v_pk_fma_f32 v[38:39], v[42:43], v[102:103], v[46:47]
	v_pk_fma_f32 v[66:67], v[50:51], v[102:103], v[66:67]
	v_pk_fma_f32 v[40:41], v[48:49], v[96:97], v[40:41]
	v_pk_mul_f32 v[32:33], v[32:33], v[44:45]
	v_pk_fma_f32 v[38:39], v[50:51], v[98:99], v[38:39]
	v_pk_mul_f32 v[34:35], v[34:35], v[36:37]
	v_pk_fma_f32 v[62:63], v[62:63], v[98:99], v[66:67]
	v_pk_mul_f32 v[58:59], v[58:59], v[60:61]
	v_pk_mul_f32 v[32:33], v[40:41], v[32:33]
	v_pk_mul_f32 v[34:35], v[38:39], v[34:35]
	v_pk_mul_f32 v[58:59], v[62:63], v[58:59]
	v_cvt_pk_bf16_f32 v160, v32, v33
	v_cvt_pk_bf16_f32 v161, v34, v35
	v_cvt_pk_bf16_f32 v57, v58, v59
	v_mov_b32_e32 v158, v251
	v_mov_b32_e32 v159, v253
	global_store_dwordx4 v[140:141], v[158:161], off
	v_mov_b32_e32 v65, 0
	v_mov_b64_e32 v[66:67], 0
	v_mov_b64_e32 v[40:41], 0
	v_mov_b64_e32 v[42:43], 0
	v_mov_b64_e32 v[32:33], 0
	v_mov_b64_e32 v[34:35], 0
	v_mov_b64_e32 v[36:37], 0
	v_mov_b64_e32 v[38:39], 0
	v_mov_b32_e32 v162, v254
	v_mov_b32_e32 v163, v255
	v_mov_b32_e32 v165, v57
	global_store_dwordx4 v[152:153], v[162:165], off
	s_barrier
	s_and_saveexec_b64 s[34:35], s[22:23]
	s_cbranch_execz .LBB0_305
	ds_read_b128 v[36:39], v237 offset:2064
	ds_read_b128 v[40:43], v237 offset:2576
	ds_read_b128 v[32:35], v237 offset:3088
	ds_read_b128 v[64:67], v237 offset:3600
	s_branch .LBB0_305

; #define LAS __attribute__((address_space(3)))
; __device__ __forceinline__ float sigmoidf_(float x) { return __builtin_amdgcn_rcpf(1.0f + __expf(-x)); }
;     __device__ __forceinline__ void operator()(AccRef acc, const Unit& u, int wr, int wc, int fr, int fq) const {
;     ...
;                 f32x4 h2v = (f32x4){0.f, 0.f, 0.f, 0.f}, h3v = h2v, h2g = h2v, h3g = h2v;
;                 const int pb = ai * 2 + wr - 1;
;                 if (pb >= 0 && fr == 0) { const LAS float* xp = xch + (pb * 2) * 256 + clb + 4 * n;
;                     h2v = *(const LAS f32x4*)(xp); h3v = *(const LAS f32x4*)(xp + 256); h2g = *(const LAS f32x4*)(xp + 128); h3g = *(const LAS f32x4*)(xp + 256 + 128); }
;                 float o[4][4];
; #pragma unroll
;                 for (int j = 0; j < 4; ++j) {
;                     const float v0 = acc[ai][0][0][n][j], v1 = acc[ai][0][1][n][j], v2 = acc[ai][0][2][n][j], v3 = acc[ai][0][3][n][j];
;                     const float g0 = acc[ai][1][0][n][j], g1 = acc[ai][1][1][n][j], g2 = acc[ai][1][2][n][j], g3 = acc[ai][1][3][n][j];
;                     const float pv3 = dpp_upd<0x111>(h3v[j], v3), pv2 = dpp_upd<0x111>(h2v[j], v2), pg3 = dpp_upd<0x111>(h3g[j], g3), pg2 = dpp_upd<0x111>(h2g[j], g2);
;                     const float hv0 = bvv[j] + w2v[j] * v0 + w1v[j] * pv3 + w0v[j] * pv2, hv1 = bvv[j] + w2v[j] * v1 + w1v[j] * v0 + w0v[j] * pv3;
;                     const float hv2 = bvv[j] + w2v[j] * v2 + w1v[j] * v1 + w0v[j] * v0, hv3 = bvv[j] + w2v[j] * v3 + w1v[j] * v2 + w0v[j] * v1;
;                     const float hg0 = bvg[j] + w2g[j] * g0 + w1g[j] * pg3 + w0g[j] * pg2, hg1 = bvg[j] + w2g[j] * g1 + w1g[j] * g0 + w0g[j] * pg3;
;                     const float hg2 = bvg[j] + w2g[j] * g2 + w1g[j] * g1 + w0g[j] * g0, hg3 = bvg[j] + w2g[j] * g3 + w1g[j] * g2 + w0g[j] * g1;
;                     o[0][j] = hg0 * sigmoidf_(hg0) * hv0; o[1][j] = hg1 * sigmoidf_(hg1) * hv1; o[2][j] = hg2 * sigmoidf_(hg2) * hv2; o[3][j] = hg3 * sigmoidf_(hg3) * hv3; }
; #pragma unroll
;                 for (int m = 0; m < 4; ++m) { u32x2 w; w.x = cvt_pk_bf16(o[m][0], o[m][1]); w.y = cvt_pk_bf16(o[m][2], o[m][3]);
;                     *(u32x2*)(Aout + (size_t)(row0 + ai * 128 + m) * FH + hc0 + 4 * n) = w; } } }
.LBB0_754:
	s_or_b64 exec, exec, s[40:41]
	s_waitcnt lgkmcnt(0)
	v_mov_b32_dpp v64, v8 row_shr:1 row_mask:0xf bank_mask:0xf
	v_mov_b32_dpp v65, v9 row_shr:1 row_mask:0xf bank_mask:0xf
	v_pk_fma_f32 v[44:45], v[24:25], v[120:121], v[124:125]
	v_mov_b32_dpp v40, v0 row_shr:1 row_mask:0xf bank_mask:0xf
	v_mov_b32_dpp v41, v1 row_shr:1 row_mask:0xf bank_mask:0xf
	v_pk_fma_f32 v[44:45], v[116:117], v[64:65], v[44:45]
	v_mov_b32_dpp v32, v20 row_shr:1 row_mask:0xf bank_mask:0xf
	v_pk_fma_f32 v[40:41], v[112:113], v[40:41], v[44:45]
	v_mov_b32_dpp v33, v21 row_shr:1 row_mask:0xf bank_mask:0xf
	v_exp_f32_e32 v44, v40
	v_exp_f32_e32 v45, v41
	v_pk_fma_f32 v[46:47], v[28:29], v[104:105], v[108:109]
	v_mov_b32_dpp v36, v12 row_shr:1 row_mask:0xf bank_mask:0xf
	v_pk_add_f32 v[44:45], v[44:45], 1.0 op_sel_hi:[1,0]
	v_rcp_f32_e32 v44, v44
	v_rcp_f32_e32 v45, v45
	v_mov_b32_dpp v37, v13 row_shr:1 row_mask:0xf bank_mask:0xf
	v_pk_fma_f32 v[46:47], v[100:101], v[32:33], v[46:47]
	v_mov_b32_dpp v66, v10 row_shr:1 row_mask:0xf bank_mask:0xf
	v_pk_fma_f32 v[36:37], v[96:97], v[36:37], v[46:47]
	v_pk_mul_f32 v[40:41], v[40:41], v[44:45]
	v_mov_b32_dpp v67, v11 row_shr:1 row_mask:0xf bank_mask:0xf
	v_pk_mul_f32 v[36:37], v[36:37], v[40:41]
	v_pk_fma_f32 v[40:41], v[26:27], v[122:123], v[126:127]
	v_mov_b32_dpp v42, v2 row_shr:1 row_mask:0xf bank_mask:0xf
	v_mov_b32_dpp v43, v3 row_shr:1 row_mask:0xf bank_mask:0xf
	v_pk_fma_f32 v[40:41], v[118:119], v[66:67], v[40:41]
	v_cvt_pk_bf16_f32 v146, v36, v37
	v_pk_fma_f32 v[40:41], v[114:115], v[42:43], v[40:41]
	v_mov_b32_dpp v34, v22 row_shr:1 row_mask:0xf bank_mask:0xf
	v_exp_f32_e32 v42, v40
	v_exp_f32_e32 v43, v41
	v_mov_b32_dpp v35, v23 row_shr:1 row_mask:0xf bank_mask:0xf
	v_pk_add_f32 v[42:43], v[42:43], 1.0 op_sel_hi:[1,0]
	v_rcp_f32_e32 v42, v42
	v_rcp_f32_e32 v43, v43
	v_pk_fma_f32 v[44:45], v[30:31], v[106:107], v[110:111]
	v_mov_b32_dpp v38, v14 row_shr:1 row_mask:0xf bank_mask:0xf
	v_mov_b32_dpp v39, v15 row_shr:1 row_mask:0xf bank_mask:0xf
	v_pk_fma_f32 v[44:45], v[102:103], v[34:35], v[44:45]
	v_pk_mul_f32 v[40:41], v[40:41], v[42:43]
	v_pk_fma_f32 v[38:39], v[98:99], v[38:39], v[44:45]
	v_pk_fma_f32 v[8:9], v[8:9], v[120:121], v[124:125]
	v_pk_mul_f32 v[38:39], v[38:39], v[40:41]
	v_pk_fma_f32 v[20:21], v[20:21], v[104:105], v[108:109]
	v_cvt_pk_bf16_f32 v147, v38, v39
	v_pk_fma_f32 v[38:39], v[4:5], v[120:121], v[124:125]
	global_store_dwordx4 v[132:133], v[144:147], off
	v_pk_fma_f32 v[38:39], v[24:25], v[116:117], v[38:39]
	s_and_b64 vcc, exec, s[14:15]
	v_pk_fma_f32 v[38:39], v[112:113], v[64:65], v[38:39]
	s_mov_b32 s41, s30
	v_exp_f32_e32 v36, v38
	v_exp_f32_e32 v37, v39
	s_mov_b32 s40, s34
	s_mov_b64 s[44:45], s[38:39]
	v_pk_add_f32 v[36:37], v[36:37], 1.0 op_sel_hi:[1,0]
	v_rcp_f32_e32 v36, v36
	v_rcp_f32_e32 v37, v37
	v_pk_fma_f32 v[40:41], v[16:17], v[104:105], v[108:109]
	s_mov_b64 s[42:43], s[36:37]
	v_pk_fma_f32 v[40:41], v[28:29], v[100:101], v[40:41]
	v_pk_mul_f32 v[36:37], v[38:39], v[36:37]
	v_pk_fma_f32 v[32:33], v[96:97], v[32:33], v[40:41]
	v_pk_fma_f32 v[40:41], v[18:19], v[106:107], v[110:111]
	v_pk_mul_f32 v[32:33], v[32:33], v[36:37]
	v_pk_fma_f32 v[36:37], v[6:7], v[122:123], v[126:127]
	v_cvt_pk_bf16_f32 v156, v32, v33
	v_pk_fma_f32 v[36:37], v[26:27], v[118:119], v[36:37]
	v_pk_fma_f32 v[40:41], v[30:31], v[102:103], v[40:41]
	s_barrier
	v_pk_fma_f32 v[36:37], v[114:115], v[66:67], v[36:37]
	v_pk_fma_f32 v[34:35], v[98:99], v[34:35], v[40:41]
	v_exp_f32_e32 v38, v36
	v_exp_f32_e32 v39, v37
	s_nop 0
	v_pk_add_f32 v[38:39], v[38:39], 1.0 op_sel_hi:[1,0]
	v_rcp_f32_e32 v38, v38
	v_rcp_f32_e32 v39, v39
	s_nop 0
	v_pk_mul_f32 v[36:37], v[36:37], v[38:39]
	s_nop 0
	v_pk_mul_f32 v[34:35], v[34:35], v[36:37]
	s_nop 0
	v_cvt_pk_bf16_f32 v157, v34, v35
	v_pk_fma_f32 v[34:35], v[0:1], v[120:121], v[124:125]
	global_store_dwordx4 v[128:129], v[154:157], off
	v_pk_fma_f32 v[34:35], v[4:5], v[116:117], v[34:35]
	v_pk_fma_f32 v[0:1], v[0:1], v[116:117], v[8:9]
	v_pk_fma_f32 v[24:25], v[24:25], v[112:113], v[34:35]
	v_pk_fma_f32 v[0:1], v[4:5], v[112:113], v[0:1]
	v_exp_f32_e32 v32, v24
	v_exp_f32_e32 v33, v25
	v_exp_f32_e32 v8, v0
	v_pk_add_f32 v[32:33], v[32:33], 1.0 op_sel_hi:[1,0]
	v_rcp_f32_e32 v32, v32
	v_rcp_f32_e32 v33, v33
	v_pk_fma_f32 v[34:35], v[12:13], v[104:105], v[108:109]
	v_pk_fma_f32 v[4:5], v[10:11], v[122:123], v[126:127]
	v_pk_fma_f32 v[34:35], v[16:17], v[100:101], v[34:35]
	v_pk_mul_f32 v[24:25], v[24:25], v[32:33]
	v_pk_fma_f32 v[28:29], v[28:29], v[96:97], v[34:35]
	v_pk_mul_f32 v[24:25], v[28:29], v[24:25]
	v_pk_fma_f32 v[28:29], v[2:3], v[122:123], v[126:127]
	v_pk_fma_f32 v[2:3], v[2:3], v[118:119], v[4:5]
	v_pk_fma_f32 v[28:29], v[6:7], v[118:119], v[28:29]
	v_pk_fma_f32 v[2:3], v[6:7], v[114:115], v[2:3]
	v_pk_fma_f32 v[26:27], v[26:27], v[114:115], v[28:29]
	v_exp_f32_e32 v28, v26
	v_exp_f32_e32 v29, v27
	v_exp_f32_e32 v9, v1
	v_exp_f32_e32 v4, v2
	v_exp_f32_e32 v5, v3
	v_cvt_pk_bf16_f32 v200, v24, v25
	v_pk_add_f32 v[28:29], v[28:29], 1.0 op_sel_hi:[1,0]
	v_pk_add_f32 v[8:9], v[8:9], 1.0 op_sel_hi:[1,0]
	v_pk_add_f32 v[4:5], v[4:5], 1.0 op_sel_hi:[1,0]
	v_rcp_f32_e32 v28, v28
	v_rcp_f32_e32 v29, v29
	v_rcp_f32_e32 v8, v8
	v_rcp_f32_e32 v9, v9
	v_rcp_f32_e32 v4, v4
	v_rcp_f32_e32 v5, v5
	v_pk_fma_f32 v[32:33], v[14:15], v[106:107], v[110:111]
	v_pk_fma_f32 v[10:11], v[22:23], v[106:107], v[110:111]
	v_pk_fma_f32 v[32:33], v[18:19], v[102:103], v[32:33]
	v_pk_fma_f32 v[12:13], v[12:13], v[100:101], v[20:21]
	v_pk_fma_f32 v[6:7], v[14:15], v[102:103], v[10:11]
	v_pk_fma_f32 v[30:31], v[30:31], v[98:99], v[32:33]
	v_pk_mul_f32 v[26:27], v[26:27], v[28:29]
	v_pk_fma_f32 v[12:13], v[16:17], v[96:97], v[12:13]
	v_pk_mul_f32 v[0:1], v[0:1], v[8:9]
	v_pk_fma_f32 v[6:7], v[18:19], v[98:99], v[6:7]
	v_pk_mul_f32 v[2:3], v[2:3], v[4:5]
	v_pk_mul_f32 v[26:27], v[30:31], v[26:27]
	v_pk_mul_f32 v[0:1], v[12:13], v[0:1]
	v_pk_mul_f32 v[2:3], v[6:7], v[2:3]
	v_cvt_pk_bf16_f32 v201, v26, v27
	v_cvt_pk_bf16_f32 v150, v0, v1
	v_cvt_pk_bf16_f32 v151, v2, v3
	global_store_dwordx4 v[88:89], v[198:201], off
	global_store_dwordx4 v[82:83], v[148:151], off
	s_cbranch_vccnz .LBB0_773

; #define LAS __attribute__((address_space(3)))
;     __device__ __forceinline__ void operator()(AccRef acc, const Unit& u, int wr, int wc, int fr, int fq) const {
;     ...
;         const int hc0 = 128 * u.pn + clb, row0 = u.pm * 256 + wr * 64 + 4 * fr;
; #pragma unroll
;         for (int n = 0; n < 2; ++n) {
;             const f32x4 w0v = cwv[n][0], w1v = cwv[n][1], w2v = cwv[n][2], bvv = cwv[n][3], w0g = cwv[n][4], w1g = cwv[n][5], w2g = cwv[n][6], bvg = cwv[n][7];
; #pragma unroll
;             for (int ai = 0; ai < 2; ++ai) {
;                 if (n == 0 && ai == 0) {
;                     asm volatile("" ::: "memory");
;                     const float* cv = cw + hc0 + 4; const float* cg = cv + FH; const float* bp = cb + hc0 + 4;
;                     cwv[1][0] = *(const f32x4*)(cv); cwv[1][1] = *(const f32x4*)(cv + F2); cwv[1][2] = *(const f32x4*)(cv + 2 * F2); cwv[1][3] = *(const f32x4*)(bp);
;                     cwv[1][4] = *(const f32x4*)(cg); cwv[1][5] = *(const f32x4*)(cg + F2); cwv[1][6] = *(const f32x4*)(cg + 2 * F2); cwv[1][7] = *(const f32x4*)(bp + FH);
;                     asm volatile("" ::: "memory"); }
;                 f32x4 h2v = (f32x4){0.f, 0.f, 0.f, 0.f}, h3v = h2v, h2g = h2v, h3g = h2v;
;                 const int pb = ai * 2 + wr - 1;
;                 if (pb >= 0 && fr == 0) { const LAS float* xp = xch + (pb * 2) * 256 + clb + 4 * n;
;                     h2v = *(const LAS f32x4*)(xp); h3v = *(const LAS f32x4*)(xp + 256); h2g = *(const LAS f32x4*)(xp + 128); h3g = *(const LAS f32x4*)(xp + 256 + 128); }
;                 float o[4][4];
; #pragma unroll
;                 for (int j = 0; j < 4; ++j) {
;                     const float v0 = acc[ai][0][0][n][j], v1 = acc[ai][0][1][n][j], v2 = acc[ai][0][2][n][j], v3 = acc[ai][0][3][n][j];
;                     const float g0 = acc[ai][1][0][n][j], g1 = acc[ai][1][1][n][j], g2 = acc[ai][1][2][n][j], g3 = acc[ai][1][3][n][j];
;                     const float pv3 = dpp_upd<0x111>(h3v[j], v3), pv2 = dpp_upd<0x111>(h2v[j], v2), pg3 = dpp_upd<0x111>(h3g[j], g3), pg2 = dpp_upd<0x111>(h2g[j], g2);
;                     const float hv0 = bvv[j] + w2v[j] * v0 + w1v[j] * pv3 + w0v[j] * pv2, hv1 = bvv[j] + w2v[j] * v1 + w1v[j] * v0 + w0v[j] * pv3;
;                     const float hv2 = bvv[j] + w2v[j] * v2 + w1v[j] * v1 + w0v[j] * v0, hv3 = bvv[j] + w2v[j] * v3 + w1v[j] * v2 + w0v[j] * v1;
.LBB0_765:
	s_or_b64 exec, exec, s[46:47]
	v_pk_fma_f32 v[248:249], v[152:153], v[184:185], v[188:189]
	v_mov_b32_dpp v206, v128 row_shr:1 row_mask:0xf bank_mask:0xf
	v_mov_b32_dpp v207, v129 row_shr:1 row_mask:0xf bank_mask:0xf
	v_pk_fma_f32 v[248:249], v[180:181], v[198:199], v[248:249]
	v_mov_b32_dpp v194, v148 row_shr:1 row_mask:0xf bank_mask:0xf
	v_pk_fma_f32 v[206:207], v[176:177], v[206:207], v[248:249]
	v_mov_b32_dpp v195, v149 row_shr:1 row_mask:0xf bank_mask:0xf
	v_exp_f32_e32 v248, v206
	v_exp_f32_e32 v249, v207
	v_pk_fma_f32 v[250:251], v[156:157], v[168:169], v[172:173]
	v_pk_add_f32 v[248:249], v[248:249], 1.0 op_sel_hi:[1,0]
	v_rcp_f32_e32 v248, v248
	v_rcp_f32_e32 v249, v249
	v_mov_b32_dpp v202, v136 row_shr:1 row_mask:0xf bank_mask:0xf
	v_mov_b32_dpp v203, v137 row_shr:1 row_mask:0xf bank_mask:0xf
	v_pk_fma_f32 v[250:251], v[164:165], v[194:195], v[250:251]
	v_pk_mul_f32 v[206:207], v[206:207], v[248:249]
	v_pk_fma_f32 v[202:203], v[160:161], v[202:203], v[250:251]
	v_mov_b32_dpp v200, v142 row_shr:1 row_mask:0xf bank_mask:0xf
	v_mov_b32_dpp v201, v143 row_shr:1 row_mask:0xf bank_mask:0xf
	v_pk_mul_f32 v[202:203], v[202:203], v[206:207]
	v_pk_fma_f32 v[206:207], v[154:155], v[186:187], v[190:191]
	v_mov_b32_dpp v208, v130 row_shr:1 row_mask:0xf bank_mask:0xf
	v_mov_b32_dpp v209, v131 row_shr:1 row_mask:0xf bank_mask:0xf
	v_pk_fma_f32 v[206:207], v[182:183], v[200:201], v[206:207]
	v_mov_b32_dpp v196, v150 row_shr:1 row_mask:0xf bank_mask:0xf
	v_pk_fma_f32 v[206:207], v[178:179], v[208:209], v[206:207]
	v_mov_b32_dpp v197, v151 row_shr:1 row_mask:0xf bank_mask:0xf
	v_exp_f32_e32 v193, v206
	v_exp_f32_e32 v209, v207
	v_cvt_pk_bf16_f32 v247, v202, v203
	v_add_f32_e32 v193, 1.0, v193
	v_rcp_f32_e32 v202, v193
	v_add_f32_e32 v193, 1.0, v209
	v_rcp_f32_e32 v203, v193
	v_pk_fma_f32 v[248:249], v[158:159], v[170:171], v[174:175]
	v_mov_b32_dpp v204, v138 row_shr:1 row_mask:0xf bank_mask:0xf
	v_mov_b32_dpp v205, v139 row_shr:1 row_mask:0xf bank_mask:0xf
	v_pk_fma_f32 v[248:249], v[166:167], v[196:197], v[248:249]
	v_pk_mul_f32 v[202:203], v[206:207], v[202:203]
	v_pk_fma_f32 v[204:205], v[162:163], v[204:205], v[248:249]
	v_lshl_add_u32 v246, s40, 8, v236
	v_pk_mul_f32 v[202:203], v[204:205], v[202:203]
	v_lshlrev_b64 v[204:205], 1, v[232:233]
	v_pk_fma_f32 v[232:233], v[132:133], v[184:185], v[188:189]
	v_mov_b64_e32 v[206:207], s[60:61]
	v_pk_fma_f32 v[232:233], v[152:153], v[180:181], v[232:233]
	v_cvt_pk_bf16_f32 v248, v202, v203
	v_pk_fma_f32 v[198:199], v[176:177], v[198:199], v[232:233]
	v_mad_i64_i32 v[202:203], s[40:41], v246, s76, v[206:207]
	v_exp_f32_e32 v193, v198
	v_exp_f32_e32 v232, v199
	v_lshl_add_u64 v[202:203], v[202:203], 0, v[204:205]
	v_add_f32_e32 v193, 1.0, v193
	v_rcp_f32_e32 v208, v193
	v_add_f32_e32 v193, 1.0, v232
	v_rcp_f32_e32 v209, v193
	v_pk_fma_f32 v[232:233], v[144:145], v[168:169], v[172:173]
	v_pk_fma_f32 v[140:141], v[140:141], v[184:185], v[188:189]
	v_pk_fma_f32 v[232:233], v[156:157], v[164:165], v[232:233]
	v_pk_mul_f32 v[198:199], v[198:199], v[208:209]
	v_pk_fma_f32 v[194:195], v[160:161], v[194:195], v[232:233]
	v_pk_fma_f32 v[208:209], v[146:147], v[170:171], v[174:175]
	v_pk_mul_f32 v[194:195], v[194:195], v[198:199]
	v_pk_fma_f32 v[198:199], v[134:135], v[186:187], v[190:191]
	v_pk_fma_f32 v[208:209], v[158:159], v[166:167], v[208:209]
	v_pk_fma_f32 v[198:199], v[154:155], v[182:183], v[198:199]
	v_pk_fma_f32 v[196:197], v[162:163], v[196:197], v[208:209]
	v_pk_fma_f32 v[198:199], v[178:179], v[200:201], v[198:199]
	v_cvt_pk_bf16_f32 v249, v194, v195
	v_exp_f32_e32 v200, v198
	v_exp_f32_e32 v201, v199
	v_pk_fma_f32 v[148:149], v[148:149], v[168:169], v[172:173]
	v_pk_add_f32 v[200:201], v[200:201], 1.0 op_sel_hi:[1,0]
	s_barrier
	v_rcp_f32_e32 v200, v200
	v_rcp_f32_e32 v201, v201
	v_or_b32_e32 v193, 1, v246
	v_pk_mul_f32 v[198:199], v[198:199], v[200:201]
	s_nop 0
	v_pk_mul_f32 v[196:197], v[196:197], v[198:199]
	v_pk_fma_f32 v[198:199], v[128:129], v[184:185], v[188:189]
	v_cvt_pk_bf16_f32 v250, v196, v197
	v_pk_fma_f32 v[198:199], v[132:133], v[180:181], v[198:199]
	v_mad_i64_i32 v[196:197], s[40:41], v193, s76, v[206:207]
	v_pk_fma_f32 v[152:153], v[152:153], v[176:177], v[198:199]
	v_lshl_add_u64 v[196:197], v[196:197], 0, v[204:205]
	v_exp_f32_e32 v193, v152
	v_exp_f32_e32 v198, v153
	v_add_f32_e32 v193, 1.0, v193
	v_rcp_f32_e32 v194, v193
	v_add_f32_e32 v193, 1.0, v198
	v_rcp_f32_e32 v195, v193
	v_pk_fma_f32 v[198:199], v[136:137], v[168:169], v[172:173]
	v_pk_fma_f32 v[128:129], v[128:129], v[180:181], v[140:141]
	v_pk_fma_f32 v[198:199], v[144:145], v[164:165], v[198:199]
	v_pk_fma_f32 v[128:129], v[132:133], v[176:177], v[128:129]
	v_pk_fma_f32 v[156:157], v[156:157], v[160:161], v[198:199]
	v_pk_mul_f32 v[152:153], v[152:153], v[194:195]
	v_pk_mul_f32 v[152:153], v[156:157], v[152:153]
	v_pk_fma_f32 v[156:157], v[130:131], v[186:187], v[190:191]
	v_exp_f32_e32 v140, v128
	v_pk_fma_f32 v[132:133], v[142:143], v[186:187], v[190:191]
	v_pk_fma_f32 v[156:157], v[134:135], v[182:183], v[156:157]
	v_pk_fma_f32 v[130:131], v[130:131], v[182:183], v[132:133]
	v_pk_fma_f32 v[154:155], v[154:155], v[178:179], v[156:157]
	v_pk_fma_f32 v[130:131], v[134:135], v[178:179], v[130:131]
	v_exp_f32_e32 v157, v154
	v_exp_f32_e32 v141, v129
	v_exp_f32_e32 v132, v130
	v_exp_f32_e32 v133, v131
	v_exp_f32_e32 v193, v155
	v_pk_add_f32 v[140:141], v[140:141], 1.0 op_sel_hi:[1,0]
	v_pk_add_f32 v[132:133], v[132:133], 1.0 op_sel_hi:[1,0]
	v_cvt_pk_bf16_f32 v254, v152, v153
	v_add_f32_e32 v152, 1.0, v157
	v_add_f32_e32 v153, 1.0, v193
	v_rcp_f32_e32 v140, v140
	v_rcp_f32_e32 v141, v141
; #define LAS __attribute__((address_space(3)))
; __device__ __forceinline__ float sigmoidf_(float x) { return __builtin_amdgcn_rcpf(1.0f + __expf(-x)); }
;     __device__ __forceinline__ void operator()(AccRef acc, const Unit& u, int wr, int wc, int fr, int fq) const {
;     ...
;                 f32x4 h2v = (f32x4){0.f, 0.f, 0.f, 0.f}, h3v = h2v, h2g = h2v, h3g = h2v;
;                 const int pb = ai * 2 + wr - 1;
;                 if (pb >= 0 && fr == 0) { const LAS float* xp = xch + (pb * 2) * 256 + clb + 4 * n;
;                     h2v = *(const LAS f32x4*)(xp); h3v = *(const LAS f32x4*)(xp + 256); h2g = *(const LAS f32x4*)(xp + 128); h3g = *(const LAS f32x4*)(xp + 256 + 128); }
;                 float o[4][4];
; #pragma unroll
;                 for (int j = 0; j < 4; ++j) {
;                     const float v0 = acc[ai][0][0][n][j], v1 = acc[ai][0][1][n][j], v2 = acc[ai][0][2][n][j], v3 = acc[ai][0][3][n][j];
;                     const float g0 = acc[ai][1][0][n][j], g1 = acc[ai][1][1][n][j], g2 = acc[ai][1][2][n][j], g3 = acc[ai][1][3][n][j];
;                     const float pv3 = dpp_upd<0x111>(h3v[j], v3), pv2 = dpp_upd<0x111>(h2v[j], v2), pg3 = dpp_upd<0x111>(h3g[j], g3), pg2 = dpp_upd<0x111>(h2g[j], g2);
;                     const float hv0 = bvv[j] + w2v[j] * v0 + w1v[j] * pv3 + w0v[j] * pv2, hv1 = bvv[j] + w2v[j] * v1 + w1v[j] * v0 + w0v[j] * pv3;
;                     const float hv2 = bvv[j] + w2v[j] * v2 + w1v[j] * v1 + w0v[j] * v0, hv3 = bvv[j] + w2v[j] * v3 + w1v[j] * v2 + w0v[j] * v1;
;                     const float hg0 = bvg[j] + w2g[j] * g0 + w1g[j] * pg3 + w0g[j] * pg2, hg1 = bvg[j] + w2g[j] * g1 + w1g[j] * g0 + w0g[j] * pg3;
;                     const float hg2 = bvg[j] + w2g[j] * g2 + w1g[j] * g1 + w0g[j] * g0, hg3 = bvg[j] + w2g[j] * g3 + w1g[j] * g2 + w0g[j] * g1;
;                     o[0][j] = hg0 * sigmoidf_(hg0) * hv0; o[1][j] = hg1 * sigmoidf_(hg1) * hv1; o[2][j] = hg2 * sigmoidf_(hg2) * hv2; o[3][j] = hg3 * sigmoidf_(hg3) * hv3; }
; #pragma unroll
;                 for (int m = 0; m < 4; ++m) { u32x2 w; w.x = cvt_pk_bf16(o[m][0], o[m][1]); w.y = cvt_pk_bf16(o[m][2], o[m][3]);
;                     *(u32x2*)(Aout + (size_t)(row0 + ai * 128 + m) * FH + hc0 + 4 * n) = w; } } }
	v_rcp_f32_e32 v132, v132
	v_rcp_f32_e32 v133, v133
	v_rcp_f32_e32 v152, v152
	v_rcp_f32_e32 v153, v153
	v_pk_fma_f32 v[142:143], v[150:151], v[170:171], v[174:175]
	v_pk_fma_f32 v[194:195], v[138:139], v[170:171], v[174:175]
	v_pk_fma_f32 v[136:137], v[136:137], v[164:165], v[148:149]
	v_pk_fma_f32 v[134:135], v[138:139], v[166:167], v[142:143]
	v_pk_fma_f32 v[194:195], v[146:147], v[166:167], v[194:195]
	v_pk_fma_f32 v[136:137], v[144:145], v[160:161], v[136:137]
	v_pk_mul_f32 v[128:129], v[128:129], v[140:141]
	v_pk_fma_f32 v[134:135], v[146:147], v[162:163], v[134:135]
	v_pk_mul_f32 v[130:131], v[130:131], v[132:133]
	v_pk_fma_f32 v[158:159], v[158:159], v[162:163], v[194:195]
	v_pk_mul_f32 v[152:153], v[154:155], v[152:153]
	v_pk_mul_f32 v[128:129], v[136:137], v[128:129]
	v_pk_mul_f32 v[130:131], v[134:135], v[130:131]
	v_pk_mul_f32 v[152:153], v[158:159], v[152:153]
	v_cvt_pk_bf16_f32 v251, v128, v129
	v_cvt_pk_bf16_f32 v253, v130, v131
	v_or_b32_e32 v130, 3, v246
	v_cvt_pk_bf16_f32 v255, v152, v153
	v_or_b32_e32 v152, 2, v246
	v_mad_i64_i32 v[130:131], s[40:41], v130, s76, v[206:207]
	v_mad_i64_i32 v[152:153], s[40:41], v152, s76, v[206:207]
	v_lshl_add_u64 v[140:141], v[130:131], 0, v[204:205]
	v_lshl_add_u64 v[152:153], v[152:153], 0, v[204:205]
	v_mov_b32_e32 v193, 0
	v_mov_b64_e32 v[194:195], 0
	v_mov_b64_e32 v[136:137], 0
	v_mov_b64_e32 v[138:139], 0
	v_mov_b64_e32 v[128:129], 0
	v_mov_b64_e32 v[130:131], 0
	v_mov_b64_e32 v[132:133], 0
	v_mov_b64_e32 v[134:135], 0
	s_barrier
	s_and_saveexec_b64 s[40:41], s[28:29]
	s_cbranch_execz .LBB0_769
	ds_read_b128 v[132:135], v237 offset:2048
	ds_read_b128 v[136:139], v237 offset:2560
	ds_read_b128 v[128:131], v237 offset:3072
	ds_read_b128 v[192:195], v237 offset:3584
.LBB0_769:
	s_or_b64 exec, exec, s[40:41]
	s_waitcnt lgkmcnt(0)
	v_mov_b32_dpp v192, v72 row_shr:1 row_mask:0xf bank_mask:0xf
	v_mov_b32_dpp v193, v73 row_shr:1 row_mask:0xf bank_mask:0xf
	v_pk_fma_f32 v[142:143], v[88:89], v[184:185], v[188:189]
	v_mov_b32_dpp v136, v64 row_shr:1 row_mask:0xf bank_mask:0xf
	v_mov_b32_dpp v137, v65 row_shr:1 row_mask:0xf bank_mask:0xf
	v_pk_fma_f32 v[142:143], v[180:181], v[192:193], v[142:143]
	v_mov_b32_dpp v128, v84 row_shr:1 row_mask:0xf bank_mask:0xf
	v_pk_fma_f32 v[136:137], v[176:177], v[136:137], v[142:143]
	v_mov_b32_dpp v129, v85 row_shr:1 row_mask:0xf bank_mask:0xf
	v_exp_f32_e32 v142, v136
	v_exp_f32_e32 v143, v137
	v_pk_fma_f32 v[144:145], v[92:93], v[168:169], v[172:173]
	v_mov_b32_dpp v132, v76 row_shr:1 row_mask:0xf bank_mask:0xf
	v_pk_add_f32 v[142:143], v[142:143], 1.0 op_sel_hi:[1,0]
	v_rcp_f32_e32 v142, v142
	v_rcp_f32_e32 v143, v143
	v_mov_b32_dpp v133, v77 row_shr:1 row_mask:0xf bank_mask:0xf
	v_pk_fma_f32 v[144:145], v[164:165], v[128:129], v[144:145]
	v_mov_b32_dpp v194, v74 row_shr:1 row_mask:0xf bank_mask:0xf
	v_pk_fma_f32 v[132:133], v[160:161], v[132:133], v[144:145]
	v_pk_mul_f32 v[136:137], v[136:137], v[142:143]
	v_mov_b32_dpp v195, v75 row_shr:1 row_mask:0xf bank_mask:0xf
	v_pk_mul_f32 v[132:133], v[132:133], v[136:137]
	v_pk_fma_f32 v[136:137], v[90:91], v[186:187], v[190:191]
	v_mov_b32_dpp v138, v66 row_shr:1 row_mask:0xf bank_mask:0xf
	v_mov_b32_dpp v139, v67 row_shr:1 row_mask:0xf bank_mask:0xf
	v_pk_fma_f32 v[136:137], v[182:183], v[194:195], v[136:137]
	v_mov_b32_dpp v130, v86 row_shr:1 row_mask:0xf bank_mask:0xf
	v_pk_fma_f32 v[136:137], v[178:179], v[138:139], v[136:137]
	v_mov_b32_dpp v131, v87 row_shr:1 row_mask:0xf bank_mask:0xf
	v_exp_f32_e32 v139, v136
	v_exp_f32_e32 v142, v137
	v_cvt_pk_bf16_f32 v144, v132, v133
	v_add_f32_e32 v132, 1.0, v139
	v_rcp_f32_e32 v132, v132
	v_add_f32_e32 v133, 1.0, v142
	v_rcp_f32_e32 v133, v133
	v_pk_fma_f32 v[142:143], v[94:95], v[170:171], v[174:175]
	v_mov_b32_dpp v134, v78 row_shr:1 row_mask:0xf bank_mask:0xf
	v_mov_b32_dpp v135, v79 row_shr:1 row_mask:0xf bank_mask:0xf
	v_pk_mul_f32 v[132:133], v[136:137], v[132:133]
	v_pk_fma_f32 v[136:137], v[68:69], v[184:185], v[188:189]
	v_pk_fma_f32 v[142:143], v[166:167], v[130:131], v[142:143]
	v_pk_fma_f32 v[136:137], v[88:89], v[180:181], v[136:137]
	v_pk_fma_f32 v[134:135], v[162:163], v[134:135], v[142:143]
	v_pk_fma_f32 v[136:137], v[176:177], v[192:193], v[136:137]
	v_add_u32_e32 v146, 0x80, v246
	v_exp_f32_e32 v142, v136
	v_exp_f32_e32 v143, v137
	v_pk_mul_f32 v[132:133], v[134:135], v[132:133]
	v_mov_b64_e32 v[134:135], s[60:61]
	v_cvt_pk_bf16_f32 v145, v132, v133
	v_mad_i64_i32 v[132:133], s[40:41], v146, s76, v[134:135]
	v_lshl_add_u64 v[132:133], v[132:133], 0, v[204:205]
	v_add_f32_e32 v138, 1.0, v142
	v_add_f32_e32 v139, 1.0, v143
	v_rcp_f32_e32 v138, v138
	v_rcp_f32_e32 v139, v139
	v_pk_fma_f32 v[142:143], v[80:81], v[168:169], v[172:173]
	v_pk_fma_f32 v[72:73], v[72:73], v[184:185], v[188:189]
	v_pk_fma_f32 v[142:143], v[92:93], v[164:165], v[142:143]
	v_pk_mul_f32 v[136:137], v[136:137], v[138:139]
	v_pk_fma_f32 v[128:129], v[160:161], v[128:129], v[142:143]
	v_pk_fma_f32 v[84:85], v[84:85], v[168:169], v[172:173]
	v_pk_mul_f32 v[128:129], v[128:129], v[136:137]
	v_pk_fma_f32 v[136:137], v[70:71], v[186:187], v[190:191]
	s_nop 0
	v_pk_fma_f32 v[136:137], v[90:91], v[182:183], v[136:137]
	s_nop 0
	v_pk_fma_f32 v[136:137], v[178:179], v[194:195], v[136:137]
	s_nop 0
	v_exp_f32_e32 v139, v136
	v_exp_f32_e32 v142, v137
	v_cvt_pk_bf16_f32 v138, v128, v129
	v_add_f32_e32 v128, 1.0, v139
	v_rcp_f32_e32 v128, v128
	v_add_f32_e32 v129, 1.0, v142
	v_rcp_f32_e32 v129, v129
	v_pk_fma_f32 v[142:143], v[82:83], v[170:171], v[174:175]
	v_pk_mul_f32 v[128:129], v[136:137], v[128:129]
	s_barrier
; #define LAS __attribute__((address_space(3)))
; __device__ __forceinline__ float sigmoidf_(float x) { return __builtin_amdgcn_rcpf(1.0f + __expf(-x)); }
;     __device__ __forceinline__ void operator()(AccRef acc, const Unit& u, int wr, int wc, int fr, int fq) const {
;     ...
;                 f32x4 h2v = (f32x4){0.f, 0.f, 0.f, 0.f}, h3v = h2v, h2g = h2v, h3g = h2v;
;                 const int pb = ai * 2 + wr - 1;
;                 if (pb >= 0 && fr == 0) { const LAS float* xp = xch + (pb * 2) * 256 + clb + 4 * n;
;                     h2v = *(const LAS f32x4*)(xp); h3v = *(const LAS f32x4*)(xp + 256); h2g = *(const LAS f32x4*)(xp + 128); h3g = *(const LAS f32x4*)(xp + 256 + 128); }
;                 float o[4][4];
; #pragma unroll
;                 for (int j = 0; j < 4; ++j) {
;                     const float v0 = acc[ai][0][0][n][j], v1 = acc[ai][0][1][n][j], v2 = acc[ai][0][2][n][j], v3 = acc[ai][0][3][n][j];
;                     const float g0 = acc[ai][1][0][n][j], g1 = acc[ai][1][1][n][j], g2 = acc[ai][1][2][n][j], g3 = acc[ai][1][3][n][j];
;                     const float pv3 = dpp_upd<0x111>(h3v[j], v3), pv2 = dpp_upd<0x111>(h2v[j], v2), pg3 = dpp_upd<0x111>(h3g[j], g3), pg2 = dpp_upd<0x111>(h2g[j], g2);
;                     const float hv0 = bvv[j] + w2v[j] * v0 + w1v[j] * pv3 + w0v[j] * pv2, hv1 = bvv[j] + w2v[j] * v1 + w1v[j] * v0 + w0v[j] * pv3;
;                     const float hv2 = bvv[j] + w2v[j] * v2 + w1v[j] * v1 + w0v[j] * v0, hv3 = bvv[j] + w2v[j] * v3 + w1v[j] * v2 + w0v[j] * v1;
;                     const float hg0 = bvg[j] + w2g[j] * g0 + w1g[j] * pg3 + w0g[j] * pg2, hg1 = bvg[j] + w2g[j] * g1 + w1g[j] * g0 + w0g[j] * pg3;
;                     const float hg2 = bvg[j] + w2g[j] * g2 + w1g[j] * g1 + w0g[j] * g0, hg3 = bvg[j] + w2g[j] * g3 + w1g[j] * g2 + w0g[j] * g1;
;                     o[0][j] = hg0 * sigmoidf_(hg0) * hv0; o[1][j] = hg1 * sigmoidf_(hg1) * hv1; o[2][j] = hg2 * sigmoidf_(hg2) * hv2; o[3][j] = hg3 * sigmoidf_(hg3) * hv3; }
; #pragma unroll
;                 for (int m = 0; m < 4; ++m) { u32x2 w; w.x = cvt_pk_bf16(o[m][0], o[m][1]); w.y = cvt_pk_bf16(o[m][2], o[m][3]);
;                     *(u32x2*)(Aout + (size_t)(row0 + ai * 128 + m) * FH + hc0 + 4 * n) = w; } } }
	v_pk_fma_f32 v[142:143], v[94:95], v[166:167], v[142:143]
	v_pk_fma_f32 v[136:137], v[76:77], v[168:169], v[172:173]
	v_pk_fma_f32 v[130:131], v[162:163], v[130:131], v[142:143]
	v_pk_fma_f32 v[136:137], v[80:81], v[164:165], v[136:137]
	v_pk_mul_f32 v[128:129], v[130:131], v[128:129]
	v_pk_fma_f32 v[130:131], v[64:65], v[184:185], v[188:189]
	v_pk_fma_f32 v[64:65], v[64:65], v[180:181], v[72:73]
	v_pk_fma_f32 v[130:131], v[68:69], v[180:181], v[130:131]
	v_pk_fma_f32 v[64:65], v[68:69], v[176:177], v[64:65]
	v_pk_fma_f32 v[88:89], v[88:89], v[176:177], v[130:131]
	v_pk_fma_f32 v[92:93], v[92:93], v[160:161], v[136:137]
	v_exp_f32_e32 v130, v88
	v_exp_f32_e32 v131, v89
	v_exp_f32_e32 v72, v64
	v_pk_add_f32 v[130:131], v[130:131], 1.0 op_sel_hi:[1,0]
	v_rcp_f32_e32 v130, v130
	v_rcp_f32_e32 v131, v131
	v_pk_fma_f32 v[68:69], v[74:75], v[186:187], v[190:191]
	v_exp_f32_e32 v73, v65
	v_pk_mul_f32 v[88:89], v[88:89], v[130:131]
	v_pk_mul_f32 v[88:89], v[92:93], v[88:89]
	v_pk_fma_f32 v[92:93], v[66:67], v[186:187], v[190:191]
	v_pk_fma_f32 v[66:67], v[66:67], v[182:183], v[68:69]
	v_pk_fma_f32 v[92:93], v[70:71], v[182:183], v[92:93]
	v_pk_fma_f32 v[66:67], v[70:71], v[178:179], v[66:67]
	v_pk_fma_f32 v[90:91], v[90:91], v[178:179], v[92:93]
	v_exp_f32_e32 v93, v90
	v_exp_f32_e32 v68, v66
	v_exp_f32_e32 v69, v67
	v_exp_f32_e32 v130, v91
	v_pk_add_f32 v[72:73], v[72:73], 1.0 op_sel_hi:[1,0]
	v_pk_add_f32 v[68:69], v[68:69], 1.0 op_sel_hi:[1,0]
	v_cvt_pk_bf16_f32 v198, v88, v89
	v_add_f32_e32 v88, 1.0, v93
	v_add_f32_e32 v89, 1.0, v130
	v_rcp_f32_e32 v72, v72
	v_rcp_f32_e32 v73, v73
	v_rcp_f32_e32 v68, v68
	v_rcp_f32_e32 v69, v69
	v_rcp_f32_e32 v88, v88
	v_rcp_f32_e32 v89, v89
	v_pk_fma_f32 v[74:75], v[86:87], v[170:171], v[174:175]
	v_pk_fma_f32 v[130:131], v[78:79], v[170:171], v[174:175]
	v_pk_fma_f32 v[76:77], v[76:77], v[164:165], v[84:85]
	v_pk_fma_f32 v[70:71], v[78:79], v[166:167], v[74:75]
	v_pk_fma_f32 v[130:131], v[82:83], v[166:167], v[130:131]
	v_pk_fma_f32 v[76:77], v[80:81], v[160:161], v[76:77]
	v_pk_mul_f32 v[64:65], v[64:65], v[72:73]
	v_pk_fma_f32 v[70:71], v[82:83], v[162:163], v[70:71]
	v_pk_mul_f32 v[66:67], v[66:67], v[68:69]
	v_pk_fma_f32 v[94:95], v[94:95], v[162:163], v[130:131]
	v_pk_mul_f32 v[88:89], v[90:91], v[88:89]
	v_pk_mul_f32 v[64:65], v[76:77], v[64:65]
	v_pk_mul_f32 v[66:67], v[70:71], v[66:67]
	v_pk_mul_f32 v[88:89], v[94:95], v[88:89]
	v_cvt_pk_bf16_f32 v148, v64, v65
	v_cvt_pk_bf16_f32 v149, v66, v67
	v_add_u32_e32 v66, 0x83, v246
	v_cvt_pk_bf16_f32 v155, v128, v129
	v_add_u32_e32 v128, 0x81, v246
	v_cvt_pk_bf16_f32 v199, v88, v89
	v_add_u32_e32 v88, 0x82, v246
	v_mad_i64_i32 v[66:67], s[40:41], v66, s76, v[134:135]
	v_mad_i64_i32 v[128:129], s[40:41], v128, s76, v[134:135]
	v_mad_i64_i32 v[88:89], s[40:41], v88, s76, v[134:135]
	v_lshl_add_u64 v[82:83], v[66:67], 0, v[204:205]
	v_lshl_add_u64 v[128:129], v[128:129], 0, v[204:205]
	v_lshl_add_u64 v[88:89], v[88:89], 0, v[204:205]
	v_mov_b32_e32 v64, 0
	v_mov_b64_e32 v[70:71], 0
	v_mov_b64_e32 v[72:73], 0
	v_mov_b64_e32 v[78:79], 0
	v_mov_b64_e32 v[80:81], 0
	v_mov_b64_e32 v[66:67], 0
	v_mov_b64_e32 v[68:69], 0
	v_mov_b64_e32 v[74:75], 0
	v_mov_b64_e32 v[76:77], 0
	v_mov_b32_e32 v154, v138
	s_barrier
	s_and_saveexec_b64 s[40:41], s[26:27]
	s_cbranch_execz .LBB0_771
	ds_read_b128 v[74:77], v242
	ds_read_b128 v[66:69], v241
	ds_read_b128 v[78:81], v240
	ds_read_b128 v[70:73], v239
;     __device__ __forceinline__ void operator()(AccRef acc, const Unit& u, int wr, int wc, int fr, int fq) const {
;     ...
;         for (int n = 0; n < 2; ++n) {
;             const f32x4 w0v = cwv[n][0], w1v = cwv[n][1], w2v = cwv[n][2], bvv = cwv[n][3], w0g = cwv[n][4], w1g = cwv[n][5], w2g = cwv[n][6], bvg = cwv[n][7];
; #pragma unroll
;             for (int ai = 0; ai < 2; ++ai) {
;                 if (n == 0 && ai == 0) {
;                     asm volatile("" ::: "memory");
;                     const float* cv = cw + hc0 + 4; const float* cg = cv + FH; const float* bp = cb + hc0 + 4;
;                     cwv[1][0] = *(const f32x4*)(cv); cwv[1][1] = *(const f32x4*)(cv + F2); cwv[1][2] = *(const f32x4*)(cv + 2 * F2); cwv[1][3] = *(const f32x4*)(bp);
;                     cwv[1][4] = *(const f32x4*)(cg); cwv[1][5] = *(const f32x4*)(cg + F2); cwv[1][6] = *(const f32x4*)(cg + 2 * F2); cwv[1][7] = *(const f32x4*)(bp + FH);
;                     asm volatile("" ::: "memory"); }
;                 f32x4 h2v = (f32x4){0.f, 0.f, 0.f, 0.f}, h3v = h2v, h2g = h2v, h3g = h2v;
;                 const int pb = ai * 2 + wr - 1;
;                 if (pb >= 0 && fr == 0) { const LAS float* xp = xch + (pb * 2) * 256 + clb + 4 * n;
;                     h2v = *(const LAS f32x4*)(xp); h3v = *(const LAS f32x4*)(xp + 256); h2g = *(const LAS f32x4*)(xp + 128); h3g = *(const LAS f32x4*)(xp + 256 + 128); }
;                 float o[4][4];
; #pragma unroll
;                 for (int j = 0; j < 4; ++j) {
;                     const float v0 = acc[ai][0][0][n][j], v1 = acc[ai][0][1][n][j], v2 = acc[ai][0][2][n][j], v3 = acc[ai][0][3][n][j];
;                     const float g0 = acc[ai][1][0][n][j], g1 = acc[ai][1][1][n][j], g2 = acc[ai][1][2][n][j], g3 = acc[ai][1][3][n][j];
;                     const float pv3 = dpp_upd<0x111>(h3v[j], v3), pv2 = dpp_upd<0x111>(h2v[j], v2), pg3 = dpp_upd<0x111>(h3g[j], g3), pg2 = dpp_upd<0x111>(h2g[j], g2);
;                     const float hv0 = bvv[j] + w2v[j] * v0 + w1v[j] * pv3 + w0v[j] * pv2, hv1 = bvv[j] + w2v[j] * v1 + w1v[j] * v0 + w0v[j] * pv3;
;                     const float hv2 = bvv[j] + w2v[j] * v2 + w1v[j] * v1 + w0v[j] * v0, hv3 = bvv[j] + w2v[j] * v3 + w1v[j] * v2 + w0v[j] * v1;
;                     const float hg0 = bvg[j] + w2g[j] * g0 + w1g[j] * pg3 + w0g[j] * pg2, hg1 = bvg[j] + w2g[j] * g1 + w1g[j] * g0 + w0g[j] * pg3;
.LBB0_771:
	s_or_b64 exec, exec, s[40:41]
	s_waitcnt lgkmcnt(0)
	v_mov_b32_dpp v70, v44 row_shr:1 row_mask:0xf bank_mask:0xf
	v_mov_b32_dpp v71, v45 row_shr:1 row_mask:0xf bank_mask:0xf
	s_waitcnt vmcnt(0)
	v_pk_fma_f32 v[84:85], v[56:57], v[120:121], v[124:125]
	v_mov_b32_dpp v78, v32 row_shr:1 row_mask:0xf bank_mask:0xf
	v_mov_b32_dpp v79, v33 row_shr:1 row_mask:0xf bank_mask:0xf
	v_pk_fma_f32 v[84:85], v[116:117], v[70:71], v[84:85]
	v_mov_b32_dpp v66, v52 row_shr:1 row_mask:0xf bank_mask:0xf
	v_pk_fma_f32 v[78:79], v[112:113], v[78:79], v[84:85]
	v_mov_b32_dpp v67, v53 row_shr:1 row_mask:0xf bank_mask:0xf
	v_exp_f32_e32 v84, v78
	v_exp_f32_e32 v85, v79
	v_pk_fma_f32 v[86:87], v[60:61], v[104:105], v[108:109]
	v_pk_add_f32 v[84:85], v[84:85], 1.0 op_sel_hi:[1,0]
	v_rcp_f32_e32 v84, v84
	v_rcp_f32_e32 v85, v85
	v_mov_b32_dpp v74, v40 row_shr:1 row_mask:0xf bank_mask:0xf
	v_mov_b32_dpp v75, v41 row_shr:1 row_mask:0xf bank_mask:0xf
	v_pk_fma_f32 v[86:87], v[100:101], v[66:67], v[86:87]
	v_pk_mul_f32 v[78:79], v[78:79], v[84:85]
	v_pk_fma_f32 v[74:75], v[96:97], v[74:75], v[86:87]
	v_mov_b32_dpp v72, v46 row_shr:1 row_mask:0xf bank_mask:0xf
	v_mov_b32_dpp v73, v47 row_shr:1 row_mask:0xf bank_mask:0xf
	v_pk_mul_f32 v[74:75], v[74:75], v[78:79]
	v_pk_fma_f32 v[78:79], v[58:59], v[122:123], v[126:127]
	v_mov_b32_dpp v80, v34 row_shr:1 row_mask:0xf bank_mask:0xf
	v_mov_b32_dpp v81, v35 row_shr:1 row_mask:0xf bank_mask:0xf
	v_pk_fma_f32 v[78:79], v[118:119], v[72:73], v[78:79]
	v_mov_b32_dpp v68, v54 row_shr:1 row_mask:0xf bank_mask:0xf
	v_pk_fma_f32 v[78:79], v[114:115], v[80:81], v[78:79]
	v_mov_b32_dpp v69, v55 row_shr:1 row_mask:0xf bank_mask:0xf
	v_exp_f32_e32 v80, v78
	v_exp_f32_e32 v81, v79
	v_pk_fma_f32 v[84:85], v[62:63], v[106:107], v[110:111]
	v_pk_add_f32 v[80:81], v[80:81], 1.0 op_sel_hi:[1,0]
	v_rcp_f32_e32 v80, v80
	v_rcp_f32_e32 v81, v81
	v_mov_b32_dpp v76, v42 row_shr:1 row_mask:0xf bank_mask:0xf
	v_mov_b32_dpp v77, v43 row_shr:1 row_mask:0xf bank_mask:0xf
	v_pk_fma_f32 v[84:85], v[102:103], v[68:69], v[84:85]
	v_pk_mul_f32 v[78:79], v[78:79], v[80:81]
	v_pk_fma_f32 v[76:77], v[98:99], v[76:77], v[84:85]
	v_cvt_pk_bf16_f32 v92, v74, v75
	v_pk_mul_f32 v[76:77], v[76:77], v[78:79]
	v_pk_fma_f32 v[44:45], v[44:45], v[120:121], v[124:125]
	v_cvt_pk_bf16_f32 v93, v76, v77
	v_pk_fma_f32 v[76:77], v[36:37], v[120:121], v[124:125]
	v_mov_b32_e32 v90, v247
	v_mov_b32_e32 v91, v248
	global_store_dwordx4 v[202:203], v[90:93], off
	v_pk_fma_f32 v[76:77], v[56:57], v[116:117], v[76:77]
	v_pk_fma_f32 v[52:53], v[52:53], v[104:105], v[108:109]
	v_pk_fma_f32 v[70:71], v[112:113], v[70:71], v[76:77]
	s_nop 0
	v_exp_f32_e32 v74, v70
	v_exp_f32_e32 v75, v71
	s_nop 0
	v_pk_add_f32 v[74:75], v[74:75], 1.0 op_sel_hi:[1,0]
	v_rcp_f32_e32 v74, v74
	v_rcp_f32_e32 v75, v75
	v_pk_fma_f32 v[76:77], v[48:49], v[104:105], v[108:109]
	v_pk_mul_f32 v[70:71], v[70:71], v[74:75]
	v_pk_fma_f32 v[76:77], v[60:61], v[100:101], v[76:77]
	v_pk_fma_f32 v[74:75], v[50:51], v[106:107], v[110:111]
	v_pk_fma_f32 v[66:67], v[96:97], v[66:67], v[76:77]
	v_pk_fma_f32 v[74:75], v[62:63], v[102:103], v[74:75]
	v_pk_mul_f32 v[66:67], v[66:67], v[70:71]
	v_pk_fma_f32 v[70:71], v[38:39], v[122:123], v[126:127]
	v_pk_fma_f32 v[68:69], v[98:99], v[68:69], v[74:75]
	v_pk_fma_f32 v[70:71], v[58:59], v[118:119], v[70:71]
	v_cvt_pk_bf16_f32 v136, v66, v67
	v_pk_fma_f32 v[70:71], v[114:115], v[72:73], v[70:71]
	s_nop 0
	v_exp_f32_e32 v72, v70
	v_exp_f32_e32 v73, v71
	s_nop 0
	v_pk_add_f32 v[72:73], v[72:73], 1.0 op_sel_hi:[1,0]
	v_rcp_f32_e32 v72, v72
	s_barrier
	v_rcp_f32_e32 v73, v73
	s_nop 0
	v_pk_mul_f32 v[70:71], v[70:71], v[72:73]
	s_nop 0
	v_pk_mul_f32 v[68:69], v[68:69], v[70:71]
	s_nop 0
	v_cvt_pk_bf16_f32 v137, v68, v69
	v_pk_fma_f32 v[68:69], v[32:33], v[120:121], v[124:125]
	v_mov_b32_e32 v134, v249
	v_mov_b32_e32 v135, v250
	global_store_dwordx4 v[196:197], v[134:137], off
	v_pk_fma_f32 v[68:69], v[36:37], v[116:117], v[68:69]
	v_pk_fma_f32 v[32:33], v[32:33], v[116:117], v[44:45]
	v_pk_fma_f32 v[56:57], v[56:57], v[112:113], v[68:69]
	v_pk_fma_f32 v[32:33], v[36:37], v[112:113], v[32:33]
	v_exp_f32_e32 v66, v56
	v_exp_f32_e32 v67, v57
	s_nop 0
	v_pk_add_f32 v[66:67], v[66:67], 1.0 op_sel_hi:[1,0]
	v_rcp_f32_e32 v66, v66
	v_rcp_f32_e32 v67, v67
	v_pk_fma_f32 v[68:69], v[40:41], v[104:105], v[108:109]
	v_exp_f32_e32 v44, v32
	v_pk_fma_f32 v[68:69], v[48:49], v[100:101], v[68:69]
	v_pk_mul_f32 v[56:57], v[56:57], v[66:67]
	v_pk_fma_f32 v[60:61], v[60:61], v[96:97], v[68:69]
	v_pk_fma_f32 v[36:37], v[46:47], v[122:123], v[126:127]
	v_pk_mul_f32 v[56:57], v[60:61], v[56:57]
	v_pk_fma_f32 v[60:61], v[34:35], v[122:123], v[126:127]
	v_pk_fma_f32 v[34:35], v[34:35], v[118:119], v[36:37]
	v_pk_fma_f32 v[60:61], v[38:39], v[118:119], v[60:61]
	v_pk_fma_f32 v[34:35], v[38:39], v[114:115], v[34:35]
	v_pk_fma_f32 v[58:59], v[58:59], v[114:115], v[60:61]
	v_exp_f32_e32 v60, v58
	v_exp_f32_e32 v45, v33
	v_exp_f32_e32 v36, v34
	v_exp_f32_e32 v37, v35
	v_exp_f32_e32 v61, v59
	v_cvt_pk_bf16_f32 v164, v56, v57
	v_pk_add_f32 v[44:45], v[44:45], 1.0 op_sel_hi:[1,0]
	v_pk_add_f32 v[36:37], v[36:37], 1.0 op_sel_hi:[1,0]
	v_pk_add_f32 v[60:61], v[60:61], 1.0 op_sel_hi:[1,0]
	v_rcp_f32_e32 v44, v44
	v_rcp_f32_e32 v45, v45
	v_rcp_f32_e32 v36, v36
	v_rcp_f32_e32 v37, v37
	v_rcp_f32_e32 v60, v60
	v_rcp_f32_e32 v61, v61
	v_pk_fma_f32 v[46:47], v[54:55], v[106:107], v[110:111]
	v_pk_fma_f32 v[66:67], v[42:43], v[106:107], v[110:111]
	v_pk_fma_f32 v[40:41], v[40:41], v[100:101], v[52:53]
	v_pk_fma_f32 v[38:39], v[42:43], v[102:103], v[46:47]
	v_pk_fma_f32 v[66:67], v[50:51], v[102:103], v[66:67]
	v_pk_fma_f32 v[40:41], v[48:49], v[96:97], v[40:41]
	v_pk_mul_f32 v[32:33], v[32:33], v[44:45]
	v_pk_fma_f32 v[38:39], v[50:51], v[98:99], v[38:39]
	v_pk_mul_f32 v[34:35], v[34:35], v[36:37]
	v_pk_fma_f32 v[62:63], v[62:63], v[98:99], v[66:67]
	v_pk_mul_f32 v[58:59], v[58:59], v[60:61]
	v_pk_mul_f32 v[32:33], v[40:41], v[32:33]
	v_pk_mul_f32 v[34:35], v[38:39], v[34:35]
	v_pk_mul_f32 v[58:59], v[62:63], v[58:59]
	v_cvt_pk_bf16_f32 v160, v32, v33
	v_cvt_pk_bf16_f32 v161, v34, v35
	v_cvt_pk_bf16_f32 v57, v58, v59
	v_mov_b32_e32 v158, v251
	v_mov_b32_e32 v159, v253
	global_store_dwordx4 v[140:141], v[158:161], off
	v_mov_b32_e32 v65, 0
	v_mov_b64_e32 v[66:67], 0
	v_mov_b64_e32 v[40:41], 0
	v_mov_b64_e32 v[42:43], 0
	v_mov_b64_e32 v[32:33], 0
	v_mov_b64_e32 v[34:35], 0
	v_mov_b64_e32 v[36:37], 0
	v_mov_b64_e32 v[38:39], 0
	v_mov_b32_e32 v162, v254
	v_mov_b32_e32 v163, v255
	v_mov_b32_e32 v165, v57
	global_store_dwordx4 v[152:153], v[162:165], off
	s_barrier
	s_and_saveexec_b64 s[40:41], s[28:29]
	s_cbranch_execz .LBB0_754
	ds_read_b128 v[36:39], v237 offset:2064
	ds_read_b128 v[40:43], v237 offset:2576
	ds_read_b128 v[32:35], v237 offset:3088
	ds_read_b128 v[64:67], v237 offset:3600
	s_branch .LBB0_754

; #define LAS __attribute__((address_space(3)))
; __device__ __forceinline__ float sigmoidf_(float x) { return __builtin_amdgcn_rcpf(1.0f + __expf(-x)); }
;     __device__ __forceinline__ void operator()(AccRef acc, const Unit& u, int wr, int wc, int fr, int fq) const {
;     ...
;                 f32x4 h2v = (f32x4){0.f, 0.f, 0.f, 0.f}, h3v = h2v, h2g = h2v, h3g = h2v;
;                 const int pb = ai * 2 + wr - 1;
;                 if (pb >= 0 && fr == 0) { const LAS float* xp = xch + (pb * 2) * 256 + clb + 4 * n;
;                     h2v = *(const LAS f32x4*)(xp); h3v = *(const LAS f32x4*)(xp + 256); h2g = *(const LAS f32x4*)(xp + 128); h3g = *(const LAS f32x4*)(xp + 256 + 128); }
;                 float o[4][4];
; #pragma unroll
;                 for (int j = 0; j < 4; ++j) {
;                     const float v0 = acc[ai][0][0][n][j], v1 = acc[ai][0][1][n][j], v2 = acc[ai][0][2][n][j], v3 = acc[ai][0][3][n][j];
;                     const float g0 = acc[ai][1][0][n][j], g1 = acc[ai][1][1][n][j], g2 = acc[ai][1][2][n][j], g3 = acc[ai][1][3][n][j];
;                     const float pv3 = dpp_upd<0x111>(h3v[j], v3), pv2 = dpp_upd<0x111>(h2v[j], v2), pg3 = dpp_upd<0x111>(h3g[j], g3), pg2 = dpp_upd<0x111>(h2g[j], g2);
;                     const float hv0 = bvv[j] + w2v[j] * v0 + w1v[j] * pv3 + w0v[j] * pv2, hv1 = bvv[j] + w2v[j] * v1 + w1v[j] * v0 + w0v[j] * pv3;
;                     const float hv2 = bvv[j] + w2v[j] * v2 + w1v[j] * v1 + w0v[j] * v0, hv3 = bvv[j] + w2v[j] * v3 + w1v[j] * v2 + w0v[j] * v1;
;                     const float hg0 = bvg[j] + w2g[j] * g0 + w1g[j] * pg3 + w0g[j] * pg2, hg1 = bvg[j] + w2g[j] * g1 + w1g[j] * g0 + w0g[j] * pg3;
;                     const float hg2 = bvg[j] + w2g[j] * g2 + w1g[j] * g1 + w0g[j] * g0, hg3 = bvg[j] + w2g[j] * g3 + w1g[j] * g2 + w0g[j] * g1;
;                     o[0][j] = hg0 * sigmoidf_(hg0) * hv0; o[1][j] = hg1 * sigmoidf_(hg1) * hv1; o[2][j] = hg2 * sigmoidf_(hg2) * hv2; o[3][j] = hg3 * sigmoidf_(hg3) * hv3; }
; #pragma unroll
;                 for (int m = 0; m < 4; ++m) { u32x2 w; w.x = cvt_pk_bf16(o[m][0], o[m][1]); w.y = cvt_pk_bf16(o[m][2], o[m][3]);
;                     *(u32x2*)(Aout + (size_t)(row0 + ai * 128 + m) * FH + hc0 + 4 * n) = w; } } }
.LBB0_1355:
	s_or_b64 exec, exec, s[42:43]
	s_waitcnt lgkmcnt(0)
	v_mov_b32_dpp v64, v8 row_shr:1 row_mask:0xf bank_mask:0xf
	v_mov_b32_dpp v65, v9 row_shr:1 row_mask:0xf bank_mask:0xf
	v_pk_fma_f32 v[44:45], v[24:25], v[120:121], v[124:125]
	v_mov_b32_dpp v40, v0 row_shr:1 row_mask:0xf bank_mask:0xf
	v_mov_b32_dpp v41, v1 row_shr:1 row_mask:0xf bank_mask:0xf
	v_pk_fma_f32 v[44:45], v[116:117], v[64:65], v[44:45]
	v_mov_b32_dpp v32, v20 row_shr:1 row_mask:0xf bank_mask:0xf
	v_pk_fma_f32 v[40:41], v[112:113], v[40:41], v[44:45]
	v_mov_b32_dpp v33, v21 row_shr:1 row_mask:0xf bank_mask:0xf
	v_exp_f32_e32 v44, v40
	v_exp_f32_e32 v45, v41
	v_pk_fma_f32 v[46:47], v[28:29], v[104:105], v[108:109]
	v_mov_b32_dpp v36, v12 row_shr:1 row_mask:0xf bank_mask:0xf
	v_pk_add_f32 v[44:45], v[44:45], 1.0 op_sel_hi:[1,0]
	v_rcp_f32_e32 v44, v44
	v_rcp_f32_e32 v45, v45
	v_mov_b32_dpp v37, v13 row_shr:1 row_mask:0xf bank_mask:0xf
	v_pk_fma_f32 v[46:47], v[100:101], v[32:33], v[46:47]
	v_mov_b32_dpp v66, v10 row_shr:1 row_mask:0xf bank_mask:0xf
	v_pk_fma_f32 v[36:37], v[96:97], v[36:37], v[46:47]
	v_pk_mul_f32 v[40:41], v[40:41], v[44:45]
	v_mov_b32_dpp v67, v11 row_shr:1 row_mask:0xf bank_mask:0xf
	v_pk_mul_f32 v[36:37], v[36:37], v[40:41]
	v_pk_fma_f32 v[40:41], v[26:27], v[122:123], v[126:127]
	v_mov_b32_dpp v42, v2 row_shr:1 row_mask:0xf bank_mask:0xf
	v_mov_b32_dpp v43, v3 row_shr:1 row_mask:0xf bank_mask:0xf
	v_pk_fma_f32 v[40:41], v[118:119], v[66:67], v[40:41]
	v_cvt_pk_bf16_f32 v146, v36, v37
	v_pk_fma_f32 v[40:41], v[114:115], v[42:43], v[40:41]
	v_mov_b32_dpp v34, v22 row_shr:1 row_mask:0xf bank_mask:0xf
	v_exp_f32_e32 v42, v40
	v_exp_f32_e32 v43, v41
	v_mov_b32_dpp v35, v23 row_shr:1 row_mask:0xf bank_mask:0xf
	v_pk_add_f32 v[42:43], v[42:43], 1.0 op_sel_hi:[1,0]
	v_rcp_f32_e32 v42, v42
	v_rcp_f32_e32 v43, v43
	v_pk_fma_f32 v[44:45], v[30:31], v[106:107], v[110:111]
	v_mov_b32_dpp v38, v14 row_shr:1 row_mask:0xf bank_mask:0xf
	v_mov_b32_dpp v39, v15 row_shr:1 row_mask:0xf bank_mask:0xf
	v_pk_fma_f32 v[44:45], v[102:103], v[34:35], v[44:45]
	v_pk_mul_f32 v[40:41], v[40:41], v[42:43]
	v_pk_fma_f32 v[38:39], v[98:99], v[38:39], v[44:45]
	v_pk_fma_f32 v[8:9], v[8:9], v[120:121], v[124:125]
	v_pk_mul_f32 v[38:39], v[38:39], v[40:41]
	v_pk_fma_f32 v[20:21], v[20:21], v[104:105], v[108:109]
	v_cvt_pk_bf16_f32 v147, v38, v39
	v_pk_fma_f32 v[38:39], v[4:5], v[120:121], v[124:125]
	global_store_dwordx4 v[132:133], v[144:147], off
	v_pk_fma_f32 v[38:39], v[24:25], v[116:117], v[38:39]
	s_and_b64 vcc, exec, s[14:15]
	v_pk_fma_f32 v[38:39], v[112:113], v[64:65], v[38:39]
	s_mov_b32 s43, s34
	v_exp_f32_e32 v36, v38
	v_exp_f32_e32 v37, v39
	s_mov_b32 s42, s36
	s_mov_b64 s[46:47], s[40:41]
	v_pk_add_f32 v[36:37], v[36:37], 1.0 op_sel_hi:[1,0]
	v_rcp_f32_e32 v36, v36
	v_rcp_f32_e32 v37, v37
	v_pk_fma_f32 v[40:41], v[16:17], v[104:105], v[108:109]
	s_mov_b64 s[44:45], s[38:39]
	v_pk_fma_f32 v[40:41], v[28:29], v[100:101], v[40:41]
	v_pk_mul_f32 v[36:37], v[38:39], v[36:37]
	v_pk_fma_f32 v[32:33], v[96:97], v[32:33], v[40:41]
	v_pk_fma_f32 v[40:41], v[18:19], v[106:107], v[110:111]
	v_pk_mul_f32 v[32:33], v[32:33], v[36:37]
	v_pk_fma_f32 v[36:37], v[6:7], v[122:123], v[126:127]
	v_cvt_pk_bf16_f32 v156, v32, v33
	v_pk_fma_f32 v[36:37], v[26:27], v[118:119], v[36:37]
	v_pk_fma_f32 v[40:41], v[30:31], v[102:103], v[40:41]
	s_barrier
	v_pk_fma_f32 v[36:37], v[114:115], v[66:67], v[36:37]
	v_pk_fma_f32 v[34:35], v[98:99], v[34:35], v[40:41]
	v_exp_f32_e32 v38, v36
	v_exp_f32_e32 v39, v37
	s_nop 0
	v_pk_add_f32 v[38:39], v[38:39], 1.0 op_sel_hi:[1,0]
	v_rcp_f32_e32 v38, v38
	v_rcp_f32_e32 v39, v39
	s_nop 0
	v_pk_mul_f32 v[36:37], v[36:37], v[38:39]
	s_nop 0
	v_pk_mul_f32 v[34:35], v[34:35], v[36:37]
	s_nop 0
	v_cvt_pk_bf16_f32 v157, v34, v35
	v_pk_fma_f32 v[34:35], v[0:1], v[120:121], v[124:125]
	global_store_dwordx4 v[128:129], v[154:157], off
	v_pk_fma_f32 v[34:35], v[4:5], v[116:117], v[34:35]
	v_pk_fma_f32 v[0:1], v[0:1], v[116:117], v[8:9]
	v_pk_fma_f32 v[24:25], v[24:25], v[112:113], v[34:35]
	v_pk_fma_f32 v[0:1], v[4:5], v[112:113], v[0:1]
	v_exp_f32_e32 v32, v24
	v_exp_f32_e32 v33, v25
	v_exp_f32_e32 v8, v0
	v_pk_add_f32 v[32:33], v[32:33], 1.0 op_sel_hi:[1,0]
	v_rcp_f32_e32 v32, v32
	v_rcp_f32_e32 v33, v33
	v_pk_fma_f32 v[34:35], v[12:13], v[104:105], v[108:109]
	v_pk_fma_f32 v[4:5], v[10:11], v[122:123], v[126:127]
	v_pk_fma_f32 v[34:35], v[16:17], v[100:101], v[34:35]
	v_pk_mul_f32 v[24:25], v[24:25], v[32:33]
	v_pk_fma_f32 v[28:29], v[28:29], v[96:97], v[34:35]
	v_pk_mul_f32 v[24:25], v[28:29], v[24:25]
	v_pk_fma_f32 v[28:29], v[2:3], v[122:123], v[126:127]
	v_pk_fma_f32 v[2:3], v[2:3], v[118:119], v[4:5]
	v_pk_fma_f32 v[28:29], v[6:7], v[118:119], v[28:29]
	v_pk_fma_f32 v[2:3], v[6:7], v[114:115], v[2:3]
	v_pk_fma_f32 v[26:27], v[26:27], v[114:115], v[28:29]
	v_exp_f32_e32 v28, v26
	v_exp_f32_e32 v29, v27
	v_exp_f32_e32 v9, v1
	v_exp_f32_e32 v4, v2
	v_exp_f32_e32 v5, v3
	v_cvt_pk_bf16_f32 v200, v24, v25
	v_pk_add_f32 v[28:29], v[28:29], 1.0 op_sel_hi:[1,0]
	v_pk_add_f32 v[8:9], v[8:9], 1.0 op_sel_hi:[1,0]
	v_pk_add_f32 v[4:5], v[4:5], 1.0 op_sel_hi:[1,0]
	v_rcp_f32_e32 v28, v28
	v_rcp_f32_e32 v29, v29
	v_rcp_f32_e32 v8, v8
	v_rcp_f32_e32 v9, v9
	v_rcp_f32_e32 v4, v4
	v_rcp_f32_e32 v5, v5
	v_pk_fma_f32 v[32:33], v[14:15], v[106:107], v[110:111]
	v_pk_fma_f32 v[10:11], v[22:23], v[106:107], v[110:111]
	v_pk_fma_f32 v[32:33], v[18:19], v[102:103], v[32:33]
	v_pk_fma_f32 v[12:13], v[12:13], v[100:101], v[20:21]
	v_pk_fma_f32 v[6:7], v[14:15], v[102:103], v[10:11]
	v_pk_fma_f32 v[30:31], v[30:31], v[98:99], v[32:33]
	v_pk_mul_f32 v[26:27], v[26:27], v[28:29]
	v_pk_fma_f32 v[12:13], v[16:17], v[96:97], v[12:13]
	v_pk_mul_f32 v[0:1], v[0:1], v[8:9]
	v_pk_fma_f32 v[6:7], v[18:19], v[98:99], v[6:7]
	v_pk_mul_f32 v[2:3], v[2:3], v[4:5]
	v_pk_mul_f32 v[26:27], v[30:31], v[26:27]
	v_pk_mul_f32 v[0:1], v[12:13], v[0:1]
	v_pk_mul_f32 v[2:3], v[6:7], v[2:3]
	v_cvt_pk_bf16_f32 v201, v26, v27
	v_cvt_pk_bf16_f32 v150, v0, v1
	v_cvt_pk_bf16_f32 v151, v2, v3
	global_store_dwordx4 v[88:89], v[198:201], off
	global_store_dwordx4 v[82:83], v[148:151], off
	s_cbranch_vccnz .LBB0_1374

; #define LAS __attribute__((address_space(3)))
;     __device__ __forceinline__ void operator()(AccRef acc, const Unit& u, int wr, int wc, int fr, int fq) const {
;     ...
;         const int hc0 = 128 * u.pn + clb, row0 = u.pm * 256 + wr * 64 + 4 * fr;
; #pragma unroll
;         for (int n = 0; n < 2; ++n) {
;             const f32x4 w0v = cwv[n][0], w1v = cwv[n][1], w2v = cwv[n][2], bvv = cwv[n][3], w0g = cwv[n][4], w1g = cwv[n][5], w2g = cwv[n][6], bvg = cwv[n][7];
; #pragma unroll
;             for (int ai = 0; ai < 2; ++ai) {
;                 if (n == 0 && ai == 0) {
;                     asm volatile("" ::: "memory");
;                     const float* cv = cw + hc0 + 4; const float* cg = cv + FH; const float* bp = cb + hc0 + 4;
;                     cwv[1][0] = *(const f32x4*)(cv); cwv[1][1] = *(const f32x4*)(cv + F2); cwv[1][2] = *(const f32x4*)(cv + 2 * F2); cwv[1][3] = *(const f32x4*)(bp);
;                     cwv[1][4] = *(const f32x4*)(cg); cwv[1][5] = *(const f32x4*)(cg + F2); cwv[1][6] = *(const f32x4*)(cg + 2 * F2); cwv[1][7] = *(const f32x4*)(bp + FH);
;                     asm volatile("" ::: "memory"); }
;                 f32x4 h2v = (f32x4){0.f, 0.f, 0.f, 0.f}, h3v = h2v, h2g = h2v, h3g = h2v;
;                 const int pb = ai * 2 + wr - 1;
;                 if (pb >= 0 && fr == 0) { const LAS float* xp = xch + (pb * 2) * 256 + clb + 4 * n;
;                     h2v = *(const LAS f32x4*)(xp); h3v = *(const LAS f32x4*)(xp + 256); h2g = *(const LAS f32x4*)(xp + 128); h3g = *(const LAS f32x4*)(xp + 256 + 128); }
;                 float o[4][4];
; #pragma unroll
;                 for (int j = 0; j < 4; ++j) {
;                     const float v0 = acc[ai][0][0][n][j], v1 = acc[ai][0][1][n][j], v2 = acc[ai][0][2][n][j], v3 = acc[ai][0][3][n][j];
;                     const float g0 = acc[ai][1][0][n][j], g1 = acc[ai][1][1][n][j], g2 = acc[ai][1][2][n][j], g3 = acc[ai][1][3][n][j];
;                     const float pv3 = dpp_upd<0x111>(h3v[j], v3), pv2 = dpp_upd<0x111>(h2v[j], v2), pg3 = dpp_upd<0x111>(h3g[j], g3), pg2 = dpp_upd<0x111>(h2g[j], g2);
;                     const float hv0 = bvv[j] + w2v[j] * v0 + w1v[j] * pv3 + w0v[j] * pv2, hv1 = bvv[j] + w2v[j] * v1 + w1v[j] * v0 + w0v[j] * pv3;
;                     const float hv2 = bvv[j] + w2v[j] * v2 + w1v[j] * v1 + w0v[j] * v0, hv3 = bvv[j] + w2v[j] * v3 + w1v[j] * v2 + w0v[j] * v1;
.LBB0_1366:
	s_or_b64 exec, exec, s[48:49]
	v_pk_fma_f32 v[248:249], v[152:153], v[184:185], v[188:189]
	v_mov_b32_dpp v206, v128 row_shr:1 row_mask:0xf bank_mask:0xf
	v_mov_b32_dpp v207, v129 row_shr:1 row_mask:0xf bank_mask:0xf
	v_pk_fma_f32 v[248:249], v[180:181], v[198:199], v[248:249]
	v_mov_b32_dpp v194, v148 row_shr:1 row_mask:0xf bank_mask:0xf
	v_pk_fma_f32 v[206:207], v[176:177], v[206:207], v[248:249]
	v_mov_b32_dpp v195, v149 row_shr:1 row_mask:0xf bank_mask:0xf
	v_exp_f32_e32 v248, v206
	v_exp_f32_e32 v249, v207
	v_pk_fma_f32 v[250:251], v[156:157], v[168:169], v[172:173]
	v_pk_add_f32 v[248:249], v[248:249], 1.0 op_sel_hi:[1,0]
	v_rcp_f32_e32 v248, v248
	v_rcp_f32_e32 v249, v249
	v_mov_b32_dpp v202, v136 row_shr:1 row_mask:0xf bank_mask:0xf
	v_mov_b32_dpp v203, v137 row_shr:1 row_mask:0xf bank_mask:0xf
	v_pk_fma_f32 v[250:251], v[164:165], v[194:195], v[250:251]
	v_pk_mul_f32 v[206:207], v[206:207], v[248:249]
	v_pk_fma_f32 v[202:203], v[160:161], v[202:203], v[250:251]
	v_mov_b32_dpp v200, v142 row_shr:1 row_mask:0xf bank_mask:0xf
	v_mov_b32_dpp v201, v143 row_shr:1 row_mask:0xf bank_mask:0xf
	v_pk_mul_f32 v[202:203], v[202:203], v[206:207]
	v_pk_fma_f32 v[206:207], v[154:155], v[186:187], v[190:191]
	v_mov_b32_dpp v208, v130 row_shr:1 row_mask:0xf bank_mask:0xf
	v_mov_b32_dpp v209, v131 row_shr:1 row_mask:0xf bank_mask:0xf
	v_pk_fma_f32 v[206:207], v[182:183], v[200:201], v[206:207]
	v_mov_b32_dpp v196, v150 row_shr:1 row_mask:0xf bank_mask:0xf
	v_pk_fma_f32 v[206:207], v[178:179], v[208:209], v[206:207]
	v_mov_b32_dpp v197, v151 row_shr:1 row_mask:0xf bank_mask:0xf
	v_exp_f32_e32 v193, v206
	v_exp_f32_e32 v209, v207
	v_cvt_pk_bf16_f32 v247, v202, v203
	v_add_f32_e32 v193, 1.0, v193
	v_rcp_f32_e32 v202, v193
	v_add_f32_e32 v193, 1.0, v209
	v_rcp_f32_e32 v203, v193
	v_pk_fma_f32 v[248:249], v[158:159], v[170:171], v[174:175]
	v_mov_b32_dpp v204, v138 row_shr:1 row_mask:0xf bank_mask:0xf
	v_mov_b32_dpp v205, v139 row_shr:1 row_mask:0xf bank_mask:0xf
	v_pk_fma_f32 v[248:249], v[166:167], v[196:197], v[248:249]
	v_pk_mul_f32 v[202:203], v[206:207], v[202:203]
	v_pk_fma_f32 v[204:205], v[162:163], v[204:205], v[248:249]
	v_lshl_add_u32 v246, s42, 8, v236
	v_pk_mul_f32 v[202:203], v[204:205], v[202:203]
	v_lshlrev_b64 v[204:205], 1, v[232:233]
	v_pk_fma_f32 v[232:233], v[132:133], v[184:185], v[188:189]
	v_mov_b64_e32 v[206:207], s[60:61]
	v_pk_fma_f32 v[232:233], v[152:153], v[180:181], v[232:233]
	v_cvt_pk_bf16_f32 v248, v202, v203
	v_pk_fma_f32 v[198:199], v[176:177], v[198:199], v[232:233]
	v_mad_i64_i32 v[202:203], s[42:43], v246, s82, v[206:207]
	v_exp_f32_e32 v193, v198
	v_exp_f32_e32 v232, v199
	v_lshl_add_u64 v[202:203], v[202:203], 0, v[204:205]
	v_add_f32_e32 v193, 1.0, v193
	v_rcp_f32_e32 v208, v193
	v_add_f32_e32 v193, 1.0, v232
	v_rcp_f32_e32 v209, v193
	v_pk_fma_f32 v[232:233], v[144:145], v[168:169], v[172:173]
	v_pk_fma_f32 v[140:141], v[140:141], v[184:185], v[188:189]
	v_pk_fma_f32 v[232:233], v[156:157], v[164:165], v[232:233]
	v_pk_mul_f32 v[198:199], v[198:199], v[208:209]
	v_pk_fma_f32 v[194:195], v[160:161], v[194:195], v[232:233]
	v_pk_fma_f32 v[208:209], v[146:147], v[170:171], v[174:175]
	v_pk_mul_f32 v[194:195], v[194:195], v[198:199]
	v_pk_fma_f32 v[198:199], v[134:135], v[186:187], v[190:191]
	v_pk_fma_f32 v[208:209], v[158:159], v[166:167], v[208:209]
	v_pk_fma_f32 v[198:199], v[154:155], v[182:183], v[198:199]
	v_pk_fma_f32 v[196:197], v[162:163], v[196:197], v[208:209]
	v_pk_fma_f32 v[198:199], v[178:179], v[200:201], v[198:199]
	v_cvt_pk_bf16_f32 v249, v194, v195
	v_exp_f32_e32 v200, v198
	v_exp_f32_e32 v201, v199
	v_pk_fma_f32 v[148:149], v[148:149], v[168:169], v[172:173]
	v_pk_add_f32 v[200:201], v[200:201], 1.0 op_sel_hi:[1,0]
	s_barrier
	v_rcp_f32_e32 v200, v200
	v_rcp_f32_e32 v201, v201
	v_or_b32_e32 v193, 1, v246
	v_pk_mul_f32 v[198:199], v[198:199], v[200:201]
	s_nop 0
	v_pk_mul_f32 v[196:197], v[196:197], v[198:199]
	v_pk_fma_f32 v[198:199], v[128:129], v[184:185], v[188:189]
	v_cvt_pk_bf16_f32 v250, v196, v197
	v_pk_fma_f32 v[198:199], v[132:133], v[180:181], v[198:199]
	v_mad_i64_i32 v[196:197], s[42:43], v193, s82, v[206:207]
	v_pk_fma_f32 v[152:153], v[152:153], v[176:177], v[198:199]
	v_lshl_add_u64 v[196:197], v[196:197], 0, v[204:205]
	v_exp_f32_e32 v193, v152
	v_exp_f32_e32 v198, v153
	v_add_f32_e32 v193, 1.0, v193
	v_rcp_f32_e32 v194, v193
	v_add_f32_e32 v193, 1.0, v198
	v_rcp_f32_e32 v195, v193
	v_pk_fma_f32 v[198:199], v[136:137], v[168:169], v[172:173]
	v_pk_fma_f32 v[128:129], v[128:129], v[180:181], v[140:141]
	v_pk_fma_f32 v[198:199], v[144:145], v[164:165], v[198:199]
	v_pk_fma_f32 v[128:129], v[132:133], v[176:177], v[128:129]
	v_pk_fma_f32 v[156:157], v[156:157], v[160:161], v[198:199]
	v_pk_mul_f32 v[152:153], v[152:153], v[194:195]
	v_pk_mul_f32 v[152:153], v[156:157], v[152:153]
	v_pk_fma_f32 v[156:157], v[130:131], v[186:187], v[190:191]
	v_exp_f32_e32 v140, v128
	v_pk_fma_f32 v[132:133], v[142:143], v[186:187], v[190:191]
	v_pk_fma_f32 v[156:157], v[134:135], v[182:183], v[156:157]
	v_pk_fma_f32 v[130:131], v[130:131], v[182:183], v[132:133]
	v_pk_fma_f32 v[154:155], v[154:155], v[178:179], v[156:157]
	v_pk_fma_f32 v[130:131], v[134:135], v[178:179], v[130:131]
	v_exp_f32_e32 v157, v154
	v_exp_f32_e32 v141, v129
	v_exp_f32_e32 v132, v130
	v_exp_f32_e32 v133, v131
	v_exp_f32_e32 v193, v155
	v_pk_add_f32 v[140:141], v[140:141], 1.0 op_sel_hi:[1,0]
	v_pk_add_f32 v[132:133], v[132:133], 1.0 op_sel_hi:[1,0]
	v_cvt_pk_bf16_f32 v254, v152, v153
	v_add_f32_e32 v152, 1.0, v157
	v_add_f32_e32 v153, 1.0, v193
	v_rcp_f32_e32 v140, v140
	v_rcp_f32_e32 v141, v141
; #define LAS __attribute__((address_space(3)))
; __device__ __forceinline__ float sigmoidf_(float x) { return __builtin_amdgcn_rcpf(1.0f + __expf(-x)); }
;     __device__ __forceinline__ void operator()(AccRef acc, const Unit& u, int wr, int wc, int fr, int fq) const {
;     ...
;                 f32x4 h2v = (f32x4){0.f, 0.f, 0.f, 0.f}, h3v = h2v, h2g = h2v, h3g = h2v;
;                 const int pb = ai * 2 + wr - 1;
;                 if (pb >= 0 && fr == 0) { const LAS float* xp = xch + (pb * 2) * 256 + clb + 4 * n;
;                     h2v = *(const LAS f32x4*)(xp); h3v = *(const LAS f32x4*)(xp + 256); h2g = *(const LAS f32x4*)(xp + 128); h3g = *(const LAS f32x4*)(xp + 256 + 128); }
;                 float o[4][4];
; #pragma unroll
;                 for (int j = 0; j < 4; ++j) {
;                     const float v0 = acc[ai][0][0][n][j], v1 = acc[ai][0][1][n][j], v2 = acc[ai][0][2][n][j], v3 = acc[ai][0][3][n][j];
;                     const float g0 = acc[ai][1][0][n][j], g1 = acc[ai][1][1][n][j], g2 = acc[ai][1][2][n][j], g3 = acc[ai][1][3][n][j];
;                     const float pv3 = dpp_upd<0x111>(h3v[j], v3), pv2 = dpp_upd<0x111>(h2v[j], v2), pg3 = dpp_upd<0x111>(h3g[j], g3), pg2 = dpp_upd<0x111>(h2g[j], g2);
;                     const float hv0 = bvv[j] + w2v[j] * v0 + w1v[j] * pv3 + w0v[j] * pv2, hv1 = bvv[j] + w2v[j] * v1 + w1v[j] * v0 + w0v[j] * pv3;
;                     const float hv2 = bvv[j] + w2v[j] * v2 + w1v[j] * v1 + w0v[j] * v0, hv3 = bvv[j] + w2v[j] * v3 + w1v[j] * v2 + w0v[j] * v1;
;                     const float hg0 = bvg[j] + w2g[j] * g0 + w1g[j] * pg3 + w0g[j] * pg2, hg1 = bvg[j] + w2g[j] * g1 + w1g[j] * g0 + w0g[j] * pg3;
;                     const float hg2 = bvg[j] + w2g[j] * g2 + w1g[j] * g1 + w0g[j] * g0, hg3 = bvg[j] + w2g[j] * g3 + w1g[j] * g2 + w0g[j] * g1;
;                     o[0][j] = hg0 * sigmoidf_(hg0) * hv0; o[1][j] = hg1 * sigmoidf_(hg1) * hv1; o[2][j] = hg2 * sigmoidf_(hg2) * hv2; o[3][j] = hg3 * sigmoidf_(hg3) * hv3; }
; #pragma unroll
;                 for (int m = 0; m < 4; ++m) { u32x2 w; w.x = cvt_pk_bf16(o[m][0], o[m][1]); w.y = cvt_pk_bf16(o[m][2], o[m][3]);
;                     *(u32x2*)(Aout + (size_t)(row0 + ai * 128 + m) * FH + hc0 + 4 * n) = w; } } }
	v_rcp_f32_e32 v132, v132
	v_rcp_f32_e32 v133, v133
	v_rcp_f32_e32 v152, v152
	v_rcp_f32_e32 v153, v153
	v_pk_fma_f32 v[142:143], v[150:151], v[170:171], v[174:175]
	v_pk_fma_f32 v[194:195], v[138:139], v[170:171], v[174:175]
	v_pk_fma_f32 v[136:137], v[136:137], v[164:165], v[148:149]
	v_pk_fma_f32 v[134:135], v[138:139], v[166:167], v[142:143]
	v_pk_fma_f32 v[194:195], v[146:147], v[166:167], v[194:195]
	v_pk_fma_f32 v[136:137], v[144:145], v[160:161], v[136:137]
	v_pk_mul_f32 v[128:129], v[128:129], v[140:141]
	v_pk_fma_f32 v[134:135], v[146:147], v[162:163], v[134:135]
	v_pk_mul_f32 v[130:131], v[130:131], v[132:133]
	v_pk_fma_f32 v[158:159], v[158:159], v[162:163], v[194:195]
	v_pk_mul_f32 v[152:153], v[154:155], v[152:153]
	v_pk_mul_f32 v[128:129], v[136:137], v[128:129]
	v_pk_mul_f32 v[130:131], v[134:135], v[130:131]
	v_pk_mul_f32 v[152:153], v[158:159], v[152:153]
	v_cvt_pk_bf16_f32 v251, v128, v129
	v_cvt_pk_bf16_f32 v253, v130, v131
	v_or_b32_e32 v130, 3, v246
	v_cvt_pk_bf16_f32 v255, v152, v153
	v_or_b32_e32 v152, 2, v246
	v_mad_i64_i32 v[130:131], s[42:43], v130, s82, v[206:207]
	v_mad_i64_i32 v[152:153], s[42:43], v152, s82, v[206:207]
	v_lshl_add_u64 v[140:141], v[130:131], 0, v[204:205]
	v_lshl_add_u64 v[152:153], v[152:153], 0, v[204:205]
	v_mov_b32_e32 v193, 0
	v_mov_b64_e32 v[194:195], 0
	v_mov_b64_e32 v[136:137], 0
	v_mov_b64_e32 v[138:139], 0
	v_mov_b64_e32 v[128:129], 0
	v_mov_b64_e32 v[130:131], 0
	v_mov_b64_e32 v[132:133], 0
	v_mov_b64_e32 v[134:135], 0
	s_barrier
	s_and_saveexec_b64 s[42:43], s[30:31]
	s_cbranch_execz .LBB0_1370
	ds_read_b128 v[132:135], v237 offset:2048
	ds_read_b128 v[136:139], v237 offset:2560
	ds_read_b128 v[128:131], v237 offset:3072
	ds_read_b128 v[192:195], v237 offset:3584
.LBB0_1370:
	s_or_b64 exec, exec, s[42:43]
	s_waitcnt lgkmcnt(0)
	v_mov_b32_dpp v192, v72 row_shr:1 row_mask:0xf bank_mask:0xf
	v_mov_b32_dpp v193, v73 row_shr:1 row_mask:0xf bank_mask:0xf
	v_pk_fma_f32 v[142:143], v[88:89], v[184:185], v[188:189]
	v_mov_b32_dpp v136, v64 row_shr:1 row_mask:0xf bank_mask:0xf
	v_mov_b32_dpp v137, v65 row_shr:1 row_mask:0xf bank_mask:0xf
	v_pk_fma_f32 v[142:143], v[180:181], v[192:193], v[142:143]
	v_mov_b32_dpp v128, v84 row_shr:1 row_mask:0xf bank_mask:0xf
	v_pk_fma_f32 v[136:137], v[176:177], v[136:137], v[142:143]
	v_mov_b32_dpp v129, v85 row_shr:1 row_mask:0xf bank_mask:0xf
	v_exp_f32_e32 v142, v136
	v_exp_f32_e32 v143, v137
	v_pk_fma_f32 v[144:145], v[92:93], v[168:169], v[172:173]
	v_mov_b32_dpp v132, v76 row_shr:1 row_mask:0xf bank_mask:0xf
	v_pk_add_f32 v[142:143], v[142:143], 1.0 op_sel_hi:[1,0]
	v_rcp_f32_e32 v142, v142
	v_rcp_f32_e32 v143, v143
	v_mov_b32_dpp v133, v77 row_shr:1 row_mask:0xf bank_mask:0xf
	v_pk_fma_f32 v[144:145], v[164:165], v[128:129], v[144:145]
	v_mov_b32_dpp v194, v74 row_shr:1 row_mask:0xf bank_mask:0xf
	v_pk_fma_f32 v[132:133], v[160:161], v[132:133], v[144:145]
	v_pk_mul_f32 v[136:137], v[136:137], v[142:143]
	v_mov_b32_dpp v195, v75 row_shr:1 row_mask:0xf bank_mask:0xf
	v_pk_mul_f32 v[132:133], v[132:133], v[136:137]
	v_pk_fma_f32 v[136:137], v[90:91], v[186:187], v[190:191]
	v_mov_b32_dpp v138, v66 row_shr:1 row_mask:0xf bank_mask:0xf
	v_mov_b32_dpp v139, v67 row_shr:1 row_mask:0xf bank_mask:0xf
	v_pk_fma_f32 v[136:137], v[182:183], v[194:195], v[136:137]
	v_mov_b32_dpp v130, v86 row_shr:1 row_mask:0xf bank_mask:0xf
	v_pk_fma_f32 v[136:137], v[178:179], v[138:139], v[136:137]
	v_mov_b32_dpp v131, v87 row_shr:1 row_mask:0xf bank_mask:0xf
	v_exp_f32_e32 v139, v136
	v_exp_f32_e32 v142, v137
	v_cvt_pk_bf16_f32 v144, v132, v133
	v_add_f32_e32 v132, 1.0, v139
	v_rcp_f32_e32 v132, v132
	v_add_f32_e32 v133, 1.0, v142
	v_rcp_f32_e32 v133, v133
	v_pk_fma_f32 v[142:143], v[94:95], v[170:171], v[174:175]
	v_mov_b32_dpp v134, v78 row_shr:1 row_mask:0xf bank_mask:0xf
	v_mov_b32_dpp v135, v79 row_shr:1 row_mask:0xf bank_mask:0xf
	v_pk_mul_f32 v[132:133], v[136:137], v[132:133]
	v_pk_fma_f32 v[136:137], v[68:69], v[184:185], v[188:189]
	v_pk_fma_f32 v[142:143], v[166:167], v[130:131], v[142:143]
	v_pk_fma_f32 v[136:137], v[88:89], v[180:181], v[136:137]
	v_pk_fma_f32 v[134:135], v[162:163], v[134:135], v[142:143]
	v_pk_fma_f32 v[136:137], v[176:177], v[192:193], v[136:137]
	v_add_u32_e32 v146, 0x80, v246
	v_exp_f32_e32 v142, v136
	v_exp_f32_e32 v143, v137
	v_pk_mul_f32 v[132:133], v[134:135], v[132:133]
	v_mov_b64_e32 v[134:135], s[60:61]
	v_cvt_pk_bf16_f32 v145, v132, v133
	v_mad_i64_i32 v[132:133], s[42:43], v146, s82, v[134:135]
	v_lshl_add_u64 v[132:133], v[132:133], 0, v[204:205]
	v_add_f32_e32 v138, 1.0, v142
	v_add_f32_e32 v139, 1.0, v143
	v_rcp_f32_e32 v138, v138
	v_rcp_f32_e32 v139, v139
	v_pk_fma_f32 v[142:143], v[80:81], v[168:169], v[172:173]
	v_pk_fma_f32 v[72:73], v[72:73], v[184:185], v[188:189]
	v_pk_fma_f32 v[142:143], v[92:93], v[164:165], v[142:143]
	v_pk_mul_f32 v[136:137], v[136:137], v[138:139]
	v_pk_fma_f32 v[128:129], v[160:161], v[128:129], v[142:143]
	v_pk_fma_f32 v[84:85], v[84:85], v[168:169], v[172:173]
	v_pk_mul_f32 v[128:129], v[128:129], v[136:137]
	v_pk_fma_f32 v[136:137], v[70:71], v[186:187], v[190:191]
	s_nop 0
	v_pk_fma_f32 v[136:137], v[90:91], v[182:183], v[136:137]
	s_nop 0
	v_pk_fma_f32 v[136:137], v[178:179], v[194:195], v[136:137]
	s_nop 0
	v_exp_f32_e32 v139, v136
	v_exp_f32_e32 v142, v137
	v_cvt_pk_bf16_f32 v138, v128, v129
	v_add_f32_e32 v128, 1.0, v139
	v_rcp_f32_e32 v128, v128
	v_add_f32_e32 v129, 1.0, v142
	v_rcp_f32_e32 v129, v129
	v_pk_fma_f32 v[142:143], v[82:83], v[170:171], v[174:175]
	v_pk_mul_f32 v[128:129], v[136:137], v[128:129]
	s_barrier
; #define LAS __attribute__((address_space(3)))
; __device__ __forceinline__ float sigmoidf_(float x) { return __builtin_amdgcn_rcpf(1.0f + __expf(-x)); }
;     __device__ __forceinline__ void operator()(AccRef acc, const Unit& u, int wr, int wc, int fr, int fq) const {
;     ...
;                 f32x4 h2v = (f32x4){0.f, 0.f, 0.f, 0.f}, h3v = h2v, h2g = h2v, h3g = h2v;
;                 const int pb = ai * 2 + wr - 1;
;                 if (pb >= 0 && fr == 0) { const LAS float* xp = xch + (pb * 2) * 256 + clb + 4 * n;
;                     h2v = *(const LAS f32x4*)(xp); h3v = *(const LAS f32x4*)(xp + 256); h2g = *(const LAS f32x4*)(xp + 128); h3g = *(const LAS f32x4*)(xp + 256 + 128); }
;                 float o[4][4];
; #pragma unroll
;                 for (int j = 0; j < 4; ++j) {
;                     const float v0 = acc[ai][0][0][n][j], v1 = acc[ai][0][1][n][j], v2 = acc[ai][0][2][n][j], v3 = acc[ai][0][3][n][j];
;                     const float g0 = acc[ai][1][0][n][j], g1 = acc[ai][1][1][n][j], g2 = acc[ai][1][2][n][j], g3 = acc[ai][1][3][n][j];
;                     const float pv3 = dpp_upd<0x111>(h3v[j], v3), pv2 = dpp_upd<0x111>(h2v[j], v2), pg3 = dpp_upd<0x111>(h3g[j], g3), pg2 = dpp_upd<0x111>(h2g[j], g2);
;                     const float hv0 = bvv[j] + w2v[j] * v0 + w1v[j] * pv3 + w0v[j] * pv2, hv1 = bvv[j] + w2v[j] * v1 + w1v[j] * v0 + w0v[j] * pv3;
;                     const float hv2 = bvv[j] + w2v[j] * v2 + w1v[j] * v1 + w0v[j] * v0, hv3 = bvv[j] + w2v[j] * v3 + w1v[j] * v2 + w0v[j] * v1;
;                     const float hg0 = bvg[j] + w2g[j] * g0 + w1g[j] * pg3 + w0g[j] * pg2, hg1 = bvg[j] + w2g[j] * g1 + w1g[j] * g0 + w0g[j] * pg3;
;                     const float hg2 = bvg[j] + w2g[j] * g2 + w1g[j] * g1 + w0g[j] * g0, hg3 = bvg[j] + w2g[j] * g3 + w1g[j] * g2 + w0g[j] * g1;
;                     o[0][j] = hg0 * sigmoidf_(hg0) * hv0; o[1][j] = hg1 * sigmoidf_(hg1) * hv1; o[2][j] = hg2 * sigmoidf_(hg2) * hv2; o[3][j] = hg3 * sigmoidf_(hg3) * hv3; }
; #pragma unroll
;                 for (int m = 0; m < 4; ++m) { u32x2 w; w.x = cvt_pk_bf16(o[m][0], o[m][1]); w.y = cvt_pk_bf16(o[m][2], o[m][3]);
;                     *(u32x2*)(Aout + (size_t)(row0 + ai * 128 + m) * FH + hc0 + 4 * n) = w; } } }
	v_pk_fma_f32 v[142:143], v[94:95], v[166:167], v[142:143]
	v_pk_fma_f32 v[136:137], v[76:77], v[168:169], v[172:173]
	v_pk_fma_f32 v[130:131], v[162:163], v[130:131], v[142:143]
	v_pk_fma_f32 v[136:137], v[80:81], v[164:165], v[136:137]
	v_pk_mul_f32 v[128:129], v[130:131], v[128:129]
	v_pk_fma_f32 v[130:131], v[64:65], v[184:185], v[188:189]
	v_pk_fma_f32 v[64:65], v[64:65], v[180:181], v[72:73]
	v_pk_fma_f32 v[130:131], v[68:69], v[180:181], v[130:131]
	v_pk_fma_f32 v[64:65], v[68:69], v[176:177], v[64:65]
	v_pk_fma_f32 v[88:89], v[88:89], v[176:177], v[130:131]
	v_pk_fma_f32 v[92:93], v[92:93], v[160:161], v[136:137]
	v_exp_f32_e32 v130, v88
	v_exp_f32_e32 v131, v89
	v_exp_f32_e32 v72, v64
	v_pk_add_f32 v[130:131], v[130:131], 1.0 op_sel_hi:[1,0]
	v_rcp_f32_e32 v130, v130
	v_rcp_f32_e32 v131, v131
	v_pk_fma_f32 v[68:69], v[74:75], v[186:187], v[190:191]
	v_exp_f32_e32 v73, v65
	v_pk_mul_f32 v[88:89], v[88:89], v[130:131]
	v_pk_mul_f32 v[88:89], v[92:93], v[88:89]
	v_pk_fma_f32 v[92:93], v[66:67], v[186:187], v[190:191]
	v_pk_fma_f32 v[66:67], v[66:67], v[182:183], v[68:69]
	v_pk_fma_f32 v[92:93], v[70:71], v[182:183], v[92:93]
	v_pk_fma_f32 v[66:67], v[70:71], v[178:179], v[66:67]
	v_pk_fma_f32 v[90:91], v[90:91], v[178:179], v[92:93]
	v_exp_f32_e32 v93, v90
	v_exp_f32_e32 v68, v66
	v_exp_f32_e32 v69, v67
	v_exp_f32_e32 v130, v91
	v_pk_add_f32 v[72:73], v[72:73], 1.0 op_sel_hi:[1,0]
	v_pk_add_f32 v[68:69], v[68:69], 1.0 op_sel_hi:[1,0]
	v_cvt_pk_bf16_f32 v198, v88, v89
	v_add_f32_e32 v88, 1.0, v93
	v_add_f32_e32 v89, 1.0, v130
	v_rcp_f32_e32 v72, v72
	v_rcp_f32_e32 v73, v73
	v_rcp_f32_e32 v68, v68
	v_rcp_f32_e32 v69, v69
	v_rcp_f32_e32 v88, v88
	v_rcp_f32_e32 v89, v89
	v_pk_fma_f32 v[74:75], v[86:87], v[170:171], v[174:175]
	v_pk_fma_f32 v[130:131], v[78:79], v[170:171], v[174:175]
	v_pk_fma_f32 v[76:77], v[76:77], v[164:165], v[84:85]
	v_pk_fma_f32 v[70:71], v[78:79], v[166:167], v[74:75]
	v_pk_fma_f32 v[130:131], v[82:83], v[166:167], v[130:131]
	v_pk_fma_f32 v[76:77], v[80:81], v[160:161], v[76:77]
	v_pk_mul_f32 v[64:65], v[64:65], v[72:73]
	v_pk_fma_f32 v[70:71], v[82:83], v[162:163], v[70:71]
	v_pk_mul_f32 v[66:67], v[66:67], v[68:69]
	v_pk_fma_f32 v[94:95], v[94:95], v[162:163], v[130:131]
	v_pk_mul_f32 v[88:89], v[90:91], v[88:89]
	v_pk_mul_f32 v[64:65], v[76:77], v[64:65]
	v_pk_mul_f32 v[66:67], v[70:71], v[66:67]
	v_pk_mul_f32 v[88:89], v[94:95], v[88:89]
	v_cvt_pk_bf16_f32 v148, v64, v65
	v_cvt_pk_bf16_f32 v149, v66, v67
	v_add_u32_e32 v66, 0x83, v246
	v_cvt_pk_bf16_f32 v155, v128, v129
	v_add_u32_e32 v128, 0x81, v246
	v_cvt_pk_bf16_f32 v199, v88, v89
	v_add_u32_e32 v88, 0x82, v246
	v_mad_i64_i32 v[66:67], s[42:43], v66, s82, v[134:135]
	v_mad_i64_i32 v[128:129], s[42:43], v128, s82, v[134:135]
	v_mad_i64_i32 v[88:89], s[42:43], v88, s82, v[134:135]
	v_lshl_add_u64 v[82:83], v[66:67], 0, v[204:205]
	v_lshl_add_u64 v[128:129], v[128:129], 0, v[204:205]
	v_lshl_add_u64 v[88:89], v[88:89], 0, v[204:205]
	v_mov_b32_e32 v64, 0
	v_mov_b64_e32 v[70:71], 0
	v_mov_b64_e32 v[72:73], 0
	v_mov_b64_e32 v[78:79], 0
	v_mov_b64_e32 v[80:81], 0
	v_mov_b64_e32 v[66:67], 0
	v_mov_b64_e32 v[68:69], 0
	v_mov_b64_e32 v[74:75], 0
	v_mov_b64_e32 v[76:77], 0
	v_mov_b32_e32 v154, v138
	s_barrier
	s_and_saveexec_b64 s[42:43], s[28:29]
	s_cbranch_execz .LBB0_1372
	ds_read_b128 v[74:77], v242
	ds_read_b128 v[66:69], v241
	ds_read_b128 v[78:81], v240
	ds_read_b128 v[70:73], v239
;     __device__ __forceinline__ void operator()(AccRef acc, const Unit& u, int wr, int wc, int fr, int fq) const {
;     ...
;         for (int n = 0; n < 2; ++n) {
;             const f32x4 w0v = cwv[n][0], w1v = cwv[n][1], w2v = cwv[n][2], bvv = cwv[n][3], w0g = cwv[n][4], w1g = cwv[n][5], w2g = cwv[n][6], bvg = cwv[n][7];
; #pragma unroll
;             for (int ai = 0; ai < 2; ++ai) {
;                 if (n == 0 && ai == 0) {
;                     asm volatile("" ::: "memory");
;                     const float* cv = cw + hc0 + 4; const float* cg = cv + FH; const float* bp = cb + hc0 + 4;
;                     cwv[1][0] = *(const f32x4*)(cv); cwv[1][1] = *(const f32x4*)(cv + F2); cwv[1][2] = *(const f32x4*)(cv + 2 * F2); cwv[1][3] = *(const f32x4*)(bp);
;                     cwv[1][4] = *(const f32x4*)(cg); cwv[1][5] = *(const f32x4*)(cg + F2); cwv[1][6] = *(const f32x4*)(cg + 2 * F2); cwv[1][7] = *(const f32x4*)(bp + FH);
;                     asm volatile("" ::: "memory"); }
;                 f32x4 h2v = (f32x4){0.f, 0.f, 0.f, 0.f}, h3v = h2v, h2g = h2v, h3g = h2v;
;                 const int pb = ai * 2 + wr - 1;
;                 if (pb >= 0 && fr == 0) { const LAS float* xp = xch + (pb * 2) * 256 + clb + 4 * n;
;                     h2v = *(const LAS f32x4*)(xp); h3v = *(const LAS f32x4*)(xp + 256); h2g = *(const LAS f32x4*)(xp + 128); h3g = *(const LAS f32x4*)(xp + 256 + 128); }
;                 float o[4][4];
; #pragma unroll
;                 for (int j = 0; j < 4; ++j) {
;                     const float v0 = acc[ai][0][0][n][j], v1 = acc[ai][0][1][n][j], v2 = acc[ai][0][2][n][j], v3 = acc[ai][0][3][n][j];
;                     const float g0 = acc[ai][1][0][n][j], g1 = acc[ai][1][1][n][j], g2 = acc[ai][1][2][n][j], g3 = acc[ai][1][3][n][j];
;                     const float pv3 = dpp_upd<0x111>(h3v[j], v3), pv2 = dpp_upd<0x111>(h2v[j], v2), pg3 = dpp_upd<0x111>(h3g[j], g3), pg2 = dpp_upd<0x111>(h2g[j], g2);
;                     const float hv0 = bvv[j] + w2v[j] * v0 + w1v[j] * pv3 + w0v[j] * pv2, hv1 = bvv[j] + w2v[j] * v1 + w1v[j] * v0 + w0v[j] * pv3;
;                     const float hv2 = bvv[j] + w2v[j] * v2 + w1v[j] * v1 + w0v[j] * v0, hv3 = bvv[j] + w2v[j] * v3 + w1v[j] * v2 + w0v[j] * v1;
;                     const float hg0 = bvg[j] + w2g[j] * g0 + w1g[j] * pg3 + w0g[j] * pg2, hg1 = bvg[j] + w2g[j] * g1 + w1g[j] * g0 + w0g[j] * pg3;
.LBB0_1372:
	s_or_b64 exec, exec, s[42:43]
	s_waitcnt lgkmcnt(0)
	v_mov_b32_dpp v70, v44 row_shr:1 row_mask:0xf bank_mask:0xf
	v_mov_b32_dpp v71, v45 row_shr:1 row_mask:0xf bank_mask:0xf
	s_waitcnt vmcnt(0)
	v_pk_fma_f32 v[84:85], v[56:57], v[120:121], v[124:125]
	v_mov_b32_dpp v78, v32 row_shr:1 row_mask:0xf bank_mask:0xf
	v_mov_b32_dpp v79, v33 row_shr:1 row_mask:0xf bank_mask:0xf
	v_pk_fma_f32 v[84:85], v[116:117], v[70:71], v[84:85]
	v_mov_b32_dpp v66, v52 row_shr:1 row_mask:0xf bank_mask:0xf
	v_pk_fma_f32 v[78:79], v[112:113], v[78:79], v[84:85]
	v_mov_b32_dpp v67, v53 row_shr:1 row_mask:0xf bank_mask:0xf
	v_exp_f32_e32 v84, v78
	v_exp_f32_e32 v85, v79
	v_pk_fma_f32 v[86:87], v[60:61], v[104:105], v[108:109]
	v_pk_add_f32 v[84:85], v[84:85], 1.0 op_sel_hi:[1,0]
	v_rcp_f32_e32 v84, v84
	v_rcp_f32_e32 v85, v85
	v_mov_b32_dpp v74, v40 row_shr:1 row_mask:0xf bank_mask:0xf
	v_mov_b32_dpp v75, v41 row_shr:1 row_mask:0xf bank_mask:0xf
	v_pk_fma_f32 v[86:87], v[100:101], v[66:67], v[86:87]
	v_pk_mul_f32 v[78:79], v[78:79], v[84:85]
	v_pk_fma_f32 v[74:75], v[96:97], v[74:75], v[86:87]
	v_mov_b32_dpp v72, v46 row_shr:1 row_mask:0xf bank_mask:0xf
	v_mov_b32_dpp v73, v47 row_shr:1 row_mask:0xf bank_mask:0xf
	v_pk_mul_f32 v[74:75], v[74:75], v[78:79]
	v_pk_fma_f32 v[78:79], v[58:59], v[122:123], v[126:127]
	v_mov_b32_dpp v80, v34 row_shr:1 row_mask:0xf bank_mask:0xf
	v_mov_b32_dpp v81, v35 row_shr:1 row_mask:0xf bank_mask:0xf
	v_pk_fma_f32 v[78:79], v[118:119], v[72:73], v[78:79]
	v_mov_b32_dpp v68, v54 row_shr:1 row_mask:0xf bank_mask:0xf
	v_pk_fma_f32 v[78:79], v[114:115], v[80:81], v[78:79]
	v_mov_b32_dpp v69, v55 row_shr:1 row_mask:0xf bank_mask:0xf
	v_exp_f32_e32 v80, v78
	v_exp_f32_e32 v81, v79
	v_pk_fma_f32 v[84:85], v[62:63], v[106:107], v[110:111]
	v_pk_add_f32 v[80:81], v[80:81], 1.0 op_sel_hi:[1,0]
	v_rcp_f32_e32 v80, v80
	v_rcp_f32_e32 v81, v81
	v_mov_b32_dpp v76, v42 row_shr:1 row_mask:0xf bank_mask:0xf
	v_mov_b32_dpp v77, v43 row_shr:1 row_mask:0xf bank_mask:0xf
	v_pk_fma_f32 v[84:85], v[102:103], v[68:69], v[84:85]
	v_pk_mul_f32 v[78:79], v[78:79], v[80:81]
	v_pk_fma_f32 v[76:77], v[98:99], v[76:77], v[84:85]
	v_cvt_pk_bf16_f32 v92, v74, v75
	v_pk_mul_f32 v[76:77], v[76:77], v[78:79]
	v_pk_fma_f32 v[44:45], v[44:45], v[120:121], v[124:125]
	v_cvt_pk_bf16_f32 v93, v76, v77
	v_pk_fma_f32 v[76:77], v[36:37], v[120:121], v[124:125]
	v_mov_b32_e32 v90, v247
	v_mov_b32_e32 v91, v248
	global_store_dwordx4 v[202:203], v[90:93], off
	v_pk_fma_f32 v[76:77], v[56:57], v[116:117], v[76:77]
	v_pk_fma_f32 v[52:53], v[52:53], v[104:105], v[108:109]
	v_pk_fma_f32 v[70:71], v[112:113], v[70:71], v[76:77]
	s_nop 0
	v_exp_f32_e32 v74, v70
	v_exp_f32_e32 v75, v71
	s_nop 0
	v_pk_add_f32 v[74:75], v[74:75], 1.0 op_sel_hi:[1,0]
	v_rcp_f32_e32 v74, v74
	v_rcp_f32_e32 v75, v75
	v_pk_fma_f32 v[76:77], v[48:49], v[104:105], v[108:109]
	v_pk_mul_f32 v[70:71], v[70:71], v[74:75]
	v_pk_fma_f32 v[76:77], v[60:61], v[100:101], v[76:77]
	v_pk_fma_f32 v[74:75], v[50:51], v[106:107], v[110:111]
	v_pk_fma_f32 v[66:67], v[96:97], v[66:67], v[76:77]
	v_pk_fma_f32 v[74:75], v[62:63], v[102:103], v[74:75]
	v_pk_mul_f32 v[66:67], v[66:67], v[70:71]
	v_pk_fma_f32 v[70:71], v[38:39], v[122:123], v[126:127]
	v_pk_fma_f32 v[68:69], v[98:99], v[68:69], v[74:75]
	v_pk_fma_f32 v[70:71], v[58:59], v[118:119], v[70:71]
	v_cvt_pk_bf16_f32 v136, v66, v67
	v_pk_fma_f32 v[70:71], v[114:115], v[72:73], v[70:71]
	s_nop 0
	v_exp_f32_e32 v72, v70
	v_exp_f32_e32 v73, v71
	s_nop 0
	v_pk_add_f32 v[72:73], v[72:73], 1.0 op_sel_hi:[1,0]
	v_rcp_f32_e32 v72, v72
	s_barrier
	v_rcp_f32_e32 v73, v73
	s_nop 0
	v_pk_mul_f32 v[70:71], v[70:71], v[72:73]
	s_nop 0
	v_pk_mul_f32 v[68:69], v[68:69], v[70:71]
	s_nop 0
	v_cvt_pk_bf16_f32 v137, v68, v69
	v_pk_fma_f32 v[68:69], v[32:33], v[120:121], v[124:125]
	v_mov_b32_e32 v134, v249
	v_mov_b32_e32 v135, v250
	global_store_dwordx4 v[196:197], v[134:137], off
	v_pk_fma_f32 v[68:69], v[36:37], v[116:117], v[68:69]
	v_pk_fma_f32 v[32:33], v[32:33], v[116:117], v[44:45]
	v_pk_fma_f32 v[56:57], v[56:57], v[112:113], v[68:69]
	v_pk_fma_f32 v[32:33], v[36:37], v[112:113], v[32:33]
	v_exp_f32_e32 v66, v56
	v_exp_f32_e32 v67, v57
	s_nop 0
	v_pk_add_f32 v[66:67], v[66:67], 1.0 op_sel_hi:[1,0]
	v_rcp_f32_e32 v66, v66
	v_rcp_f32_e32 v67, v67
	v_pk_fma_f32 v[68:69], v[40:41], v[104:105], v[108:109]
	v_exp_f32_e32 v44, v32
	v_pk_fma_f32 v[68:69], v[48:49], v[100:101], v[68:69]
	v_pk_mul_f32 v[56:57], v[56:57], v[66:67]
	v_pk_fma_f32 v[60:61], v[60:61], v[96:97], v[68:69]
	v_pk_fma_f32 v[36:37], v[46:47], v[122:123], v[126:127]
	v_pk_mul_f32 v[56:57], v[60:61], v[56:57]
	v_pk_fma_f32 v[60:61], v[34:35], v[122:123], v[126:127]
	v_pk_fma_f32 v[34:35], v[34:35], v[118:119], v[36:37]
	v_pk_fma_f32 v[60:61], v[38:39], v[118:119], v[60:61]
	v_pk_fma_f32 v[34:35], v[38:39], v[114:115], v[34:35]
	v_pk_fma_f32 v[58:59], v[58:59], v[114:115], v[60:61]
	v_exp_f32_e32 v60, v58
	v_exp_f32_e32 v45, v33
	v_exp_f32_e32 v36, v34
	v_exp_f32_e32 v37, v35
	v_exp_f32_e32 v61, v59
	v_cvt_pk_bf16_f32 v164, v56, v57
	v_pk_add_f32 v[44:45], v[44:45], 1.0 op_sel_hi:[1,0]
	v_pk_add_f32 v[36:37], v[36:37], 1.0 op_sel_hi:[1,0]
	v_pk_add_f32 v[60:61], v[60:61], 1.0 op_sel_hi:[1,0]
	v_rcp_f32_e32 v44, v44
	v_rcp_f32_e32 v45, v45
	v_rcp_f32_e32 v36, v36
	v_rcp_f32_e32 v37, v37
	v_rcp_f32_e32 v60, v60
	v_rcp_f32_e32 v61, v61
	v_pk_fma_f32 v[46:47], v[54:55], v[106:107], v[110:111]
	v_pk_fma_f32 v[66:67], v[42:43], v[106:107], v[110:111]
	v_pk_fma_f32 v[40:41], v[40:41], v[100:101], v[52:53]
	v_pk_fma_f32 v[38:39], v[42:43], v[102:103], v[46:47]
	v_pk_fma_f32 v[66:67], v[50:51], v[102:103], v[66:67]
	v_pk_fma_f32 v[40:41], v[48:49], v[96:97], v[40:41]
	v_pk_mul_f32 v[32:33], v[32:33], v[44:45]
	v_pk_fma_f32 v[38:39], v[50:51], v[98:99], v[38:39]
	v_pk_mul_f32 v[34:35], v[34:35], v[36:37]
	v_pk_fma_f32 v[62:63], v[62:63], v[98:99], v[66:67]
	v_pk_mul_f32 v[58:59], v[58:59], v[60:61]
	v_pk_mul_f32 v[32:33], v[40:41], v[32:33]
	v_pk_mul_f32 v[34:35], v[38:39], v[34:35]
	v_pk_mul_f32 v[58:59], v[62:63], v[58:59]
	v_cvt_pk_bf16_f32 v160, v32, v33
	v_cvt_pk_bf16_f32 v161, v34, v35
	v_cvt_pk_bf16_f32 v57, v58, v59
	v_mov_b32_e32 v158, v251
	v_mov_b32_e32 v159, v253
	global_store_dwordx4 v[140:141], v[158:161], off
	v_mov_b32_e32 v65, 0
	v_mov_b64_e32 v[66:67], 0
	v_mov_b64_e32 v[40:41], 0
	v_mov_b64_e32 v[42:43], 0
	v_mov_b64_e32 v[32:33], 0
	v_mov_b64_e32 v[34:35], 0
	v_mov_b64_e32 v[36:37], 0
	v_mov_b64_e32 v[38:39], 0
	v_mov_b32_e32 v162, v254
	v_mov_b32_e32 v163, v255
	v_mov_b32_e32 v165, v57
	global_store_dwordx4 v[152:153], v[162:165], off
	s_barrier
	s_and_saveexec_b64 s[42:43], s[30:31]
	s_cbranch_execz .LBB0_1355
	ds_read_b128 v[36:39], v237 offset:2064
	ds_read_b128 v[40:43], v237 offset:2576
	ds_read_b128 v[32:35], v237 offset:3088
	ds_read_b128 v[64:67], v237 offset:3600
	s_branch .LBB0_1355

; #define LAS __attribute__((address_space(3)))
; __device__ __forceinline__ float sigmoidf_(float x) { return __builtin_amdgcn_rcpf(1.0f + __expf(-x)); }
;     __device__ __forceinline__ void operator()(AccRef acc, const Unit& u, int wr, int wc, int fr, int fq) const {
;     ...
;                 f32x4 h2v = (f32x4){0.f, 0.f, 0.f, 0.f}, h3v = h2v, h2g = h2v, h3g = h2v;
;                 const int pb = ai * 2 + wr - 1;
;                 if (pb >= 0 && fr == 0) { const LAS float* xp = xch + (pb * 2) * 256 + clb + 4 * n;
;                     h2v = *(const LAS f32x4*)(xp); h3v = *(const LAS f32x4*)(xp + 256); h2g = *(const LAS f32x4*)(xp + 128); h3g = *(const LAS f32x4*)(xp + 256 + 128); }
;                 float o[4][4];
; #pragma unroll
;                 for (int j = 0; j < 4; ++j) {
;                     const float v0 = acc[ai][0][0][n][j], v1 = acc[ai][0][1][n][j], v2 = acc[ai][0][2][n][j], v3 = acc[ai][0][3][n][j];
;                     const float g0 = acc[ai][1][0][n][j], g1 = acc[ai][1][1][n][j], g2 = acc[ai][1][2][n][j], g3 = acc[ai][1][3][n][j];
;                     const float pv3 = dpp_upd<0x111>(h3v[j], v3), pv2 = dpp_upd<0x111>(h2v[j], v2), pg3 = dpp_upd<0x111>(h3g[j], g3), pg2 = dpp_upd<0x111>(h2g[j], g2);
;                     const float hv0 = bvv[j] + w2v[j] * v0 + w1v[j] * pv3 + w0v[j] * pv2, hv1 = bvv[j] + w2v[j] * v1 + w1v[j] * v0 + w0v[j] * pv3;
;                     const float hv2 = bvv[j] + w2v[j] * v2 + w1v[j] * v1 + w0v[j] * v0, hv3 = bvv[j] + w2v[j] * v3 + w1v[j] * v2 + w0v[j] * v1;
;                     const float hg0 = bvg[j] + w2g[j] * g0 + w1g[j] * pg3 + w0g[j] * pg2, hg1 = bvg[j] + w2g[j] * g1 + w1g[j] * g0 + w0g[j] * pg3;
;                     const float hg2 = bvg[j] + w2g[j] * g2 + w1g[j] * g1 + w0g[j] * g0, hg3 = bvg[j] + w2g[j] * g3 + w1g[j] * g2 + w0g[j] * g1;
;                     o[0][j] = hg0 * sigmoidf_(hg0) * hv0; o[1][j] = hg1 * sigmoidf_(hg1) * hv1; o[2][j] = hg2 * sigmoidf_(hg2) * hv2; o[3][j] = hg3 * sigmoidf_(hg3) * hv3; }
; #pragma unroll
;                 for (int m = 0; m < 4; ++m) { u32x2 w; w.x = cvt_pk_bf16(o[m][0], o[m][1]); w.y = cvt_pk_bf16(o[m][2], o[m][3]);
;                     *(u32x2*)(Aout + (size_t)(row0 + ai * 128 + m) * FH + hc0 + 4 * n) = w; } } }
.LBB0_1936:
	s_or_b64 exec, exec, s[34:35]
	s_waitcnt lgkmcnt(0)
	v_mov_b32_dpp v64, v8 row_shr:1 row_mask:0xf bank_mask:0xf
	v_mov_b32_dpp v65, v9 row_shr:1 row_mask:0xf bank_mask:0xf
	v_pk_fma_f32 v[44:45], v[24:25], v[120:121], v[124:125]
	v_mov_b32_dpp v40, v0 row_shr:1 row_mask:0xf bank_mask:0xf
	v_mov_b32_dpp v41, v1 row_shr:1 row_mask:0xf bank_mask:0xf
	v_pk_fma_f32 v[44:45], v[116:117], v[64:65], v[44:45]
	v_mov_b32_dpp v32, v20 row_shr:1 row_mask:0xf bank_mask:0xf
	v_pk_fma_f32 v[40:41], v[112:113], v[40:41], v[44:45]
	v_mov_b32_dpp v33, v21 row_shr:1 row_mask:0xf bank_mask:0xf
	v_exp_f32_e32 v44, v40
	v_exp_f32_e32 v45, v41
	v_pk_fma_f32 v[46:47], v[28:29], v[104:105], v[108:109]
	v_mov_b32_dpp v36, v12 row_shr:1 row_mask:0xf bank_mask:0xf
	v_pk_add_f32 v[44:45], v[44:45], 1.0 op_sel_hi:[1,0]
	v_rcp_f32_e32 v44, v44
	v_rcp_f32_e32 v45, v45
	v_mov_b32_dpp v37, v13 row_shr:1 row_mask:0xf bank_mask:0xf
	v_pk_fma_f32 v[46:47], v[100:101], v[32:33], v[46:47]
	v_mov_b32_dpp v66, v10 row_shr:1 row_mask:0xf bank_mask:0xf
	v_pk_fma_f32 v[36:37], v[96:97], v[36:37], v[46:47]
	v_pk_mul_f32 v[40:41], v[40:41], v[44:45]
	v_mov_b32_dpp v67, v11 row_shr:1 row_mask:0xf bank_mask:0xf
	v_pk_mul_f32 v[36:37], v[36:37], v[40:41]
	v_pk_fma_f32 v[40:41], v[26:27], v[122:123], v[126:127]
	v_mov_b32_dpp v42, v2 row_shr:1 row_mask:0xf bank_mask:0xf
	v_mov_b32_dpp v43, v3 row_shr:1 row_mask:0xf bank_mask:0xf
	v_pk_fma_f32 v[40:41], v[118:119], v[66:67], v[40:41]
	v_cvt_pk_bf16_f32 v146, v36, v37
	v_pk_fma_f32 v[40:41], v[114:115], v[42:43], v[40:41]
	v_mov_b32_dpp v34, v22 row_shr:1 row_mask:0xf bank_mask:0xf
	v_exp_f32_e32 v42, v40
	v_exp_f32_e32 v43, v41
	v_mov_b32_dpp v35, v23 row_shr:1 row_mask:0xf bank_mask:0xf
	v_pk_add_f32 v[42:43], v[42:43], 1.0 op_sel_hi:[1,0]
	v_rcp_f32_e32 v42, v42
	v_rcp_f32_e32 v43, v43
	v_pk_fma_f32 v[44:45], v[30:31], v[106:107], v[110:111]
	v_mov_b32_dpp v38, v14 row_shr:1 row_mask:0xf bank_mask:0xf
	v_mov_b32_dpp v39, v15 row_shr:1 row_mask:0xf bank_mask:0xf
	v_pk_fma_f32 v[44:45], v[102:103], v[34:35], v[44:45]
	v_pk_mul_f32 v[40:41], v[40:41], v[42:43]
	v_pk_fma_f32 v[38:39], v[98:99], v[38:39], v[44:45]
	v_pk_fma_f32 v[8:9], v[8:9], v[120:121], v[124:125]
	v_pk_mul_f32 v[38:39], v[38:39], v[40:41]
	v_pk_fma_f32 v[20:21], v[20:21], v[104:105], v[108:109]
	v_cvt_pk_bf16_f32 v147, v38, v39
	v_pk_fma_f32 v[38:39], v[4:5], v[120:121], v[124:125]
	global_store_dwordx4 v[132:133], v[144:147], off
	v_pk_fma_f32 v[38:39], v[24:25], v[116:117], v[38:39]
	s_and_b64 vcc, exec, s[10:11]
	v_pk_fma_f32 v[38:39], v[112:113], v[64:65], v[38:39]
	s_mov_b32 s35, s24
	v_exp_f32_e32 v36, v38
	v_exp_f32_e32 v37, v39
	s_mov_b32 s34, s26
	s_mov_b64 s[38:39], s[30:31]
	v_pk_add_f32 v[36:37], v[36:37], 1.0 op_sel_hi:[1,0]
	v_rcp_f32_e32 v36, v36
	v_rcp_f32_e32 v37, v37
	v_pk_fma_f32 v[40:41], v[16:17], v[104:105], v[108:109]
	s_mov_b64 s[36:37], s[28:29]
	v_pk_fma_f32 v[40:41], v[28:29], v[100:101], v[40:41]
	v_pk_mul_f32 v[36:37], v[38:39], v[36:37]
	v_pk_fma_f32 v[32:33], v[96:97], v[32:33], v[40:41]
	v_pk_fma_f32 v[40:41], v[18:19], v[106:107], v[110:111]
	v_pk_mul_f32 v[32:33], v[32:33], v[36:37]
	v_pk_fma_f32 v[36:37], v[6:7], v[122:123], v[126:127]
	v_cvt_pk_bf16_f32 v156, v32, v33
	v_pk_fma_f32 v[36:37], v[26:27], v[118:119], v[36:37]
	v_pk_fma_f32 v[40:41], v[30:31], v[102:103], v[40:41]
	s_barrier
	v_pk_fma_f32 v[36:37], v[114:115], v[66:67], v[36:37]
	v_pk_fma_f32 v[34:35], v[98:99], v[34:35], v[40:41]
	v_exp_f32_e32 v38, v36
	v_exp_f32_e32 v39, v37
	s_nop 0
	v_pk_add_f32 v[38:39], v[38:39], 1.0 op_sel_hi:[1,0]
	v_rcp_f32_e32 v38, v38
	v_rcp_f32_e32 v39, v39
	s_nop 0
	v_pk_mul_f32 v[36:37], v[36:37], v[38:39]
	s_nop 0
	v_pk_mul_f32 v[34:35], v[34:35], v[36:37]
	s_nop 0
	v_cvt_pk_bf16_f32 v157, v34, v35
	v_pk_fma_f32 v[34:35], v[0:1], v[120:121], v[124:125]
	global_store_dwordx4 v[128:129], v[154:157], off
	v_pk_fma_f32 v[34:35], v[4:5], v[116:117], v[34:35]
	v_pk_fma_f32 v[0:1], v[0:1], v[116:117], v[8:9]
	v_pk_fma_f32 v[24:25], v[24:25], v[112:113], v[34:35]
	v_pk_fma_f32 v[0:1], v[4:5], v[112:113], v[0:1]
	v_exp_f32_e32 v32, v24
	v_exp_f32_e32 v33, v25
	v_exp_f32_e32 v8, v0
	v_pk_add_f32 v[32:33], v[32:33], 1.0 op_sel_hi:[1,0]
	v_rcp_f32_e32 v32, v32
	v_rcp_f32_e32 v33, v33
	v_pk_fma_f32 v[34:35], v[12:13], v[104:105], v[108:109]
	v_pk_fma_f32 v[4:5], v[10:11], v[122:123], v[126:127]
	v_pk_fma_f32 v[34:35], v[16:17], v[100:101], v[34:35]
	v_pk_mul_f32 v[24:25], v[24:25], v[32:33]
	v_pk_fma_f32 v[28:29], v[28:29], v[96:97], v[34:35]
	v_pk_mul_f32 v[24:25], v[28:29], v[24:25]
	v_pk_fma_f32 v[28:29], v[2:3], v[122:123], v[126:127]
	v_pk_fma_f32 v[2:3], v[2:3], v[118:119], v[4:5]
	v_pk_fma_f32 v[28:29], v[6:7], v[118:119], v[28:29]
	v_pk_fma_f32 v[2:3], v[6:7], v[114:115], v[2:3]
	v_pk_fma_f32 v[26:27], v[26:27], v[114:115], v[28:29]
	v_exp_f32_e32 v28, v26
	v_exp_f32_e32 v29, v27
	v_exp_f32_e32 v9, v1
	v_exp_f32_e32 v4, v2
	v_exp_f32_e32 v5, v3
	v_cvt_pk_bf16_f32 v200, v24, v25
	v_pk_add_f32 v[28:29], v[28:29], 1.0 op_sel_hi:[1,0]
	v_pk_add_f32 v[8:9], v[8:9], 1.0 op_sel_hi:[1,0]
	v_pk_add_f32 v[4:5], v[4:5], 1.0 op_sel_hi:[1,0]
	v_rcp_f32_e32 v28, v28
	v_rcp_f32_e32 v29, v29
	v_rcp_f32_e32 v8, v8
	v_rcp_f32_e32 v9, v9
	v_rcp_f32_e32 v4, v4
	v_rcp_f32_e32 v5, v5
	v_pk_fma_f32 v[32:33], v[14:15], v[106:107], v[110:111]
	v_pk_fma_f32 v[10:11], v[22:23], v[106:107], v[110:111]
	v_pk_fma_f32 v[32:33], v[18:19], v[102:103], v[32:33]
	v_pk_fma_f32 v[12:13], v[12:13], v[100:101], v[20:21]
	v_pk_fma_f32 v[6:7], v[14:15], v[102:103], v[10:11]
	v_pk_fma_f32 v[30:31], v[30:31], v[98:99], v[32:33]
	v_pk_mul_f32 v[26:27], v[26:27], v[28:29]
	v_pk_fma_f32 v[12:13], v[16:17], v[96:97], v[12:13]
	v_pk_mul_f32 v[0:1], v[0:1], v[8:9]
	v_pk_fma_f32 v[6:7], v[18:19], v[98:99], v[6:7]
	v_pk_mul_f32 v[2:3], v[2:3], v[4:5]
	v_pk_mul_f32 v[26:27], v[30:31], v[26:27]
	v_pk_mul_f32 v[0:1], v[12:13], v[0:1]
	v_pk_mul_f32 v[2:3], v[6:7], v[2:3]
	v_cvt_pk_bf16_f32 v201, v26, v27
	v_cvt_pk_bf16_f32 v150, v0, v1
	v_cvt_pk_bf16_f32 v151, v2, v3
	global_store_dwordx4 v[88:89], v[198:201], off
	global_store_dwordx4 v[82:83], v[148:151], off
	s_cbranch_vccnz .LBB0_1955

; #define LAS __attribute__((address_space(3)))
; __device__ __forceinline__ float sigmoidf_(float x) { return __builtin_amdgcn_rcpf(1.0f + __expf(-x)); }
;     __device__ __forceinline__ void operator()(AccRef acc, const Unit& u, int wr, int wc, int fr, int fq) const {
;     ...
;                 f32x4 h2v = (f32x4){0.f, 0.f, 0.f, 0.f}, h3v = h2v, h2g = h2v, h3g = h2v;
;                 const int pb = ai * 2 + wr - 1;
;                 if (pb >= 0 && fr == 0) { const LAS float* xp = xch + (pb * 2) * 256 + clb + 4 * n;
;                     h2v = *(const LAS f32x4*)(xp); h3v = *(const LAS f32x4*)(xp + 256); h2g = *(const LAS f32x4*)(xp + 128); h3g = *(const LAS f32x4*)(xp + 256 + 128); }
;                 float o[4][4];
; #pragma unroll
;                 for (int j = 0; j < 4; ++j) {
;                     const float v0 = acc[ai][0][0][n][j], v1 = acc[ai][0][1][n][j], v2 = acc[ai][0][2][n][j], v3 = acc[ai][0][3][n][j];
;                     const float g0 = acc[ai][1][0][n][j], g1 = acc[ai][1][1][n][j], g2 = acc[ai][1][2][n][j], g3 = acc[ai][1][3][n][j];
;                     const float pv3 = dpp_upd<0x111>(h3v[j], v3), pv2 = dpp_upd<0x111>(h2v[j], v2), pg3 = dpp_upd<0x111>(h3g[j], g3), pg2 = dpp_upd<0x111>(h2g[j], g2);
;                     const float hv0 = bvv[j] + w2v[j] * v0 + w1v[j] * pv3 + w0v[j] * pv2, hv1 = bvv[j] + w2v[j] * v1 + w1v[j] * v0 + w0v[j] * pv3;
;                     const float hv2 = bvv[j] + w2v[j] * v2 + w1v[j] * v1 + w0v[j] * v0, hv3 = bvv[j] + w2v[j] * v3 + w1v[j] * v2 + w0v[j] * v1;
;                     const float hg0 = bvg[j] + w2g[j] * g0 + w1g[j] * pg3 + w0g[j] * pg2, hg1 = bvg[j] + w2g[j] * g1 + w1g[j] * g0 + w0g[j] * pg3;
;                     const float hg2 = bvg[j] + w2g[j] * g2 + w1g[j] * g1 + w0g[j] * g0, hg3 = bvg[j] + w2g[j] * g3 + w1g[j] * g2 + w0g[j] * g1;
;                     o[0][j] = hg0 * sigmoidf_(hg0) * hv0; o[1][j] = hg1 * sigmoidf_(hg1) * hv1; o[2][j] = hg2 * sigmoidf_(hg2) * hv2; o[3][j] = hg3 * sigmoidf_(hg3) * hv3; }
; #pragma unroll
;                 for (int m = 0; m < 4; ++m) { u32x2 w; w.x = cvt_pk_bf16(o[m][0], o[m][1]); w.y = cvt_pk_bf16(o[m][2], o[m][3]);
;                     *(u32x2*)(Aout + (size_t)(row0 + ai * 128 + m) * FH + hc0 + 4 * n) = w; } } }
.LBB0_1947:
	s_or_b64 exec, exec, s[40:41]
	v_pk_fma_f32 v[246:247], v[152:153], v[184:185], v[188:189]
	v_mov_b32_dpp v206, v128 row_shr:1 row_mask:0xf bank_mask:0xf
	v_mov_b32_dpp v207, v129 row_shr:1 row_mask:0xf bank_mask:0xf
	v_pk_fma_f32 v[246:247], v[180:181], v[198:199], v[246:247]
	v_mov_b32_dpp v194, v148 row_shr:1 row_mask:0xf bank_mask:0xf
	v_pk_fma_f32 v[206:207], v[176:177], v[206:207], v[246:247]
	v_mov_b32_dpp v195, v149 row_shr:1 row_mask:0xf bank_mask:0xf
	v_exp_f32_e32 v246, v206
	v_exp_f32_e32 v247, v207
	v_pk_fma_f32 v[248:249], v[156:157], v[168:169], v[172:173]
	v_pk_add_f32 v[246:247], v[246:247], 1.0 op_sel_hi:[1,0]
	v_rcp_f32_e32 v246, v246
	v_rcp_f32_e32 v247, v247
	v_mov_b32_dpp v202, v136 row_shr:1 row_mask:0xf bank_mask:0xf
	v_mov_b32_dpp v203, v137 row_shr:1 row_mask:0xf bank_mask:0xf
	v_pk_fma_f32 v[248:249], v[164:165], v[194:195], v[248:249]
	v_pk_mul_f32 v[206:207], v[206:207], v[246:247]
	v_pk_fma_f32 v[202:203], v[160:161], v[202:203], v[248:249]
	v_mov_b32_dpp v200, v142 row_shr:1 row_mask:0xf bank_mask:0xf
	v_mov_b32_dpp v201, v143 row_shr:1 row_mask:0xf bank_mask:0xf
	v_pk_mul_f32 v[202:203], v[202:203], v[206:207]
	v_pk_fma_f32 v[206:207], v[154:155], v[186:187], v[190:191]
	v_mov_b32_dpp v208, v130 row_shr:1 row_mask:0xf bank_mask:0xf
	v_mov_b32_dpp v209, v131 row_shr:1 row_mask:0xf bank_mask:0xf
	v_pk_fma_f32 v[206:207], v[182:183], v[200:201], v[206:207]
	v_mov_b32_dpp v196, v150 row_shr:1 row_mask:0xf bank_mask:0xf
	v_pk_fma_f32 v[206:207], v[178:179], v[208:209], v[206:207]
	v_mov_b32_dpp v197, v151 row_shr:1 row_mask:0xf bank_mask:0xf
	v_exp_f32_e32 v193, v206
	v_exp_f32_e32 v209, v207
	v_cvt_pk_bf16_f32 v208, v202, v203
	v_add_f32_e32 v193, 1.0, v193
	v_rcp_f32_e32 v202, v193
	v_add_f32_e32 v193, 1.0, v209
	v_rcp_f32_e32 v203, v193
	v_pk_fma_f32 v[246:247], v[158:159], v[170:171], v[174:175]
	v_mov_b32_dpp v204, v138 row_shr:1 row_mask:0xf bank_mask:0xf
	v_mov_b32_dpp v205, v139 row_shr:1 row_mask:0xf bank_mask:0xf
	v_pk_fma_f32 v[246:247], v[166:167], v[196:197], v[246:247]
	v_pk_mul_f32 v[202:203], v[206:207], v[202:203]
	v_pk_fma_f32 v[204:205], v[162:163], v[204:205], v[246:247]
	v_lshl_add_u32 v245, s34, 8, v235
	v_pk_mul_f32 v[202:203], v[204:205], v[202:203]
	v_lshlrev_b64 v[204:205], 1, v[232:233]
	v_pk_fma_f32 v[232:233], v[132:133], v[184:185], v[188:189]
	v_mov_b64_e32 v[206:207], s[60:61]
	v_pk_fma_f32 v[232:233], v[152:153], v[180:181], v[232:233]
	v_cvt_pk_bf16_f32 v247, v202, v203
	v_pk_fma_f32 v[198:199], v[176:177], v[198:199], v[232:233]
	v_mad_i64_i32 v[202:203], s[34:35], v245, s63, v[206:207]
	v_exp_f32_e32 v193, v198
	v_exp_f32_e32 v232, v199
	v_lshl_add_u64 v[202:203], v[202:203], 0, v[204:205]
	v_add_f32_e32 v193, 1.0, v193
	v_mov_b32_e32 v246, v208
	v_rcp_f32_e32 v208, v193
	v_add_f32_e32 v193, 1.0, v232
	v_rcp_f32_e32 v209, v193
	v_pk_fma_f32 v[232:233], v[144:145], v[168:169], v[172:173]
	v_pk_fma_f32 v[140:141], v[140:141], v[184:185], v[188:189]
	v_pk_fma_f32 v[232:233], v[156:157], v[164:165], v[232:233]
	v_pk_mul_f32 v[198:199], v[198:199], v[208:209]
	v_pk_fma_f32 v[194:195], v[160:161], v[194:195], v[232:233]
	v_pk_fma_f32 v[208:209], v[146:147], v[170:171], v[174:175]
	v_pk_mul_f32 v[194:195], v[194:195], v[198:199]
	v_pk_fma_f32 v[198:199], v[134:135], v[186:187], v[190:191]
	v_pk_fma_f32 v[208:209], v[158:159], v[166:167], v[208:209]
	v_pk_fma_f32 v[198:199], v[154:155], v[182:183], v[198:199]
	v_pk_fma_f32 v[196:197], v[162:163], v[196:197], v[208:209]
	v_pk_fma_f32 v[198:199], v[178:179], v[200:201], v[198:199]
	v_cvt_pk_bf16_f32 v248, v194, v195
	v_exp_f32_e32 v200, v198
	v_exp_f32_e32 v201, v199
	v_pk_fma_f32 v[148:149], v[148:149], v[168:169], v[172:173]
	s_barrier
	v_pk_add_f32 v[200:201], v[200:201], 1.0 op_sel_hi:[1,0]
	v_rcp_f32_e32 v200, v200
	v_rcp_f32_e32 v201, v201
	v_or_b32_e32 v193, 1, v245
	v_pk_mul_f32 v[198:199], v[198:199], v[200:201]
	s_nop 0
	v_pk_mul_f32 v[196:197], v[196:197], v[198:199]
	v_pk_fma_f32 v[198:199], v[128:129], v[184:185], v[188:189]
	v_cvt_pk_bf16_f32 v249, v196, v197
	v_pk_fma_f32 v[198:199], v[132:133], v[180:181], v[198:199]
	v_mad_i64_i32 v[196:197], s[34:35], v193, s63, v[206:207]
	v_pk_fma_f32 v[152:153], v[152:153], v[176:177], v[198:199]
	v_lshl_add_u64 v[196:197], v[196:197], 0, v[204:205]
	v_exp_f32_e32 v193, v152
	v_exp_f32_e32 v198, v153
	v_add_f32_e32 v193, 1.0, v193
	v_rcp_f32_e32 v194, v193
	v_add_f32_e32 v193, 1.0, v198
	v_rcp_f32_e32 v195, v193
	v_pk_fma_f32 v[198:199], v[136:137], v[168:169], v[172:173]
	v_pk_fma_f32 v[128:129], v[128:129], v[180:181], v[140:141]
	v_pk_fma_f32 v[198:199], v[144:145], v[164:165], v[198:199]
	v_pk_fma_f32 v[128:129], v[132:133], v[176:177], v[128:129]
	v_pk_fma_f32 v[156:157], v[156:157], v[160:161], v[198:199]
	v_pk_mul_f32 v[152:153], v[152:153], v[194:195]
	v_pk_mul_f32 v[152:153], v[156:157], v[152:153]
	v_pk_fma_f32 v[156:157], v[130:131], v[186:187], v[190:191]
	v_exp_f32_e32 v140, v128
	v_pk_fma_f32 v[132:133], v[142:143], v[186:187], v[190:191]
	v_pk_fma_f32 v[156:157], v[134:135], v[182:183], v[156:157]
	v_pk_fma_f32 v[130:131], v[130:131], v[182:183], v[132:133]
	v_pk_fma_f32 v[154:155], v[154:155], v[178:179], v[156:157]
	v_pk_fma_f32 v[130:131], v[134:135], v[178:179], v[130:131]
	v_exp_f32_e32 v157, v154
	v_exp_f32_e32 v141, v129
	v_exp_f32_e32 v132, v130
	v_exp_f32_e32 v133, v131
	v_exp_f32_e32 v193, v155
	v_pk_add_f32 v[140:141], v[140:141], 1.0 op_sel_hi:[1,0]
	v_pk_add_f32 v[132:133], v[132:133], 1.0 op_sel_hi:[1,0]
	v_cvt_pk_bf16_f32 v253, v152, v153
	v_add_f32_e32 v152, 1.0, v157
	v_add_f32_e32 v153, 1.0, v193
	v_rcp_f32_e32 v140, v140
; #define LAS __attribute__((address_space(3)))
; __device__ __forceinline__ float sigmoidf_(float x) { return __builtin_amdgcn_rcpf(1.0f + __expf(-x)); }
;     __device__ __forceinline__ void operator()(AccRef acc, const Unit& u, int wr, int wc, int fr, int fq) const {
;     ...
;                 f32x4 h2v = (f32x4){0.f, 0.f, 0.f, 0.f}, h3v = h2v, h2g = h2v, h3g = h2v;
;                 const int pb = ai * 2 + wr - 1;
;                 if (pb >= 0 && fr == 0) { const LAS float* xp = xch + (pb * 2) * 256 + clb + 4 * n;
;                     h2v = *(const LAS f32x4*)(xp); h3v = *(const LAS f32x4*)(xp + 256); h2g = *(const LAS f32x4*)(xp + 128); h3g = *(const LAS f32x4*)(xp + 256 + 128); }
;                 float o[4][4];
; #pragma unroll
;                 for (int j = 0; j < 4; ++j) {
;                     const float v0 = acc[ai][0][0][n][j], v1 = acc[ai][0][1][n][j], v2 = acc[ai][0][2][n][j], v3 = acc[ai][0][3][n][j];
;                     const float g0 = acc[ai][1][0][n][j], g1 = acc[ai][1][1][n][j], g2 = acc[ai][1][2][n][j], g3 = acc[ai][1][3][n][j];
;                     const float pv3 = dpp_upd<0x111>(h3v[j], v3), pv2 = dpp_upd<0x111>(h2v[j], v2), pg3 = dpp_upd<0x111>(h3g[j], g3), pg2 = dpp_upd<0x111>(h2g[j], g2);
;                     const float hv0 = bvv[j] + w2v[j] * v0 + w1v[j] * pv3 + w0v[j] * pv2, hv1 = bvv[j] + w2v[j] * v1 + w1v[j] * v0 + w0v[j] * pv3;
;                     const float hv2 = bvv[j] + w2v[j] * v2 + w1v[j] * v1 + w0v[j] * v0, hv3 = bvv[j] + w2v[j] * v3 + w1v[j] * v2 + w0v[j] * v1;
;                     const float hg0 = bvg[j] + w2g[j] * g0 + w1g[j] * pg3 + w0g[j] * pg2, hg1 = bvg[j] + w2g[j] * g1 + w1g[j] * g0 + w0g[j] * pg3;
;                     const float hg2 = bvg[j] + w2g[j] * g2 + w1g[j] * g1 + w0g[j] * g0, hg3 = bvg[j] + w2g[j] * g3 + w1g[j] * g2 + w0g[j] * g1;
;                     o[0][j] = hg0 * sigmoidf_(hg0) * hv0; o[1][j] = hg1 * sigmoidf_(hg1) * hv1; o[2][j] = hg2 * sigmoidf_(hg2) * hv2; o[3][j] = hg3 * sigmoidf_(hg3) * hv3; }
; #pragma unroll
;                 for (int m = 0; m < 4; ++m) { u32x2 w; w.x = cvt_pk_bf16(o[m][0], o[m][1]); w.y = cvt_pk_bf16(o[m][2], o[m][3]);
;                     *(u32x2*)(Aout + (size_t)(row0 + ai * 128 + m) * FH + hc0 + 4 * n) = w; } } }
	v_rcp_f32_e32 v141, v141
	v_rcp_f32_e32 v132, v132
	v_rcp_f32_e32 v133, v133
	v_rcp_f32_e32 v152, v152
	v_rcp_f32_e32 v153, v153
	v_pk_fma_f32 v[142:143], v[150:151], v[170:171], v[174:175]
	v_pk_fma_f32 v[194:195], v[138:139], v[170:171], v[174:175]
	v_pk_fma_f32 v[136:137], v[136:137], v[164:165], v[148:149]
	v_pk_fma_f32 v[134:135], v[138:139], v[166:167], v[142:143]
	v_pk_fma_f32 v[194:195], v[146:147], v[166:167], v[194:195]
	v_pk_fma_f32 v[136:137], v[144:145], v[160:161], v[136:137]
	v_pk_mul_f32 v[128:129], v[128:129], v[140:141]
	v_pk_fma_f32 v[134:135], v[146:147], v[162:163], v[134:135]
	v_pk_mul_f32 v[130:131], v[130:131], v[132:133]
	v_pk_fma_f32 v[158:159], v[158:159], v[162:163], v[194:195]
	v_pk_mul_f32 v[152:153], v[154:155], v[152:153]
	v_pk_mul_f32 v[128:129], v[136:137], v[128:129]
	v_pk_mul_f32 v[130:131], v[134:135], v[130:131]
	v_pk_mul_f32 v[152:153], v[158:159], v[152:153]
	v_cvt_pk_bf16_f32 v250, v128, v129
	v_cvt_pk_bf16_f32 v251, v130, v131
	v_or_b32_e32 v130, 3, v245
	v_cvt_pk_bf16_f32 v254, v152, v153
	v_or_b32_e32 v152, 2, v245
	v_mad_i64_i32 v[130:131], s[34:35], v130, s63, v[206:207]
	v_mad_i64_i32 v[152:153], s[34:35], v152, s63, v[206:207]
	v_lshl_add_u64 v[140:141], v[130:131], 0, v[204:205]
	v_lshl_add_u64 v[152:153], v[152:153], 0, v[204:205]
	v_mov_b32_e32 v193, 0
	v_mov_b64_e32 v[194:195], 0
	v_mov_b64_e32 v[136:137], 0
	v_mov_b64_e32 v[138:139], 0
	v_mov_b64_e32 v[128:129], 0
	v_mov_b64_e32 v[130:131], 0
	v_mov_b64_e32 v[132:133], 0
	v_mov_b64_e32 v[134:135], 0
	s_barrier
	s_and_saveexec_b64 s[34:35], s[22:23]
	s_cbranch_execz .LBB0_1951
	ds_read_b128 v[132:135], v236 offset:2048
	ds_read_b128 v[136:139], v236 offset:2560
	ds_read_b128 v[128:131], v236 offset:3072
	ds_read_b128 v[192:195], v236 offset:3584
.LBB0_1951:
	s_or_b64 exec, exec, s[34:35]
	s_waitcnt lgkmcnt(0)
	v_mov_b32_dpp v192, v72 row_shr:1 row_mask:0xf bank_mask:0xf
	v_mov_b32_dpp v193, v73 row_shr:1 row_mask:0xf bank_mask:0xf
	v_pk_fma_f32 v[142:143], v[88:89], v[184:185], v[188:189]
	v_mov_b32_dpp v136, v64 row_shr:1 row_mask:0xf bank_mask:0xf
	v_mov_b32_dpp v137, v65 row_shr:1 row_mask:0xf bank_mask:0xf
	v_pk_fma_f32 v[142:143], v[180:181], v[192:193], v[142:143]
	v_mov_b32_dpp v128, v84 row_shr:1 row_mask:0xf bank_mask:0xf
	v_pk_fma_f32 v[136:137], v[176:177], v[136:137], v[142:143]
	v_mov_b32_dpp v129, v85 row_shr:1 row_mask:0xf bank_mask:0xf
	v_exp_f32_e32 v142, v136
	v_exp_f32_e32 v143, v137
	v_pk_fma_f32 v[144:145], v[92:93], v[168:169], v[172:173]
	v_mov_b32_dpp v132, v76 row_shr:1 row_mask:0xf bank_mask:0xf
	v_pk_add_f32 v[142:143], v[142:143], 1.0 op_sel_hi:[1,0]
	v_rcp_f32_e32 v142, v142
	v_rcp_f32_e32 v143, v143
	v_mov_b32_dpp v133, v77 row_shr:1 row_mask:0xf bank_mask:0xf
	v_pk_fma_f32 v[144:145], v[164:165], v[128:129], v[144:145]
	v_mov_b32_dpp v194, v74 row_shr:1 row_mask:0xf bank_mask:0xf
	v_pk_fma_f32 v[132:133], v[160:161], v[132:133], v[144:145]
	v_pk_mul_f32 v[136:137], v[136:137], v[142:143]
	v_mov_b32_dpp v195, v75 row_shr:1 row_mask:0xf bank_mask:0xf
	v_pk_mul_f32 v[132:133], v[132:133], v[136:137]
	v_pk_fma_f32 v[136:137], v[90:91], v[186:187], v[190:191]
	v_mov_b32_dpp v138, v66 row_shr:1 row_mask:0xf bank_mask:0xf
	v_mov_b32_dpp v139, v67 row_shr:1 row_mask:0xf bank_mask:0xf
	v_pk_fma_f32 v[136:137], v[182:183], v[194:195], v[136:137]
	v_mov_b32_dpp v130, v86 row_shr:1 row_mask:0xf bank_mask:0xf
	v_pk_fma_f32 v[136:137], v[178:179], v[138:139], v[136:137]
	v_mov_b32_dpp v131, v87 row_shr:1 row_mask:0xf bank_mask:0xf
	v_exp_f32_e32 v139, v136
	v_exp_f32_e32 v142, v137
	v_cvt_pk_bf16_f32 v144, v132, v133
	v_add_f32_e32 v132, 1.0, v139
	v_rcp_f32_e32 v132, v132
	v_add_f32_e32 v133, 1.0, v142
	v_rcp_f32_e32 v133, v133
	v_pk_fma_f32 v[142:143], v[94:95], v[170:171], v[174:175]
	v_mov_b32_dpp v134, v78 row_shr:1 row_mask:0xf bank_mask:0xf
	v_mov_b32_dpp v135, v79 row_shr:1 row_mask:0xf bank_mask:0xf
	v_pk_mul_f32 v[132:133], v[136:137], v[132:133]
	v_pk_fma_f32 v[136:137], v[68:69], v[184:185], v[188:189]
	v_pk_fma_f32 v[142:143], v[166:167], v[130:131], v[142:143]
	v_pk_fma_f32 v[136:137], v[88:89], v[180:181], v[136:137]
	v_pk_fma_f32 v[134:135], v[162:163], v[134:135], v[142:143]
	v_pk_fma_f32 v[136:137], v[176:177], v[192:193], v[136:137]
	v_add_u32_e32 v146, 0x80, v245
	v_exp_f32_e32 v142, v136
	v_exp_f32_e32 v143, v137
	v_pk_mul_f32 v[132:133], v[134:135], v[132:133]
	v_mov_b64_e32 v[134:135], s[60:61]
	v_cvt_pk_bf16_f32 v145, v132, v133
	v_mad_i64_i32 v[132:133], s[34:35], v146, s63, v[134:135]
	v_lshl_add_u64 v[132:133], v[132:133], 0, v[204:205]
	v_add_f32_e32 v138, 1.0, v142
	v_add_f32_e32 v139, 1.0, v143
	v_rcp_f32_e32 v138, v138
	v_rcp_f32_e32 v139, v139
	v_pk_fma_f32 v[142:143], v[80:81], v[168:169], v[172:173]
	v_pk_fma_f32 v[72:73], v[72:73], v[184:185], v[188:189]
	v_pk_fma_f32 v[142:143], v[92:93], v[164:165], v[142:143]
	v_pk_mul_f32 v[136:137], v[136:137], v[138:139]
	v_pk_fma_f32 v[128:129], v[160:161], v[128:129], v[142:143]
	v_pk_fma_f32 v[84:85], v[84:85], v[168:169], v[172:173]
	v_pk_mul_f32 v[128:129], v[128:129], v[136:137]
	v_pk_fma_f32 v[136:137], v[70:71], v[186:187], v[190:191]
	s_nop 0
	v_pk_fma_f32 v[136:137], v[90:91], v[182:183], v[136:137]
	s_nop 0
	v_pk_fma_f32 v[136:137], v[178:179], v[194:195], v[136:137]
	s_nop 0
	v_exp_f32_e32 v139, v136
	v_exp_f32_e32 v142, v137
	v_cvt_pk_bf16_f32 v138, v128, v129
	v_add_f32_e32 v128, 1.0, v139
	v_rcp_f32_e32 v128, v128
	v_add_f32_e32 v129, 1.0, v142
	v_rcp_f32_e32 v129, v129
	v_pk_fma_f32 v[142:143], v[82:83], v[170:171], v[174:175]
	v_pk_mul_f32 v[128:129], v[136:137], v[128:129]
	s_barrier
; #define LAS __attribute__((address_space(3)))
; __device__ __forceinline__ float sigmoidf_(float x) { return __builtin_amdgcn_rcpf(1.0f + __expf(-x)); }
;     __device__ __forceinline__ void operator()(AccRef acc, const Unit& u, int wr, int wc, int fr, int fq) const {
;     ...
;                 f32x4 h2v = (f32x4){0.f, 0.f, 0.f, 0.f}, h3v = h2v, h2g = h2v, h3g = h2v;
;                 const int pb = ai * 2 + wr - 1;
;                 if (pb >= 0 && fr == 0) { const LAS float* xp = xch + (pb * 2) * 256 + clb + 4 * n;
;                     h2v = *(const LAS f32x4*)(xp); h3v = *(const LAS f32x4*)(xp + 256); h2g = *(const LAS f32x4*)(xp + 128); h3g = *(const LAS f32x4*)(xp + 256 + 128); }
;                 float o[4][4];
; #pragma unroll
;                 for (int j = 0; j < 4; ++j) {
;                     const float v0 = acc[ai][0][0][n][j], v1 = acc[ai][0][1][n][j], v2 = acc[ai][0][2][n][j], v3 = acc[ai][0][3][n][j];
;                     const float g0 = acc[ai][1][0][n][j], g1 = acc[ai][1][1][n][j], g2 = acc[ai][1][2][n][j], g3 = acc[ai][1][3][n][j];
;                     const float pv3 = dpp_upd<0x111>(h3v[j], v3), pv2 = dpp_upd<0x111>(h2v[j], v2), pg3 = dpp_upd<0x111>(h3g[j], g3), pg2 = dpp_upd<0x111>(h2g[j], g2);
;                     const float hv0 = bvv[j] + w2v[j] * v0 + w1v[j] * pv3 + w0v[j] * pv2, hv1 = bvv[j] + w2v[j] * v1 + w1v[j] * v0 + w0v[j] * pv3;
;                     const float hv2 = bvv[j] + w2v[j] * v2 + w1v[j] * v1 + w0v[j] * v0, hv3 = bvv[j] + w2v[j] * v3 + w1v[j] * v2 + w0v[j] * v1;
;                     const float hg0 = bvg[j] + w2g[j] * g0 + w1g[j] * pg3 + w0g[j] * pg2, hg1 = bvg[j] + w2g[j] * g1 + w1g[j] * g0 + w0g[j] * pg3;
;                     const float hg2 = bvg[j] + w2g[j] * g2 + w1g[j] * g1 + w0g[j] * g0, hg3 = bvg[j] + w2g[j] * g3 + w1g[j] * g2 + w0g[j] * g1;
;                     o[0][j] = hg0 * sigmoidf_(hg0) * hv0; o[1][j] = hg1 * sigmoidf_(hg1) * hv1; o[2][j] = hg2 * sigmoidf_(hg2) * hv2; o[3][j] = hg3 * sigmoidf_(hg3) * hv3; }
; #pragma unroll
;                 for (int m = 0; m < 4; ++m) { u32x2 w; w.x = cvt_pk_bf16(o[m][0], o[m][1]); w.y = cvt_pk_bf16(o[m][2], o[m][3]);
;                     *(u32x2*)(Aout + (size_t)(row0 + ai * 128 + m) * FH + hc0 + 4 * n) = w; } } }
	v_pk_fma_f32 v[142:143], v[94:95], v[166:167], v[142:143]
	v_pk_fma_f32 v[136:137], v[76:77], v[168:169], v[172:173]
	v_pk_fma_f32 v[130:131], v[162:163], v[130:131], v[142:143]
	v_pk_fma_f32 v[136:137], v[80:81], v[164:165], v[136:137]
	v_pk_mul_f32 v[128:129], v[130:131], v[128:129]
	v_pk_fma_f32 v[130:131], v[64:65], v[184:185], v[188:189]
	v_pk_fma_f32 v[64:65], v[64:65], v[180:181], v[72:73]
	v_pk_fma_f32 v[130:131], v[68:69], v[180:181], v[130:131]
	v_pk_fma_f32 v[64:65], v[68:69], v[176:177], v[64:65]
	v_pk_fma_f32 v[88:89], v[88:89], v[176:177], v[130:131]
	v_pk_fma_f32 v[92:93], v[92:93], v[160:161], v[136:137]
	v_exp_f32_e32 v130, v88
	v_exp_f32_e32 v131, v89
	v_exp_f32_e32 v72, v64
	v_pk_add_f32 v[130:131], v[130:131], 1.0 op_sel_hi:[1,0]
	v_rcp_f32_e32 v130, v130
	v_rcp_f32_e32 v131, v131
	v_pk_fma_f32 v[68:69], v[74:75], v[186:187], v[190:191]
	v_exp_f32_e32 v73, v65
	v_pk_mul_f32 v[88:89], v[88:89], v[130:131]
	v_pk_mul_f32 v[88:89], v[92:93], v[88:89]
	v_pk_fma_f32 v[92:93], v[66:67], v[186:187], v[190:191]
	v_pk_fma_f32 v[66:67], v[66:67], v[182:183], v[68:69]
	v_pk_fma_f32 v[92:93], v[70:71], v[182:183], v[92:93]
	v_pk_fma_f32 v[66:67], v[70:71], v[178:179], v[66:67]
	v_pk_fma_f32 v[90:91], v[90:91], v[178:179], v[92:93]
	v_exp_f32_e32 v93, v90
	v_exp_f32_e32 v68, v66
	v_exp_f32_e32 v69, v67
	v_exp_f32_e32 v130, v91
	v_pk_add_f32 v[72:73], v[72:73], 1.0 op_sel_hi:[1,0]
	v_pk_add_f32 v[68:69], v[68:69], 1.0 op_sel_hi:[1,0]
	v_cvt_pk_bf16_f32 v198, v88, v89
	v_add_f32_e32 v88, 1.0, v93
	v_add_f32_e32 v89, 1.0, v130
	v_rcp_f32_e32 v72, v72
	v_rcp_f32_e32 v73, v73
	v_rcp_f32_e32 v68, v68
	v_rcp_f32_e32 v69, v69
	v_rcp_f32_e32 v88, v88
	v_rcp_f32_e32 v89, v89
	v_pk_fma_f32 v[74:75], v[86:87], v[170:171], v[174:175]
	v_pk_fma_f32 v[130:131], v[78:79], v[170:171], v[174:175]
	v_pk_fma_f32 v[76:77], v[76:77], v[164:165], v[84:85]
	v_pk_fma_f32 v[70:71], v[78:79], v[166:167], v[74:75]
	v_pk_fma_f32 v[130:131], v[82:83], v[166:167], v[130:131]
	v_pk_fma_f32 v[76:77], v[80:81], v[160:161], v[76:77]
	v_pk_mul_f32 v[64:65], v[64:65], v[72:73]
	v_pk_fma_f32 v[70:71], v[82:83], v[162:163], v[70:71]
	v_pk_mul_f32 v[66:67], v[66:67], v[68:69]
	v_pk_fma_f32 v[94:95], v[94:95], v[162:163], v[130:131]
	v_pk_mul_f32 v[88:89], v[90:91], v[88:89]
	v_pk_mul_f32 v[64:65], v[76:77], v[64:65]
	v_pk_mul_f32 v[66:67], v[70:71], v[66:67]
	v_pk_mul_f32 v[88:89], v[94:95], v[88:89]
	v_cvt_pk_bf16_f32 v148, v64, v65
	v_cvt_pk_bf16_f32 v149, v66, v67
	v_add_u32_e32 v66, 0x83, v245
	v_cvt_pk_bf16_f32 v155, v128, v129
	v_add_u32_e32 v128, 0x81, v245
	v_cvt_pk_bf16_f32 v199, v88, v89
	v_add_u32_e32 v88, 0x82, v245
	v_mad_i64_i32 v[66:67], s[34:35], v66, s63, v[134:135]
	v_mad_i64_i32 v[128:129], s[34:35], v128, s63, v[134:135]
	v_mad_i64_i32 v[88:89], s[34:35], v88, s63, v[134:135]
	v_lshl_add_u64 v[82:83], v[66:67], 0, v[204:205]
	v_lshl_add_u64 v[128:129], v[128:129], 0, v[204:205]
	v_lshl_add_u64 v[88:89], v[88:89], 0, v[204:205]
	v_mov_b32_e32 v64, 0
	v_mov_b64_e32 v[70:71], 0
	v_mov_b64_e32 v[72:73], 0
	v_mov_b64_e32 v[78:79], 0
	v_mov_b64_e32 v[80:81], 0
	v_mov_b64_e32 v[66:67], 0
	v_mov_b64_e32 v[68:69], 0
	v_mov_b64_e32 v[74:75], 0
	v_mov_b64_e32 v[76:77], 0
	v_mov_b32_e32 v154, v138
	s_barrier
	s_and_saveexec_b64 s[34:35], s[20:21]
	s_cbranch_execz .LBB0_1953
	ds_read_b128 v[74:77], v241
	ds_read_b128 v[66:69], v240
	ds_read_b128 v[78:81], v239
	ds_read_b128 v[70:73], v238
; #define LAS __attribute__((address_space(3)))
; __device__ __forceinline__ float sigmoidf_(float x) { return __builtin_amdgcn_rcpf(1.0f + __expf(-x)); }
;     __device__ __forceinline__ void operator()(AccRef acc, const Unit& u, int wr, int wc, int fr, int fq) const {
;     ...
;                 f32x4 h2v = (f32x4){0.f, 0.f, 0.f, 0.f}, h3v = h2v, h2g = h2v, h3g = h2v;
;                 const int pb = ai * 2 + wr - 1;
;                 if (pb >= 0 && fr == 0) { const LAS float* xp = xch + (pb * 2) * 256 + clb + 4 * n;
;                     h2v = *(const LAS f32x4*)(xp); h3v = *(const LAS f32x4*)(xp + 256); h2g = *(const LAS f32x4*)(xp + 128); h3g = *(const LAS f32x4*)(xp + 256 + 128); }
;                 float o[4][4];
; #pragma unroll
;                 for (int j = 0; j < 4; ++j) {
;                     const float v0 = acc[ai][0][0][n][j], v1 = acc[ai][0][1][n][j], v2 = acc[ai][0][2][n][j], v3 = acc[ai][0][3][n][j];
;                     const float g0 = acc[ai][1][0][n][j], g1 = acc[ai][1][1][n][j], g2 = acc[ai][1][2][n][j], g3 = acc[ai][1][3][n][j];
;                     const float pv3 = dpp_upd<0x111>(h3v[j], v3), pv2 = dpp_upd<0x111>(h2v[j], v2), pg3 = dpp_upd<0x111>(h3g[j], g3), pg2 = dpp_upd<0x111>(h2g[j], g2);
;                     const float hv0 = bvv[j] + w2v[j] * v0 + w1v[j] * pv3 + w0v[j] * pv2, hv1 = bvv[j] + w2v[j] * v1 + w1v[j] * v0 + w0v[j] * pv3;
;                     const float hv2 = bvv[j] + w2v[j] * v2 + w1v[j] * v1 + w0v[j] * v0, hv3 = bvv[j] + w2v[j] * v3 + w1v[j] * v2 + w0v[j] * v1;
;                     const float hg0 = bvg[j] + w2g[j] * g0 + w1g[j] * pg3 + w0g[j] * pg2, hg1 = bvg[j] + w2g[j] * g1 + w1g[j] * g0 + w0g[j] * pg3;
;                     const float hg2 = bvg[j] + w2g[j] * g2 + w1g[j] * g1 + w0g[j] * g0, hg3 = bvg[j] + w2g[j] * g3 + w1g[j] * g2 + w0g[j] * g1;
;                     o[0][j] = hg0 * sigmoidf_(hg0) * hv0; o[1][j] = hg1 * sigmoidf_(hg1) * hv1; o[2][j] = hg2 * sigmoidf_(hg2) * hv2; o[3][j] = hg3 * sigmoidf_(hg3) * hv3; }
; #pragma unroll
;                 for (int m = 0; m < 4; ++m) { u32x2 w; w.x = cvt_pk_bf16(o[m][0], o[m][1]); w.y = cvt_pk_bf16(o[m][2], o[m][3]);
;                     *(u32x2*)(Aout + (size_t)(row0 + ai * 128 + m) * FH + hc0 + 4 * n) = w; } } }
.LBB0_1953:
	s_or_b64 exec, exec, s[34:35]
	s_waitcnt lgkmcnt(0)
	v_mov_b32_dpp v70, v44 row_shr:1 row_mask:0xf bank_mask:0xf
	v_mov_b32_dpp v71, v45 row_shr:1 row_mask:0xf bank_mask:0xf
	s_waitcnt vmcnt(0)
	v_pk_fma_f32 v[84:85], v[56:57], v[120:121], v[124:125]
	v_mov_b32_dpp v78, v32 row_shr:1 row_mask:0xf bank_mask:0xf
	v_mov_b32_dpp v79, v33 row_shr:1 row_mask:0xf bank_mask:0xf
	v_pk_fma_f32 v[84:85], v[116:117], v[70:71], v[84:85]
	v_mov_b32_dpp v66, v52 row_shr:1 row_mask:0xf bank_mask:0xf
	v_pk_fma_f32 v[78:79], v[112:113], v[78:79], v[84:85]
	v_mov_b32_dpp v67, v53 row_shr:1 row_mask:0xf bank_mask:0xf
	v_exp_f32_e32 v84, v78
	v_exp_f32_e32 v85, v79
	v_pk_fma_f32 v[86:87], v[60:61], v[104:105], v[108:109]
	v_pk_add_f32 v[84:85], v[84:85], 1.0 op_sel_hi:[1,0]
	v_rcp_f32_e32 v84, v84
	v_rcp_f32_e32 v85, v85
	v_mov_b32_dpp v74, v40 row_shr:1 row_mask:0xf bank_mask:0xf
	v_mov_b32_dpp v75, v41 row_shr:1 row_mask:0xf bank_mask:0xf
	v_pk_fma_f32 v[86:87], v[100:101], v[66:67], v[86:87]
	v_pk_mul_f32 v[78:79], v[78:79], v[84:85]
	v_pk_fma_f32 v[74:75], v[96:97], v[74:75], v[86:87]
	v_mov_b32_dpp v72, v46 row_shr:1 row_mask:0xf bank_mask:0xf
	v_mov_b32_dpp v73, v47 row_shr:1 row_mask:0xf bank_mask:0xf
	v_pk_mul_f32 v[74:75], v[74:75], v[78:79]
	v_pk_fma_f32 v[78:79], v[58:59], v[122:123], v[126:127]
	v_mov_b32_dpp v80, v34 row_shr:1 row_mask:0xf bank_mask:0xf
	v_mov_b32_dpp v81, v35 row_shr:1 row_mask:0xf bank_mask:0xf
	v_pk_fma_f32 v[78:79], v[118:119], v[72:73], v[78:79]
	v_mov_b32_dpp v68, v54 row_shr:1 row_mask:0xf bank_mask:0xf
	v_pk_fma_f32 v[78:79], v[114:115], v[80:81], v[78:79]
	v_mov_b32_dpp v69, v55 row_shr:1 row_mask:0xf bank_mask:0xf
	v_exp_f32_e32 v80, v78
	v_exp_f32_e32 v81, v79
	v_pk_fma_f32 v[84:85], v[62:63], v[106:107], v[110:111]
	v_pk_add_f32 v[80:81], v[80:81], 1.0 op_sel_hi:[1,0]
	v_rcp_f32_e32 v80, v80
	v_rcp_f32_e32 v81, v81
	v_mov_b32_dpp v76, v42 row_shr:1 row_mask:0xf bank_mask:0xf
	v_mov_b32_dpp v77, v43 row_shr:1 row_mask:0xf bank_mask:0xf
	v_pk_fma_f32 v[84:85], v[102:103], v[68:69], v[84:85]
	v_pk_mul_f32 v[78:79], v[78:79], v[80:81]
	v_pk_fma_f32 v[76:77], v[98:99], v[76:77], v[84:85]
	v_cvt_pk_bf16_f32 v92, v74, v75
	v_pk_mul_f32 v[76:77], v[76:77], v[78:79]
	v_pk_fma_f32 v[44:45], v[44:45], v[120:121], v[124:125]
	v_cvt_pk_bf16_f32 v93, v76, v77
	v_pk_fma_f32 v[76:77], v[36:37], v[120:121], v[124:125]
	v_mov_b32_e32 v90, v246
	v_mov_b32_e32 v91, v247
	global_store_dwordx4 v[202:203], v[90:93], off
	v_pk_fma_f32 v[76:77], v[56:57], v[116:117], v[76:77]
	v_pk_fma_f32 v[52:53], v[52:53], v[104:105], v[108:109]
	v_pk_fma_f32 v[70:71], v[112:113], v[70:71], v[76:77]
	s_nop 0
	v_exp_f32_e32 v74, v70
	v_exp_f32_e32 v75, v71
	s_nop 0
	v_pk_add_f32 v[74:75], v[74:75], 1.0 op_sel_hi:[1,0]
	v_rcp_f32_e32 v74, v74
	v_rcp_f32_e32 v75, v75
	v_pk_fma_f32 v[76:77], v[48:49], v[104:105], v[108:109]
	v_pk_mul_f32 v[70:71], v[70:71], v[74:75]
	v_pk_fma_f32 v[76:77], v[60:61], v[100:101], v[76:77]
	v_pk_fma_f32 v[74:75], v[50:51], v[106:107], v[110:111]
	v_pk_fma_f32 v[66:67], v[96:97], v[66:67], v[76:77]
	v_pk_fma_f32 v[74:75], v[62:63], v[102:103], v[74:75]
	v_pk_mul_f32 v[66:67], v[66:67], v[70:71]
	v_pk_fma_f32 v[70:71], v[38:39], v[122:123], v[126:127]
	v_pk_fma_f32 v[68:69], v[98:99], v[68:69], v[74:75]
	v_pk_fma_f32 v[70:71], v[58:59], v[118:119], v[70:71]
	v_cvt_pk_bf16_f32 v136, v66, v67
	v_pk_fma_f32 v[70:71], v[114:115], v[72:73], v[70:71]
	s_nop 0
	v_exp_f32_e32 v72, v70
	v_exp_f32_e32 v73, v71
	s_nop 0
	v_pk_add_f32 v[72:73], v[72:73], 1.0 op_sel_hi:[1,0]
	v_rcp_f32_e32 v72, v72
	s_barrier
	v_rcp_f32_e32 v73, v73
	s_nop 0
	v_pk_mul_f32 v[70:71], v[70:71], v[72:73]
	s_nop 0
	v_pk_mul_f32 v[68:69], v[68:69], v[70:71]
	s_nop 0
	v_cvt_pk_bf16_f32 v137, v68, v69
	v_pk_fma_f32 v[68:69], v[32:33], v[120:121], v[124:125]
	v_mov_b32_e32 v134, v248
	v_mov_b32_e32 v135, v249
	global_store_dwordx4 v[196:197], v[134:137], off
	v_pk_fma_f32 v[68:69], v[36:37], v[116:117], v[68:69]
	v_pk_fma_f32 v[32:33], v[32:33], v[116:117], v[44:45]
	v_pk_fma_f32 v[56:57], v[56:57], v[112:113], v[68:69]
	v_pk_fma_f32 v[32:33], v[36:37], v[112:113], v[32:33]
	v_exp_f32_e32 v66, v56
	v_exp_f32_e32 v67, v57
	s_nop 0
	v_pk_add_f32 v[66:67], v[66:67], 1.0 op_sel_hi:[1,0]
	v_rcp_f32_e32 v66, v66
	v_rcp_f32_e32 v67, v67
	v_pk_fma_f32 v[68:69], v[40:41], v[104:105], v[108:109]
	v_exp_f32_e32 v44, v32
	v_pk_fma_f32 v[68:69], v[48:49], v[100:101], v[68:69]
	v_pk_mul_f32 v[56:57], v[56:57], v[66:67]
	v_pk_fma_f32 v[60:61], v[60:61], v[96:97], v[68:69]
	v_pk_fma_f32 v[36:37], v[46:47], v[122:123], v[126:127]
	v_pk_mul_f32 v[56:57], v[60:61], v[56:57]
	v_pk_fma_f32 v[60:61], v[34:35], v[122:123], v[126:127]
	v_pk_fma_f32 v[34:35], v[34:35], v[118:119], v[36:37]
	v_pk_fma_f32 v[60:61], v[38:39], v[118:119], v[60:61]
	v_pk_fma_f32 v[34:35], v[38:39], v[114:115], v[34:35]
	v_pk_fma_f32 v[58:59], v[58:59], v[114:115], v[60:61]
	v_exp_f32_e32 v60, v58
	v_exp_f32_e32 v45, v33
	v_exp_f32_e32 v36, v34
	v_exp_f32_e32 v37, v35
	v_exp_f32_e32 v61, v59
	v_cvt_pk_bf16_f32 v164, v56, v57
	v_pk_add_f32 v[44:45], v[44:45], 1.0 op_sel_hi:[1,0]
	v_pk_add_f32 v[36:37], v[36:37], 1.0 op_sel_hi:[1,0]
	v_pk_add_f32 v[60:61], v[60:61], 1.0 op_sel_hi:[1,0]
	v_rcp_f32_e32 v44, v44
	v_rcp_f32_e32 v45, v45
	v_rcp_f32_e32 v36, v36
	v_rcp_f32_e32 v37, v37
	v_rcp_f32_e32 v60, v60
	v_rcp_f32_e32 v61, v61
	v_pk_fma_f32 v[46:47], v[54:55], v[106:107], v[110:111]
	v_pk_fma_f32 v[66:67], v[42:43], v[106:107], v[110:111]
	v_pk_fma_f32 v[40:41], v[40:41], v[100:101], v[52:53]
	v_pk_fma_f32 v[38:39], v[42:43], v[102:103], v[46:47]
	v_pk_fma_f32 v[66:67], v[50:51], v[102:103], v[66:67]
	v_pk_fma_f32 v[40:41], v[48:49], v[96:97], v[40:41]
	v_pk_mul_f32 v[32:33], v[32:33], v[44:45]
	v_pk_fma_f32 v[38:39], v[50:51], v[98:99], v[38:39]
	v_pk_mul_f32 v[34:35], v[34:35], v[36:37]
	v_pk_fma_f32 v[62:63], v[62:63], v[98:99], v[66:67]
	v_pk_mul_f32 v[58:59], v[58:59], v[60:61]
	v_pk_mul_f32 v[32:33], v[40:41], v[32:33]
	v_pk_mul_f32 v[34:35], v[38:39], v[34:35]
	v_pk_mul_f32 v[58:59], v[62:63], v[58:59]
	v_cvt_pk_bf16_f32 v160, v32, v33
	v_cvt_pk_bf16_f32 v161, v34, v35
	v_cvt_pk_bf16_f32 v165, v58, v59
	v_mov_b32_e32 v158, v250
	v_mov_b32_e32 v159, v251
	global_store_dwordx4 v[140:141], v[158:161], off
	v_mov_b32_e32 v65, 0
	v_mov_b64_e32 v[66:67], 0
	v_mov_b64_e32 v[40:41], 0
	v_mov_b64_e32 v[42:43], 0
	v_mov_b64_e32 v[32:33], 0
	v_mov_b64_e32 v[34:35], 0
	v_mov_b64_e32 v[36:37], 0
	v_mov_b64_e32 v[38:39], 0
	v_mov_b32_e32 v162, v253
	v_mov_b32_e32 v163, v254
	global_store_dwordx4 v[152:153], v[162:165], off
	s_barrier
	s_and_saveexec_b64 s[34:35], s[22:23]
	s_cbranch_execz .LBB0_1936
	ds_read_b128 v[36:39], v236 offset:2064
	ds_read_b128 v[40:43], v236 offset:2576
	ds_read_b128 v[32:35], v236 offset:3088
	ds_read_b128 v[64:67], v236 offset:3600
	s_branch .LBB0_1936
